# GEMM K-loops: the loading wave runs its load segment at priority 3 (above the computing wave) instead of 0
# baseline (speedup 1.0000x reference)
; #define PG8_STAGE(bufoff, gbase, voff) do { if constexpr (!pg8_noload<Epi>::value) { _Pragma("unroll") for (int _i = 0; _i < 2; ++_i) \
;         __builtin_amdgcn_global_load_lds((const unsigned*)((const char*)(gbase) + (size_t)_i * pstep + (voff)[0]), (PG8_LAS unsigned*)(lds + (bufoff) + ldsw + _i * 8192), 16, 0, 0); } } while (0)
; #define PG8_LDA(dst, b, h) do { _Pragma("unroll") for (int m = 0; m < 4; ++m) _Pragma("unroll") for (int k = 0; k < 2; ++k) dst[m][k] = *(const PG8_LAS bf16x8*)(lds + PG8_SA(b, h) + aoff + m * 2048 + k * 1024); } while (0)
; #define PG8_LDB(dst, b, h) do { _Pragma("unroll") for (int n = 0; n < 2; ++n) _Pragma("unroll") for (int k = 0; k < 2; ++k) dst[n][k] = *(const PG8_LAS bf16x8*)(lds + PG8_SB(b, h) + boff + n * 2048 + k * 1024); } while (0)
; #define PG8_MMA(ai, bj, At, Bt) do { __builtin_amdgcn_s_setprio(1); _Pragma("unroll") for (int m = 0; m < 4; ++m) _Pragma("unroll") for (int n = 0; n < 2; ++n) _Pragma("unroll") for (int k = 0; k < 2; ++k) \
;         acc[ai][bj][m][n] = __builtin_amdgcn_mfma_f32_16x16x32_bf16(Bt[n][k], At[m][k], acc[ai][bj][m][n], 0, 0, 0); __builtin_amdgcn_s_setprio(0); } while (0)
; #define PG8_BAR __builtin_amdgcn_s_barrier()
; template <class Epi, class Sched, bool ALIGN_EPI = false, bool SP2 = false, bool ABLK = false>
; __device__ __forceinline__ void gemm_phase(PG8_LAS unsigned char* lds, const Gemm g, const Sched& S, const Epi& E) {
;     ...
;         for (int t = 0; t < nt; t += 2) {
;             const bool last = (t == nt - 2);
;             const char* a1 = cA + (size_t)(t + 1) * kstep;
;             const char* a2 = last ? nA : cA + (size_t)(t + 2) * kstep; const char* b2 = last ? nB : cB + (size_t)(t + 2) * kstepB;
;             const char* a3 = a2 + kstep; const char* b3 = b2 + kstepB;
;             if (last && has_next) S.a_ready(nxt);
;             if constexpr (SP2) {
;             PG8_LDB(B0, 0, 0); PG8_LDB(B1, 0, 1); PG8_SCHED; PG8_LDA(At, 0, 0); PG8_STAGE(PG8_SA(1, 1), a1 + hstep, voffA);
;             PG8_WAIT_V(8); PG8_WAIT_L(0); PG8_BAR; PG8_MMA(0, 0, At, B0); PG8_MMA(0, 1, At, B1); PG8_BAR; PG8_SCHED;
;             PG8_LDA(At, 0, 1); PG8_STAGE(PG8_SB(0, 0), b2, voffB); PG8_STAGE(PG8_SB(0, 1), b2 + hstep, voffB); PG8_STAGE(PG8_SA(0, 0), a2, voffA);
;             PG8_WAIT_V(8); PG8_WAIT_L(0); PG8_BAR; PG8_MMA(1, 0, At, B0); PG8_MMA(1, 1, At, B1); PG8_BAR; PG8_SCHED;
.LBB0_114:
	ds_read_b128 v[144:147], v168
	ds_read_b128 v[184:187], v168 offset:1024
	ds_read_b128 v[188:191], v168 offset:2048
	ds_read_b128 v[192:195], v168 offset:3072
	ds_read_b128 v[196:199], v169
	ds_read_b128 v[200:203], v169 offset:1024
	ds_read_b128 v[204:207], v169 offset:2048
	ds_read_b128 v[208:211], v169 offset:3072
	s_add_u32 s71, vcc_lo, 0xfff80800
	s_addc_u32 s73, vcc_hi, -1
	s_cmp_eq_u32 s70, 28
	s_cselect_b32 s75, s3, s73
	s_cselect_b32 s74, s7, s71
	s_cselect_b32 s77, s21, s17
	s_cselect_b32 s76, s72, s16
	v_lshl_add_u64 v[244:245], vcc, 0, v[136:137]
	s_add_i32 m0, s53, 0xc000
	ds_read_b128 v[212:215], v170
	ds_read_b128 v[216:219], v170 offset:1024
	ds_read_b128 v[220:223], v170 offset:2048
	ds_read_b128 v[224:227], v170 offset:3072
	ds_read_b128 v[228:231], v170 offset:4096
	ds_read_b128 v[232:235], v170 offset:5120
	ds_read_b128 v[236:239], v170 offset:6144
	ds_read_b128 v[240:243], v170 offset:7168
	global_load_lds_dwordx4 v[244:245], off
	v_lshl_add_u64 v[244:245], v[244:245], 0, s[0:1]
	s_add_i32 m0, s53, 0xe000
	s_nop 0
	global_load_lds_dwordx4 v[244:245], off
	s_waitcnt vmcnt(8)
	s_waitcnt lgkmcnt(0)
	s_barrier
	s_setprio 1
	s_waitcnt lgkmcnt(0)
	v_mfma_f32_16x16x32_bf16 v[126:129], v[144:147], v[212:215], v[126:129]
	v_mfma_f32_16x16x32_bf16 v[126:129], v[184:187], v[216:219], v[126:129]
	v_mfma_f32_16x16x32_bf16 v[110:113], v[184:187], v[224:227], v[110:113]
	v_mfma_f32_16x16x32_bf16 v[110:113], v[144:147], v[220:223], v[110:113]
	v_mfma_f32_16x16x32_bf16 v[94:97], v[144:147], v[228:231], v[94:97]
	v_mfma_f32_16x16x32_bf16 v[94:97], v[184:187], v[232:235], v[94:97]
	v_mfma_f32_16x16x32_bf16 v[78:81], v[184:187], v[240:243], v[78:81]
	v_mfma_f32_16x16x32_bf16 v[78:81], v[144:147], v[236:239], v[78:81]
	v_mfma_f32_16x16x32_bf16 v[74:77], v[188:191], v[236:239], v[74:77]
	v_mfma_f32_16x16x32_bf16 v[74:77], v[192:195], v[240:243], v[74:77]
	v_mfma_f32_16x16x32_bf16 v[90:93], v[192:195], v[232:235], v[90:93]
	v_mfma_f32_16x16x32_bf16 v[90:93], v[188:191], v[228:231], v[90:93]
	v_mfma_f32_16x16x32_bf16 v[106:109], v[188:191], v[220:223], v[106:109]
	v_mfma_f32_16x16x32_bf16 v[106:109], v[192:195], v[224:227], v[106:109]
	v_mfma_f32_16x16x32_bf16 v[122:125], v[192:195], v[216:219], v[122:125]
	v_mfma_f32_16x16x32_bf16 v[122:125], v[188:191], v[212:215], v[122:125]
	v_mfma_f32_16x16x32_bf16 v[118:121], v[196:199], v[212:215], v[118:121]
	v_mfma_f32_16x16x32_bf16 v[118:121], v[200:203], v[216:219], v[118:121]
	v_mfma_f32_16x16x32_bf16 v[102:105], v[200:203], v[224:227], v[102:105]
	v_mfma_f32_16x16x32_bf16 v[102:105], v[196:199], v[220:223], v[102:105]
	v_mfma_f32_16x16x32_bf16 v[86:89], v[196:199], v[228:231], v[86:89]
	v_mfma_f32_16x16x32_bf16 v[86:89], v[200:203], v[232:235], v[86:89]
	v_mfma_f32_16x16x32_bf16 v[70:73], v[200:203], v[240:243], v[70:73]
	v_mfma_f32_16x16x32_bf16 v[70:73], v[196:199], v[236:239], v[70:73]
	v_mfma_f32_16x16x32_bf16 v[66:69], v[204:207], v[236:239], v[66:69]
	v_mfma_f32_16x16x32_bf16 v[66:69], v[208:211], v[240:243], v[66:69]
	v_mfma_f32_16x16x32_bf16 v[82:85], v[208:211], v[232:235], v[82:85]
	v_mfma_f32_16x16x32_bf16 v[82:85], v[204:207], v[228:231], v[82:85]
	s_barrier
	s_setprio 2
	v_mfma_f32_16x16x32_bf16 v[98:101], v[204:207], v[220:223], v[98:101]
	v_mfma_f32_16x16x32_bf16 v[98:101], v[208:211], v[224:227], v[98:101]
	v_mfma_f32_16x16x32_bf16 v[114:117], v[208:211], v[216:219], v[114:117]
	v_mfma_f32_16x16x32_bf16 v[114:117], v[204:207], v[212:215], v[114:117]
	s_setprio 3
	s_add_i32 s71, s64, s52
	v_lshl_add_u64 v[244:245], s[76:77], 0, v[130:131]
	s_mov_b32 m0, s71
	ds_read_b128 v[212:215], v170 offset:16384
	ds_read_b128 v[216:219], v170 offset:17408
	ds_read_b128 v[220:223], v170 offset:18432
	ds_read_b128 v[224:227], v170 offset:19456
	ds_read_b128 v[228:231], v170 offset:20480
	ds_read_b128 v[232:235], v170 offset:21504
	ds_read_b128 v[236:239], v170 offset:22528
	ds_read_b128 v[240:243], v170 offset:23552
	global_load_lds_dwordx4 v[244:245], off
	v_lshl_add_u64 v[246:247], v[244:245], 0, s[0:1]
	s_add_i32 m0, s71, 0x2000
	s_add_i32 s71, s65, s52
	global_load_lds_dwordx4 v[246:247], off
	v_lshl_add_u64 v[246:247], v[244:245], 0, s[14:15]
	s_mov_b32 m0, s71
	s_nop 0
	global_load_lds_dwordx4 v[246:247], off
	v_lshl_add_u64 v[246:247], v[244:245], 0, s[18:19]
	s_add_i32 m0, s71, 0x2000
	s_nop 0
	global_load_lds_dwordx4 v[246:247], off
	v_lshl_add_u64 v[246:247], s[74:75], 0, v[130:131]
	s_mov_b32 m0, s53
	v_lshl_add_u64 v[248:249], v[246:247], 0, s[0:1]
	global_load_lds_dwordx4 v[246:247], off
	s_mov_b32 m0, s54
	s_nop 0
	global_load_lds_dwordx4 v[248:249], off
	s_waitcnt vmcnt(8)
	s_waitcnt lgkmcnt(0)
	s_barrier
; #define PG8_STAGE(bufoff, gbase, voff) do { if constexpr (!pg8_noload<Epi>::value) { _Pragma("unroll") for (int _i = 0; _i < 2; ++_i) \
;         __builtin_amdgcn_global_load_lds((const unsigned*)((const char*)(gbase) + (size_t)_i * pstep + (voff)[0]), (PG8_LAS unsigned*)(lds + (bufoff) + ldsw + _i * 8192), 16, 0, 0); } } while (0)
; #define PG8_LDA(dst, b, h) do { _Pragma("unroll") for (int m = 0; m < 4; ++m) _Pragma("unroll") for (int k = 0; k < 2; ++k) dst[m][k] = *(const PG8_LAS bf16x8*)(lds + PG8_SA(b, h) + aoff + m * 2048 + k * 1024); } while (0)
; #define PG8_LDB(dst, b, h) do { _Pragma("unroll") for (int n = 0; n < 2; ++n) _Pragma("unroll") for (int k = 0; k < 2; ++k) dst[n][k] = *(const PG8_LAS bf16x8*)(lds + PG8_SB(b, h) + boff + n * 2048 + k * 1024); } while (0)
; #define PG8_MMA(ai, bj, At, Bt) do { __builtin_amdgcn_s_setprio(1); _Pragma("unroll") for (int m = 0; m < 4; ++m) _Pragma("unroll") for (int n = 0; n < 2; ++n) _Pragma("unroll") for (int k = 0; k < 2; ++k) \
;         acc[ai][bj][m][n] = __builtin_amdgcn_mfma_f32_16x16x32_bf16(Bt[n][k], At[m][k], acc[ai][bj][m][n], 0, 0, 0); __builtin_amdgcn_s_setprio(0); } while (0)
; #define PG8_WAIT_V(n) asm volatile("s_waitcnt vmcnt(" #n ")" ::: "memory")
; #define PG8_WAIT_L(n) asm volatile("s_waitcnt lgkmcnt(" #n ")" ::: "memory")
; #define PG8_BAR __builtin_amdgcn_s_barrier()
; #define PG8_SCHED __builtin_amdgcn_sched_barrier(0)
; template <class Epi, class Sched, bool ALIGN_EPI = false, bool SP2 = false, bool ABLK = false>
; __device__ __forceinline__ void gemm_phase(PG8_LAS unsigned char* lds, const Gemm g, const Sched& S, const Epi& E) {
;     ...
;             PG8_WAIT_V(8); PG8_WAIT_L(0); PG8_BAR; PG8_MMA(1, 0, At, B0); PG8_MMA(1, 1, At, B1); PG8_BAR; PG8_SCHED;
;             PG8_LDB(B0, 1, 0); PG8_LDB(B1, 1, 1); PG8_SCHED; PG8_LDA(At, 1, 0); PG8_STAGE(PG8_SA(0, 1), a2 + hstep, voffA);
;             PG8_WAIT_V(8); PG8_WAIT_L(0); PG8_BAR; PG8_MMA(0, 0, At, B0); PG8_MMA(0, 1, At, B1); PG8_BAR; PG8_SCHED;
	s_setprio 1
	s_waitcnt lgkmcnt(0)
	v_mfma_f32_16x16x32_bf16 v[62:65], v[144:147], v[212:215], v[62:65]
	v_mfma_f32_16x16x32_bf16 v[62:65], v[184:187], v[216:219], v[62:65]
	v_mfma_f32_16x16x32_bf16 v[46:49], v[184:187], v[224:227], v[46:49]
	v_mfma_f32_16x16x32_bf16 v[46:49], v[144:147], v[220:223], v[46:49]
	v_mfma_f32_16x16x32_bf16 v[30:33], v[144:147], v[228:231], v[30:33]
	v_mfma_f32_16x16x32_bf16 v[30:33], v[184:187], v[232:235], v[30:33]
	v_mfma_f32_16x16x32_bf16 v[14:17], v[184:187], v[240:243], v[14:17]
	v_mfma_f32_16x16x32_bf16 v[14:17], v[144:147], v[236:239], v[14:17]
	v_mfma_f32_16x16x32_bf16 v[10:13], v[188:191], v[236:239], v[10:13]
	v_mfma_f32_16x16x32_bf16 v[10:13], v[192:195], v[240:243], v[10:13]
	v_mfma_f32_16x16x32_bf16 v[26:29], v[192:195], v[232:235], v[26:29]
	v_mfma_f32_16x16x32_bf16 v[26:29], v[188:191], v[228:231], v[26:29]
	v_mfma_f32_16x16x32_bf16 v[42:45], v[188:191], v[220:223], v[42:45]
	v_mfma_f32_16x16x32_bf16 v[42:45], v[192:195], v[224:227], v[42:45]
	v_mfma_f32_16x16x32_bf16 v[58:61], v[192:195], v[216:219], v[58:61]
	v_mfma_f32_16x16x32_bf16 v[58:61], v[188:191], v[212:215], v[58:61]
	v_mfma_f32_16x16x32_bf16 v[54:57], v[196:199], v[212:215], v[54:57]
	v_mfma_f32_16x16x32_bf16 v[54:57], v[200:203], v[216:219], v[54:57]
	v_mfma_f32_16x16x32_bf16 v[38:41], v[200:203], v[224:227], v[38:41]
	v_mfma_f32_16x16x32_bf16 v[38:41], v[196:199], v[220:223], v[38:41]
	v_mfma_f32_16x16x32_bf16 v[22:25], v[196:199], v[228:231], v[22:25]
	v_mfma_f32_16x16x32_bf16 v[22:25], v[200:203], v[232:235], v[22:25]
	v_mfma_f32_16x16x32_bf16 v[6:9], v[200:203], v[240:243], v[6:9]
	v_mfma_f32_16x16x32_bf16 v[6:9], v[196:199], v[236:239], v[6:9]
	v_mfma_f32_16x16x32_bf16 v[2:5], v[204:207], v[236:239], v[2:5]
	v_mfma_f32_16x16x32_bf16 v[2:5], v[208:211], v[240:243], v[2:5]
	v_mfma_f32_16x16x32_bf16 v[18:21], v[208:211], v[232:235], v[18:21]
	v_mfma_f32_16x16x32_bf16 v[18:21], v[204:207], v[228:231], v[18:21]
	s_barrier
	s_setprio 2
	v_mfma_f32_16x16x32_bf16 v[34:37], v[204:207], v[220:223], v[34:37]
	v_mfma_f32_16x16x32_bf16 v[34:37], v[208:211], v[224:227], v[34:37]
	v_mfma_f32_16x16x32_bf16 v[50:53], v[208:211], v[216:219], v[50:53]
	v_mfma_f32_16x16x32_bf16 v[50:53], v[204:207], v[212:215], v[50:53]
	s_setprio 3
	s_add_i32 s71, 0, 0x18000
	v_add_u32_e32 v133, s71, v149
	s_add_i32 s73, 0, 0x1c000
	ds_read_b128 v[144:147], v133
	ds_read_b128 v[184:187], v133 offset:1024
	ds_read_b128 v[188:191], v133 offset:2048
	ds_read_b128 v[192:195], v133 offset:3072
	v_add_u32_e32 v133, s73, v149
	ds_read_b128 v[196:199], v133
	ds_read_b128 v[200:203], v133 offset:1024
	ds_read_b128 v[204:207], v133 offset:2048
	ds_read_b128 v[208:211], v133 offset:3072
	s_mov_b32 m0, s55
	v_lshl_add_u64 v[248:249], v[246:247], 0, s[14:15]
	ds_read_b128 v[212:215], v170 offset:32768
	ds_read_b128 v[216:219], v170 offset:33792
	ds_read_b128 v[220:223], v170 offset:34816
	ds_read_b128 v[224:227], v170 offset:35840
	ds_read_b128 v[228:231], v170 offset:36864
	ds_read_b128 v[232:235], v170 offset:37888
	ds_read_b128 v[236:239], v170 offset:38912
	ds_read_b128 v[240:243], v170 offset:39936
	global_load_lds_dwordx4 v[248:249], off
	v_lshl_add_u64 v[248:249], v[246:247], 0, s[18:19]
	s_mov_b32 m0, s56
	s_nop 0
	global_load_lds_dwordx4 v[248:249], off
	s_waitcnt vmcnt(8)
	s_waitcnt lgkmcnt(0)
	s_barrier
	s_setprio 1
	s_waitcnt lgkmcnt(0)
	v_mfma_f32_16x16x32_bf16 v[126:129], v[144:147], v[212:215], v[126:129]
	v_mfma_f32_16x16x32_bf16 v[126:129], v[184:187], v[216:219], v[126:129]
	v_mfma_f32_16x16x32_bf16 v[110:113], v[184:187], v[224:227], v[110:113]
	v_mfma_f32_16x16x32_bf16 v[110:113], v[144:147], v[220:223], v[110:113]
	v_mfma_f32_16x16x32_bf16 v[94:97], v[144:147], v[228:231], v[94:97]
	v_mfma_f32_16x16x32_bf16 v[94:97], v[184:187], v[232:235], v[94:97]
	v_mfma_f32_16x16x32_bf16 v[78:81], v[184:187], v[240:243], v[78:81]
	v_mfma_f32_16x16x32_bf16 v[78:81], v[144:147], v[236:239], v[78:81]
	v_mfma_f32_16x16x32_bf16 v[74:77], v[188:191], v[236:239], v[74:77]
	v_mfma_f32_16x16x32_bf16 v[74:77], v[192:195], v[240:243], v[74:77]
	v_mfma_f32_16x16x32_bf16 v[90:93], v[192:195], v[232:235], v[90:93]
	v_mfma_f32_16x16x32_bf16 v[90:93], v[188:191], v[228:231], v[90:93]
	v_mfma_f32_16x16x32_bf16 v[106:109], v[188:191], v[220:223], v[106:109]
	v_mfma_f32_16x16x32_bf16 v[106:109], v[192:195], v[224:227], v[106:109]
	v_mfma_f32_16x16x32_bf16 v[122:125], v[192:195], v[216:219], v[122:125]
	v_mfma_f32_16x16x32_bf16 v[122:125], v[188:191], v[212:215], v[122:125]
	v_mfma_f32_16x16x32_bf16 v[118:121], v[196:199], v[212:215], v[118:121]
	v_mfma_f32_16x16x32_bf16 v[118:121], v[200:203], v[216:219], v[118:121]
	v_mfma_f32_16x16x32_bf16 v[102:105], v[200:203], v[224:227], v[102:105]
	v_mfma_f32_16x16x32_bf16 v[102:105], v[196:199], v[220:223], v[102:105]
	v_mfma_f32_16x16x32_bf16 v[86:89], v[196:199], v[228:231], v[86:89]
	v_mfma_f32_16x16x32_bf16 v[86:89], v[200:203], v[232:235], v[86:89]
	v_mfma_f32_16x16x32_bf16 v[70:73], v[200:203], v[240:243], v[70:73]
	v_mfma_f32_16x16x32_bf16 v[70:73], v[196:199], v[236:239], v[70:73]
	v_mfma_f32_16x16x32_bf16 v[66:69], v[204:207], v[236:239], v[66:69]
	v_mfma_f32_16x16x32_bf16 v[66:69], v[208:211], v[240:243], v[66:69]
	v_mfma_f32_16x16x32_bf16 v[82:85], v[208:211], v[232:235], v[82:85]
	v_mfma_f32_16x16x32_bf16 v[82:85], v[204:207], v[228:231], v[82:85]
	s_barrier
; #define PG8_STAGE(bufoff, gbase, voff) do { if constexpr (!pg8_noload<Epi>::value) { _Pragma("unroll") for (int _i = 0; _i < 2; ++_i) \
;         __builtin_amdgcn_global_load_lds((const unsigned*)((const char*)(gbase) + (size_t)_i * pstep + (voff)[0]), (PG8_LAS unsigned*)(lds + (bufoff) + ldsw + _i * 8192), 16, 0, 0); } } while (0)
; #define PG8_LDA(dst, b, h) do { _Pragma("unroll") for (int m = 0; m < 4; ++m) _Pragma("unroll") for (int k = 0; k < 2; ++k) dst[m][k] = *(const PG8_LAS bf16x8*)(lds + PG8_SA(b, h) + aoff + m * 2048 + k * 1024); } while (0)
; #define PG8_MMA(ai, bj, At, Bt) do { __builtin_amdgcn_s_setprio(1); _Pragma("unroll") for (int m = 0; m < 4; ++m) _Pragma("unroll") for (int n = 0; n < 2; ++n) _Pragma("unroll") for (int k = 0; k < 2; ++k) \
;         acc[ai][bj][m][n] = __builtin_amdgcn_mfma_f32_16x16x32_bf16(Bt[n][k], At[m][k], acc[ai][bj][m][n], 0, 0, 0); __builtin_amdgcn_s_setprio(0); } while (0)
; #define PG8_WAIT_V(n) asm volatile("s_waitcnt vmcnt(" #n ")" ::: "memory")
; #define PG8_WAIT_L(n) asm volatile("s_waitcnt lgkmcnt(" #n ")" ::: "memory")
; #define PG8_BAR __builtin_amdgcn_s_barrier()
; #define PG8_SCHED __builtin_amdgcn_sched_barrier(0)
; template <class Epi, class Sched, bool ALIGN_EPI = false, bool SP2 = false, bool ABLK = false>
; __device__ __forceinline__ void gemm_phase(PG8_LAS unsigned char* lds, const Gemm g, const Sched& S, const Epi& E) {
;     ...
;             PG8_WAIT_V(8); PG8_WAIT_L(0); PG8_BAR; PG8_MMA(0, 0, At, B0); PG8_MMA(0, 1, At, B1); PG8_BAR; PG8_SCHED;
;             PG8_LDA(At, 1, 1); PG8_STAGE(PG8_SB(1, 0), b3, voffB); PG8_STAGE(PG8_SB(1, 1), b3 + hstep, voffB); PG8_STAGE(PG8_SA(1, 0), a3, voffA);
;             PG8_WAIT_V(8); PG8_WAIT_L(0); PG8_BAR; PG8_MMA(1, 0, At, B0); PG8_MMA(1, 1, At, B1); PG8_BAR; PG8_SCHED;
	s_setprio 2
	v_mfma_f32_16x16x32_bf16 v[98:101], v[204:207], v[220:223], v[98:101]
	v_mfma_f32_16x16x32_bf16 v[98:101], v[208:211], v[224:227], v[98:101]
	v_mfma_f32_16x16x32_bf16 v[114:117], v[208:211], v[216:219], v[114:117]
	v_mfma_f32_16x16x32_bf16 v[114:117], v[204:207], v[212:215], v[114:117]
	s_setprio 3
	s_add_i32 s71, s71, s52
	v_lshl_add_u64 v[248:249], v[244:245], 0, s[28:29]
	s_mov_b32 m0, s71
	ds_read_b128 v[212:215], v170 offset:49152
	ds_read_b128 v[216:219], v170 offset:50176
	ds_read_b128 v[220:223], v170 offset:51200
	ds_read_b128 v[224:227], v170 offset:52224
	ds_read_b128 v[228:231], v170 offset:53248
	ds_read_b128 v[232:235], v170 offset:54272
	ds_read_b128 v[236:239], v170 offset:55296
	ds_read_b128 v[240:243], v170 offset:56320
	global_load_lds_dwordx4 v[248:249], off
	v_lshl_add_u64 v[248:249], v[244:245], 0, s[30:31]
	s_add_i32 m0, s71, 0x2000
	s_add_i32 s71, s73, s52
	global_load_lds_dwordx4 v[248:249], off
	v_lshl_add_u64 v[248:249], v[244:245], 0, s[34:35]
	s_mov_b32 m0, s71
	v_lshl_add_u64 v[244:245], v[244:245], 0, s[36:37]
	global_load_lds_dwordx4 v[248:249], off
	s_add_i32 m0, s71, 0x2000
	s_nop 0
	global_load_lds_dwordx4 v[244:245], off
	v_lshl_add_u64 v[244:245], v[246:247], 0, s[28:29]
	s_mov_b32 m0, s59
	s_nop 0
	global_load_lds_dwordx4 v[244:245], off
	v_lshl_add_u64 v[244:245], v[246:247], 0, s[30:31]
	s_mov_b32 m0, s60
	s_nop 0
	global_load_lds_dwordx4 v[244:245], off
	s_waitcnt vmcnt(8)
	s_waitcnt lgkmcnt(0)
	s_barrier
	s_setprio 1
	s_waitcnt lgkmcnt(0)
	v_mfma_f32_16x16x32_bf16 v[62:65], v[144:147], v[212:215], v[62:65]
	v_mfma_f32_16x16x32_bf16 v[62:65], v[184:187], v[216:219], v[62:65]
	v_mfma_f32_16x16x32_bf16 v[46:49], v[184:187], v[224:227], v[46:49]
	v_mfma_f32_16x16x32_bf16 v[46:49], v[144:147], v[220:223], v[46:49]
	v_mfma_f32_16x16x32_bf16 v[30:33], v[144:147], v[228:231], v[30:33]
	v_mfma_f32_16x16x32_bf16 v[30:33], v[184:187], v[232:235], v[30:33]
	v_mfma_f32_16x16x32_bf16 v[14:17], v[184:187], v[240:243], v[14:17]
	v_mfma_f32_16x16x32_bf16 v[14:17], v[144:147], v[236:239], v[14:17]
	v_mfma_f32_16x16x32_bf16 v[10:13], v[188:191], v[236:239], v[10:13]
	v_mfma_f32_16x16x32_bf16 v[10:13], v[192:195], v[240:243], v[10:13]
	v_mfma_f32_16x16x32_bf16 v[26:29], v[192:195], v[232:235], v[26:29]
	v_mfma_f32_16x16x32_bf16 v[26:29], v[188:191], v[228:231], v[26:29]
	v_mfma_f32_16x16x32_bf16 v[42:45], v[188:191], v[220:223], v[42:45]
	v_mfma_f32_16x16x32_bf16 v[42:45], v[192:195], v[224:227], v[42:45]
	v_mfma_f32_16x16x32_bf16 v[58:61], v[192:195], v[216:219], v[58:61]
	v_mfma_f32_16x16x32_bf16 v[58:61], v[188:191], v[212:215], v[58:61]
	v_mfma_f32_16x16x32_bf16 v[54:57], v[196:199], v[212:215], v[54:57]
	v_mfma_f32_16x16x32_bf16 v[54:57], v[200:203], v[216:219], v[54:57]
	v_mfma_f32_16x16x32_bf16 v[38:41], v[200:203], v[224:227], v[38:41]
	v_mfma_f32_16x16x32_bf16 v[38:41], v[196:199], v[220:223], v[38:41]
	v_mfma_f32_16x16x32_bf16 v[22:25], v[196:199], v[228:231], v[22:25]
	v_mfma_f32_16x16x32_bf16 v[22:25], v[200:203], v[232:235], v[22:25]
	v_mfma_f32_16x16x32_bf16 v[6:9], v[200:203], v[240:243], v[6:9]
	v_mfma_f32_16x16x32_bf16 v[6:9], v[196:199], v[236:239], v[6:9]
	v_mfma_f32_16x16x32_bf16 v[2:5], v[204:207], v[236:239], v[2:5]
	v_mfma_f32_16x16x32_bf16 v[2:5], v[208:211], v[240:243], v[2:5]
	v_mfma_f32_16x16x32_bf16 v[18:21], v[208:211], v[232:235], v[18:21]
	v_mfma_f32_16x16x32_bf16 v[18:21], v[204:207], v[228:231], v[18:21]
	s_barrier
	s_setprio 2
	v_mfma_f32_16x16x32_bf16 v[34:37], v[204:207], v[220:223], v[34:37]
	v_mfma_f32_16x16x32_bf16 v[34:37], v[208:211], v[224:227], v[34:37]
	v_mfma_f32_16x16x32_bf16 v[50:53], v[208:211], v[216:219], v[50:53]
	v_mfma_f32_16x16x32_bf16 v[50:53], v[204:207], v[212:215], v[50:53]
	s_setprio 3
	s_add_i32 s70, s70, 2
	s_add_u32 vcc_lo, vcc_lo, 0x1000
	s_addc_u32 vcc_hi, vcc_hi, 0
	s_add_u32 s16, s16, 0x1000
	s_addc_u32 s17, s17, 0
	s_cmp_gt_u32 s70, 29
	s_cbranch_scc0 .LBB0_114
	s_and_b64 vcc, exec, s[38:39]
	s_cbranch_vccz .LBB0_117
	s_barrier

; #define PG8_STAGE(bufoff, gbase, voff) do { if constexpr (!pg8_noload<Epi>::value) { _Pragma("unroll") for (int _i = 0; _i < 2; ++_i) \
;         __builtin_amdgcn_global_load_lds((const unsigned*)((const char*)(gbase) + (size_t)_i * pstep + (voff)[0]), (PG8_LAS unsigned*)(lds + (bufoff) + ldsw + _i * 8192), 16, 0, 0); } } while (0)
; #define PG8_LDA(dst, b, h) do { _Pragma("unroll") for (int m = 0; m < 4; ++m) _Pragma("unroll") for (int k = 0; k < 2; ++k) dst[m][k] = *(const PG8_LAS bf16x8*)(lds + PG8_SA(b, h) + aoff + m * 2048 + k * 1024); } while (0)
; #define PG8_LDB(dst, b, h) do { _Pragma("unroll") for (int n = 0; n < 2; ++n) _Pragma("unroll") for (int k = 0; k < 2; ++k) dst[n][k] = *(const PG8_LAS bf16x8*)(lds + PG8_SB(b, h) + boff + n * 2048 + k * 1024); } while (0)
; #define PG8_MMA(ai, bj, At, Bt) do { __builtin_amdgcn_s_setprio(1); _Pragma("unroll") for (int m = 0; m < 4; ++m) _Pragma("unroll") for (int n = 0; n < 2; ++n) _Pragma("unroll") for (int k = 0; k < 2; ++k) \
;         acc[ai][bj][m][n] = __builtin_amdgcn_mfma_f32_16x16x32_bf16(Bt[n][k], At[m][k], acc[ai][bj][m][n], 0, 0, 0); __builtin_amdgcn_s_setprio(0); } while (0)
; #define PG8_BAR __builtin_amdgcn_s_barrier()
; template <class Epi, class Sched, bool ALIGN_EPI = false, bool SP2 = false, bool ABLK = false>
; __device__ __forceinline__ void gemm_phase(PG8_LAS unsigned char* lds, const Gemm g, const Sched& S, const Epi& E) {
;     ...
;         for (int t = 0; t < nt; t += 2) {
;             const bool last = (t == nt - 2);
;             const char* a1 = cA + (size_t)(t + 1) * kstep;
;             const char* a2 = last ? nA : cA + (size_t)(t + 2) * kstep; const char* b2 = last ? nB : cB + (size_t)(t + 2) * kstepB;
;             const char* a3 = a2 + kstep; const char* b3 = b2 + kstepB;
;             if (last && has_next) S.a_ready(nxt);
;             if constexpr (SP2) {
;             PG8_LDB(B0, 0, 0); PG8_LDB(B1, 0, 1); PG8_SCHED; PG8_LDA(At, 0, 0); PG8_STAGE(PG8_SA(1, 1), a1 + hstep, voffA);
;             PG8_WAIT_V(8); PG8_WAIT_L(0); PG8_BAR; PG8_MMA(0, 0, At, B0); PG8_MMA(0, 1, At, B1); PG8_BAR; PG8_SCHED;
;             PG8_LDA(At, 0, 1); PG8_STAGE(PG8_SB(0, 0), b2, voffB); PG8_STAGE(PG8_SB(0, 1), b2 + hstep, voffB); PG8_STAGE(PG8_SA(0, 0), a2, voffA);
;             PG8_WAIT_V(8); PG8_WAIT_L(0); PG8_BAR; PG8_MMA(1, 0, At, B0); PG8_MMA(1, 1, At, B1); PG8_BAR; PG8_SCHED;
.LBB0_487:
	ds_read_b128 v[114:117], v167
	ds_read_b128 v[126:129], v167 offset:1024
	ds_read_b128 v[130:133], v167 offset:2048
	ds_read_b128 v[142:145], v167 offset:3072
	ds_read_b128 v[146:149], v168
	ds_read_b128 v[150:153], v168 offset:1024
	ds_read_b128 v[174:177], v168 offset:2048
	ds_read_b128 v[178:181], v168 offset:3072
	s_add_i32 s65, s39, 2
	s_add_u32 s68, s92, 0xfff00800
	s_addc_u32 s69, s93, -1
	s_cmp_eq_u32 s3, s39
	s_cselect_b32 s69, s79, s69
	s_cselect_b32 s68, s78, s68
	s_cselect_b32 s71, s89, s37
	s_cselect_b32 s70, s88, s11
	v_lshl_add_u64 v[162:163], s[92:93], 0, v[158:159]
	s_add_i32 m0, s56, 0xc000
	ds_read_b128 v[184:187], v169
	ds_read_b128 v[188:191], v169 offset:1024
	ds_read_b128 v[192:195], v169 offset:2048
	ds_read_b128 v[196:199], v169 offset:3072
	ds_read_b128 v[200:203], v169 offset:4096
	ds_read_b128 v[204:207], v169 offset:5120
	ds_read_b128 v[208:211], v169 offset:6144
	ds_read_b128 v[212:215], v169 offset:7168
	global_load_lds_dwordx4 v[162:163], off
	v_lshl_add_u64 v[162:163], v[162:163], 0, s[12:13]
	s_add_i32 m0, s56, 0xe000
	s_nop 0
	global_load_lds_dwordx4 v[162:163], off
	s_waitcnt vmcnt(8)
	s_waitcnt lgkmcnt(0)
	s_barrier
	s_setprio 1
	s_waitcnt lgkmcnt(0)
	v_mfma_f32_16x16x32_bf16 v[138:141], v[114:117], v[184:187], v[138:141]
	v_mfma_f32_16x16x32_bf16 v[138:141], v[126:129], v[188:191], v[138:141]
	v_mfma_f32_16x16x32_bf16 v[110:113], v[126:129], v[196:199], v[110:113]
	v_mfma_f32_16x16x32_bf16 v[110:113], v[114:117], v[192:195], v[110:113]
	v_mfma_f32_16x16x32_bf16 v[94:97], v[114:117], v[200:203], v[94:97]
	v_mfma_f32_16x16x32_bf16 v[94:97], v[126:129], v[204:207], v[94:97]
	v_mfma_f32_16x16x32_bf16 v[78:81], v[126:129], v[212:215], v[78:81]
	v_mfma_f32_16x16x32_bf16 v[78:81], v[114:117], v[208:211], v[78:81]
	v_mfma_f32_16x16x32_bf16 v[74:77], v[130:133], v[208:211], v[74:77]
	v_mfma_f32_16x16x32_bf16 v[74:77], v[142:145], v[212:215], v[74:77]
	v_mfma_f32_16x16x32_bf16 v[90:93], v[142:145], v[204:207], v[90:93]
	v_mfma_f32_16x16x32_bf16 v[90:93], v[130:133], v[200:203], v[90:93]
	v_mfma_f32_16x16x32_bf16 v[106:109], v[130:133], v[192:195], v[106:109]
	v_mfma_f32_16x16x32_bf16 v[106:109], v[142:145], v[196:199], v[106:109]
	v_mfma_f32_16x16x32_bf16 v[134:137], v[142:145], v[188:191], v[134:137]
	v_mfma_f32_16x16x32_bf16 v[134:137], v[130:133], v[184:187], v[134:137]
	v_mfma_f32_16x16x32_bf16 v[122:125], v[146:149], v[184:187], v[122:125]
	v_mfma_f32_16x16x32_bf16 v[122:125], v[150:153], v[188:191], v[122:125]
	v_mfma_f32_16x16x32_bf16 v[102:105], v[150:153], v[196:199], v[102:105]
	v_mfma_f32_16x16x32_bf16 v[102:105], v[146:149], v[192:195], v[102:105]
	v_mfma_f32_16x16x32_bf16 v[86:89], v[146:149], v[200:203], v[86:89]
	v_mfma_f32_16x16x32_bf16 v[86:89], v[150:153], v[204:207], v[86:89]
	v_mfma_f32_16x16x32_bf16 v[70:73], v[150:153], v[212:215], v[70:73]
	v_mfma_f32_16x16x32_bf16 v[70:73], v[146:149], v[208:211], v[70:73]
	v_mfma_f32_16x16x32_bf16 v[66:69], v[174:177], v[208:211], v[66:69]
	v_mfma_f32_16x16x32_bf16 v[66:69], v[178:181], v[212:215], v[66:69]
	v_mfma_f32_16x16x32_bf16 v[82:85], v[178:181], v[204:207], v[82:85]
	v_mfma_f32_16x16x32_bf16 v[82:85], v[174:177], v[200:203], v[82:85]
	s_barrier
	s_setprio 2
	v_mfma_f32_16x16x32_bf16 v[98:101], v[174:177], v[192:195], v[98:101]
	v_mfma_f32_16x16x32_bf16 v[98:101], v[178:181], v[196:199], v[98:101]
	v_mfma_f32_16x16x32_bf16 v[118:121], v[178:181], v[188:191], v[118:121]
	v_mfma_f32_16x16x32_bf16 v[118:121], v[174:177], v[184:187], v[118:121]
	s_setprio 3
	s_add_i32 s39, s73, s55
	v_lshl_add_u64 v[162:163], s[70:71], 0, v[154:155]
	s_mov_b32 m0, s39
	ds_read_b128 v[184:187], v169 offset:16384
	ds_read_b128 v[188:191], v169 offset:17408
	ds_read_b128 v[192:195], v169 offset:18432
	ds_read_b128 v[196:199], v169 offset:19456
	ds_read_b128 v[200:203], v169 offset:20480
	ds_read_b128 v[204:207], v169 offset:21504
	ds_read_b128 v[208:211], v169 offset:22528
	ds_read_b128 v[212:215], v169 offset:23552
	global_load_lds_dwordx4 v[162:163], off
	v_lshl_add_u64 v[216:217], v[162:163], 0, s[12:13]
	s_add_i32 m0, s39, 0x2000
	s_add_i32 s39, s74, s55
	global_load_lds_dwordx4 v[216:217], off
	v_lshl_add_u64 v[216:217], v[162:163], 0, s[14:15]
	s_mov_b32 m0, s39
	s_nop 0
	global_load_lds_dwordx4 v[216:217], off
	v_lshl_add_u64 v[216:217], v[162:163], 0, s[16:17]
	s_add_i32 m0, s39, 0x2000
	s_nop 0
	global_load_lds_dwordx4 v[216:217], off
	v_lshl_add_u64 v[216:217], s[68:69], 0, v[154:155]
	s_mov_b32 m0, s56
	v_lshl_add_u64 v[218:219], v[216:217], 0, s[12:13]
	global_load_lds_dwordx4 v[216:217], off
	s_mov_b32 m0, s57
	s_nop 0
	global_load_lds_dwordx4 v[218:219], off
	s_waitcnt vmcnt(8)
	s_waitcnt lgkmcnt(0)
	s_barrier
; #define PG8_STAGE(bufoff, gbase, voff) do { if constexpr (!pg8_noload<Epi>::value) { _Pragma("unroll") for (int _i = 0; _i < 2; ++_i) \
;         __builtin_amdgcn_global_load_lds((const unsigned*)((const char*)(gbase) + (size_t)_i * pstep + (voff)[0]), (PG8_LAS unsigned*)(lds + (bufoff) + ldsw + _i * 8192), 16, 0, 0); } } while (0)
; #define PG8_LDA(dst, b, h) do { _Pragma("unroll") for (int m = 0; m < 4; ++m) _Pragma("unroll") for (int k = 0; k < 2; ++k) dst[m][k] = *(const PG8_LAS bf16x8*)(lds + PG8_SA(b, h) + aoff + m * 2048 + k * 1024); } while (0)
; #define PG8_LDB(dst, b, h) do { _Pragma("unroll") for (int n = 0; n < 2; ++n) _Pragma("unroll") for (int k = 0; k < 2; ++k) dst[n][k] = *(const PG8_LAS bf16x8*)(lds + PG8_SB(b, h) + boff + n * 2048 + k * 1024); } while (0)
; #define PG8_MMA(ai, bj, At, Bt) do { __builtin_amdgcn_s_setprio(1); _Pragma("unroll") for (int m = 0; m < 4; ++m) _Pragma("unroll") for (int n = 0; n < 2; ++n) _Pragma("unroll") for (int k = 0; k < 2; ++k) \
;         acc[ai][bj][m][n] = __builtin_amdgcn_mfma_f32_16x16x32_bf16(Bt[n][k], At[m][k], acc[ai][bj][m][n], 0, 0, 0); __builtin_amdgcn_s_setprio(0); } while (0)
; #define PG8_WAIT_V(n) asm volatile("s_waitcnt vmcnt(" #n ")" ::: "memory")
; #define PG8_WAIT_L(n) asm volatile("s_waitcnt lgkmcnt(" #n ")" ::: "memory")
; #define PG8_BAR __builtin_amdgcn_s_barrier()
; #define PG8_SCHED __builtin_amdgcn_sched_barrier(0)
; template <class Epi, class Sched, bool ALIGN_EPI = false, bool SP2 = false, bool ABLK = false>
; __device__ __forceinline__ void gemm_phase(PG8_LAS unsigned char* lds, const Gemm g, const Sched& S, const Epi& E) {
;     ...
;             PG8_WAIT_V(8); PG8_WAIT_L(0); PG8_BAR; PG8_MMA(1, 0, At, B0); PG8_MMA(1, 1, At, B1); PG8_BAR; PG8_SCHED;
;             PG8_LDB(B0, 1, 0); PG8_LDB(B1, 1, 1); PG8_SCHED; PG8_LDA(At, 1, 0); PG8_STAGE(PG8_SA(0, 1), a2 + hstep, voffA);
;             PG8_WAIT_V(8); PG8_WAIT_L(0); PG8_BAR; PG8_MMA(0, 0, At, B0); PG8_MMA(0, 1, At, B1); PG8_BAR; PG8_SCHED;
	s_setprio 1
	s_waitcnt lgkmcnt(0)
	v_mfma_f32_16x16x32_bf16 v[62:65], v[114:117], v[184:187], v[62:65]
	v_mfma_f32_16x16x32_bf16 v[62:65], v[126:129], v[188:191], v[62:65]
	v_mfma_f32_16x16x32_bf16 v[46:49], v[126:129], v[196:199], v[46:49]
	v_mfma_f32_16x16x32_bf16 v[46:49], v[114:117], v[192:195], v[46:49]
	v_mfma_f32_16x16x32_bf16 v[30:33], v[114:117], v[200:203], v[30:33]
	v_mfma_f32_16x16x32_bf16 v[30:33], v[126:129], v[204:207], v[30:33]
	v_mfma_f32_16x16x32_bf16 v[14:17], v[126:129], v[212:215], v[14:17]
	v_mfma_f32_16x16x32_bf16 v[14:17], v[114:117], v[208:211], v[14:17]
	v_mfma_f32_16x16x32_bf16 v[10:13], v[130:133], v[208:211], v[10:13]
	v_mfma_f32_16x16x32_bf16 v[10:13], v[142:145], v[212:215], v[10:13]
	v_mfma_f32_16x16x32_bf16 v[26:29], v[142:145], v[204:207], v[26:29]
	v_mfma_f32_16x16x32_bf16 v[26:29], v[130:133], v[200:203], v[26:29]
	v_mfma_f32_16x16x32_bf16 v[42:45], v[130:133], v[192:195], v[42:45]
	v_mfma_f32_16x16x32_bf16 v[42:45], v[142:145], v[196:199], v[42:45]
	v_mfma_f32_16x16x32_bf16 v[58:61], v[142:145], v[188:191], v[58:61]
	v_mfma_f32_16x16x32_bf16 v[58:61], v[130:133], v[184:187], v[58:61]
	v_mfma_f32_16x16x32_bf16 v[54:57], v[146:149], v[184:187], v[54:57]
	v_mfma_f32_16x16x32_bf16 v[54:57], v[150:153], v[188:191], v[54:57]
	v_mfma_f32_16x16x32_bf16 v[38:41], v[150:153], v[196:199], v[38:41]
	v_mfma_f32_16x16x32_bf16 v[38:41], v[146:149], v[192:195], v[38:41]
	v_mfma_f32_16x16x32_bf16 v[22:25], v[146:149], v[200:203], v[22:25]
	v_mfma_f32_16x16x32_bf16 v[22:25], v[150:153], v[204:207], v[22:25]
	v_mfma_f32_16x16x32_bf16 v[6:9], v[150:153], v[212:215], v[6:9]
	v_mfma_f32_16x16x32_bf16 v[6:9], v[146:149], v[208:211], v[6:9]
	v_mfma_f32_16x16x32_bf16 v[2:5], v[174:177], v[208:211], v[2:5]
	v_mfma_f32_16x16x32_bf16 v[2:5], v[178:181], v[212:215], v[2:5]
	v_mfma_f32_16x16x32_bf16 v[18:21], v[178:181], v[204:207], v[18:21]
	v_mfma_f32_16x16x32_bf16 v[18:21], v[174:177], v[200:203], v[18:21]
	s_barrier
	s_setprio 2
	v_mfma_f32_16x16x32_bf16 v[34:37], v[174:177], v[192:195], v[34:37]
	v_mfma_f32_16x16x32_bf16 v[34:37], v[178:181], v[196:199], v[34:37]
	v_mfma_f32_16x16x32_bf16 v[50:53], v[178:181], v[188:191], v[50:53]
	v_mfma_f32_16x16x32_bf16 v[50:53], v[174:177], v[184:187], v[50:53]
	s_setprio 3
	s_add_i32 s39, 0, 0x18000
	s_add_i32 s68, 0, 0x1c000
	v_add_u32_e32 v142, s39, v1
	v_add_u32_e32 v173, s68, v1
	ds_read_b128 v[114:117], v142
	ds_read_b128 v[126:129], v142 offset:1024
	ds_read_b128 v[130:133], v142 offset:2048
	ds_read_b128 v[142:145], v142 offset:3072
	ds_read_b128 v[146:149], v173
	ds_read_b128 v[150:153], v173 offset:1024
	ds_read_b128 v[174:177], v173 offset:2048
	ds_read_b128 v[178:181], v173 offset:3072
	s_mov_b32 m0, s58
	v_lshl_add_u64 v[218:219], v[216:217], 0, s[14:15]
	ds_read_b128 v[184:187], v169 offset:32768
	ds_read_b128 v[188:191], v169 offset:33792
	ds_read_b128 v[192:195], v169 offset:34816
	ds_read_b128 v[196:199], v169 offset:35840
	ds_read_b128 v[200:203], v169 offset:36864
	ds_read_b128 v[204:207], v169 offset:37888
	ds_read_b128 v[208:211], v169 offset:38912
	ds_read_b128 v[212:215], v169 offset:39936
	global_load_lds_dwordx4 v[218:219], off
	v_lshl_add_u64 v[218:219], v[216:217], 0, s[16:17]
	s_mov_b32 m0, s59
	s_nop 0
	global_load_lds_dwordx4 v[218:219], off
	s_waitcnt vmcnt(8)
	s_waitcnt lgkmcnt(0)
	s_barrier
	s_setprio 1
	s_waitcnt lgkmcnt(0)
	v_mfma_f32_16x16x32_bf16 v[138:141], v[114:117], v[184:187], v[138:141]
	v_mfma_f32_16x16x32_bf16 v[138:141], v[126:129], v[188:191], v[138:141]
	v_mfma_f32_16x16x32_bf16 v[110:113], v[126:129], v[196:199], v[110:113]
	v_mfma_f32_16x16x32_bf16 v[110:113], v[114:117], v[192:195], v[110:113]
	v_mfma_f32_16x16x32_bf16 v[94:97], v[114:117], v[200:203], v[94:97]
	v_mfma_f32_16x16x32_bf16 v[94:97], v[126:129], v[204:207], v[94:97]
	v_mfma_f32_16x16x32_bf16 v[78:81], v[126:129], v[212:215], v[78:81]
	v_mfma_f32_16x16x32_bf16 v[78:81], v[114:117], v[208:211], v[78:81]
	v_mfma_f32_16x16x32_bf16 v[74:77], v[130:133], v[208:211], v[74:77]
	v_mfma_f32_16x16x32_bf16 v[74:77], v[142:145], v[212:215], v[74:77]
	v_mfma_f32_16x16x32_bf16 v[90:93], v[142:145], v[204:207], v[90:93]
	v_mfma_f32_16x16x32_bf16 v[90:93], v[130:133], v[200:203], v[90:93]
	v_mfma_f32_16x16x32_bf16 v[106:109], v[130:133], v[192:195], v[106:109]
	v_mfma_f32_16x16x32_bf16 v[106:109], v[142:145], v[196:199], v[106:109]
	v_mfma_f32_16x16x32_bf16 v[134:137], v[142:145], v[188:191], v[134:137]
	v_mfma_f32_16x16x32_bf16 v[134:137], v[130:133], v[184:187], v[134:137]
	v_mfma_f32_16x16x32_bf16 v[122:125], v[146:149], v[184:187], v[122:125]
	v_mfma_f32_16x16x32_bf16 v[122:125], v[150:153], v[188:191], v[122:125]
	v_mfma_f32_16x16x32_bf16 v[102:105], v[150:153], v[196:199], v[102:105]
	v_mfma_f32_16x16x32_bf16 v[102:105], v[146:149], v[192:195], v[102:105]
	v_mfma_f32_16x16x32_bf16 v[86:89], v[146:149], v[200:203], v[86:89]
	v_mfma_f32_16x16x32_bf16 v[86:89], v[150:153], v[204:207], v[86:89]
	v_mfma_f32_16x16x32_bf16 v[70:73], v[150:153], v[212:215], v[70:73]
	v_mfma_f32_16x16x32_bf16 v[70:73], v[146:149], v[208:211], v[70:73]
	v_mfma_f32_16x16x32_bf16 v[66:69], v[174:177], v[208:211], v[66:69]
	v_mfma_f32_16x16x32_bf16 v[66:69], v[178:181], v[212:215], v[66:69]
	v_mfma_f32_16x16x32_bf16 v[82:85], v[178:181], v[204:207], v[82:85]
	v_mfma_f32_16x16x32_bf16 v[82:85], v[174:177], v[200:203], v[82:85]
	s_barrier
; #define PG8_STAGE(bufoff, gbase, voff) do { if constexpr (!pg8_noload<Epi>::value) { _Pragma("unroll") for (int _i = 0; _i < 2; ++_i) \
;         __builtin_amdgcn_global_load_lds((const unsigned*)((const char*)(gbase) + (size_t)_i * pstep + (voff)[0]), (PG8_LAS unsigned*)(lds + (bufoff) + ldsw + _i * 8192), 16, 0, 0); } } while (0)
; #define PG8_LDA(dst, b, h) do { _Pragma("unroll") for (int m = 0; m < 4; ++m) _Pragma("unroll") for (int k = 0; k < 2; ++k) dst[m][k] = *(const PG8_LAS bf16x8*)(lds + PG8_SA(b, h) + aoff + m * 2048 + k * 1024); } while (0)
; #define PG8_MMA(ai, bj, At, Bt) do { __builtin_amdgcn_s_setprio(1); _Pragma("unroll") for (int m = 0; m < 4; ++m) _Pragma("unroll") for (int n = 0; n < 2; ++n) _Pragma("unroll") for (int k = 0; k < 2; ++k) \
;         acc[ai][bj][m][n] = __builtin_amdgcn_mfma_f32_16x16x32_bf16(Bt[n][k], At[m][k], acc[ai][bj][m][n], 0, 0, 0); __builtin_amdgcn_s_setprio(0); } while (0)
; #define PG8_WAIT_V(n) asm volatile("s_waitcnt vmcnt(" #n ")" ::: "memory")
; #define PG8_WAIT_L(n) asm volatile("s_waitcnt lgkmcnt(" #n ")" ::: "memory")
; #define PG8_BAR __builtin_amdgcn_s_barrier()
; #define PG8_SCHED __builtin_amdgcn_sched_barrier(0)
; template <class Epi, class Sched, bool ALIGN_EPI = false, bool SP2 = false, bool ABLK = false>
; __device__ __forceinline__ void gemm_phase(PG8_LAS unsigned char* lds, const Gemm g, const Sched& S, const Epi& E) {
;     ...
;             PG8_WAIT_V(8); PG8_WAIT_L(0); PG8_BAR; PG8_MMA(0, 0, At, B0); PG8_MMA(0, 1, At, B1); PG8_BAR; PG8_SCHED;
;             PG8_LDA(At, 1, 1); PG8_STAGE(PG8_SB(1, 0), b3, voffB); PG8_STAGE(PG8_SB(1, 1), b3 + hstep, voffB); PG8_STAGE(PG8_SA(1, 0), a3, voffA);
;             PG8_WAIT_V(8); PG8_WAIT_L(0); PG8_BAR; PG8_MMA(1, 0, At, B0); PG8_MMA(1, 1, At, B1); PG8_BAR; PG8_SCHED;
	s_setprio 2
	v_mfma_f32_16x16x32_bf16 v[98:101], v[174:177], v[192:195], v[98:101]
	v_mfma_f32_16x16x32_bf16 v[98:101], v[178:181], v[196:199], v[98:101]
	v_mfma_f32_16x16x32_bf16 v[118:121], v[178:181], v[188:191], v[118:121]
	v_mfma_f32_16x16x32_bf16 v[118:121], v[174:177], v[184:187], v[118:121]
	s_setprio 3
	s_add_i32 s39, s39, s55
	v_lshl_add_u64 v[218:219], v[162:163], 0, s[24:25]
	s_mov_b32 m0, s39
	ds_read_b128 v[184:187], v169 offset:49152
	ds_read_b128 v[188:191], v169 offset:50176
	ds_read_b128 v[192:195], v169 offset:51200
	ds_read_b128 v[196:199], v169 offset:52224
	ds_read_b128 v[200:203], v169 offset:53248
	ds_read_b128 v[204:207], v169 offset:54272
	ds_read_b128 v[208:211], v169 offset:55296
	ds_read_b128 v[212:215], v169 offset:56320
	global_load_lds_dwordx4 v[218:219], off
	v_lshl_add_u64 v[218:219], v[162:163], 0, s[26:27]
	s_add_i32 m0, s39, 0x2000
	s_add_i32 s39, s68, s55
	global_load_lds_dwordx4 v[218:219], off
	v_lshl_add_u64 v[218:219], v[162:163], 0, s[28:29]
	s_mov_b32 m0, s39
	v_lshl_add_u64 v[162:163], v[162:163], 0, s[30:31]
	global_load_lds_dwordx4 v[218:219], off
	s_add_i32 m0, s39, 0x2000
	s_nop 0
	global_load_lds_dwordx4 v[162:163], off
	v_lshl_add_u64 v[162:163], v[216:217], 0, s[24:25]
	s_mov_b32 m0, s62
	s_nop 0
	global_load_lds_dwordx4 v[162:163], off
	v_lshl_add_u64 v[162:163], v[216:217], 0, s[26:27]
	s_mov_b32 m0, s63
	s_nop 0
	global_load_lds_dwordx4 v[162:163], off
	s_waitcnt vmcnt(8)
	s_waitcnt lgkmcnt(0)
	s_barrier
	s_setprio 1
	s_waitcnt lgkmcnt(0)
	v_mfma_f32_16x16x32_bf16 v[62:65], v[114:117], v[184:187], v[62:65]
	v_mfma_f32_16x16x32_bf16 v[62:65], v[126:129], v[188:191], v[62:65]
	v_mfma_f32_16x16x32_bf16 v[46:49], v[126:129], v[196:199], v[46:49]
	v_mfma_f32_16x16x32_bf16 v[46:49], v[114:117], v[192:195], v[46:49]
	v_mfma_f32_16x16x32_bf16 v[30:33], v[114:117], v[200:203], v[30:33]
	v_mfma_f32_16x16x32_bf16 v[30:33], v[126:129], v[204:207], v[30:33]
	v_mfma_f32_16x16x32_bf16 v[14:17], v[126:129], v[212:215], v[14:17]
	v_mfma_f32_16x16x32_bf16 v[14:17], v[114:117], v[208:211], v[14:17]
	v_mfma_f32_16x16x32_bf16 v[10:13], v[130:133], v[208:211], v[10:13]
	v_mfma_f32_16x16x32_bf16 v[10:13], v[142:145], v[212:215], v[10:13]
	v_mfma_f32_16x16x32_bf16 v[26:29], v[142:145], v[204:207], v[26:29]
	v_mfma_f32_16x16x32_bf16 v[26:29], v[130:133], v[200:203], v[26:29]
	v_mfma_f32_16x16x32_bf16 v[42:45], v[130:133], v[192:195], v[42:45]
	v_mfma_f32_16x16x32_bf16 v[42:45], v[142:145], v[196:199], v[42:45]
	v_mfma_f32_16x16x32_bf16 v[58:61], v[142:145], v[188:191], v[58:61]
	v_mfma_f32_16x16x32_bf16 v[58:61], v[130:133], v[184:187], v[58:61]
	v_mfma_f32_16x16x32_bf16 v[54:57], v[146:149], v[184:187], v[54:57]
	v_mfma_f32_16x16x32_bf16 v[54:57], v[150:153], v[188:191], v[54:57]
	v_mfma_f32_16x16x32_bf16 v[38:41], v[150:153], v[196:199], v[38:41]
	v_mfma_f32_16x16x32_bf16 v[38:41], v[146:149], v[192:195], v[38:41]
	v_mfma_f32_16x16x32_bf16 v[22:25], v[146:149], v[200:203], v[22:25]
	v_mfma_f32_16x16x32_bf16 v[22:25], v[150:153], v[204:207], v[22:25]
	v_mfma_f32_16x16x32_bf16 v[6:9], v[150:153], v[212:215], v[6:9]
	v_mfma_f32_16x16x32_bf16 v[6:9], v[146:149], v[208:211], v[6:9]
	v_mfma_f32_16x16x32_bf16 v[2:5], v[174:177], v[208:211], v[2:5]
	v_mfma_f32_16x16x32_bf16 v[2:5], v[178:181], v[212:215], v[2:5]
	v_mfma_f32_16x16x32_bf16 v[18:21], v[178:181], v[204:207], v[18:21]
	v_mfma_f32_16x16x32_bf16 v[18:21], v[174:177], v[200:203], v[18:21]
	s_barrier
	s_setprio 2
	v_mfma_f32_16x16x32_bf16 v[34:37], v[174:177], v[192:195], v[34:37]
	v_mfma_f32_16x16x32_bf16 v[34:37], v[178:181], v[196:199], v[34:37]
	v_mfma_f32_16x16x32_bf16 v[50:53], v[178:181], v[188:191], v[50:53]
	v_mfma_f32_16x16x32_bf16 v[50:53], v[174:177], v[184:187], v[50:53]
	s_setprio 3
	s_add_u32 s92, s92, 0x1000
	s_addc_u32 s93, s93, 0
	s_add_u32 s11, s11, 0x1000
	s_addc_u32 s37, s37, 0
	s_cmp_ge_i32 s65, s80
	s_mov_b32 s39, s65
	s_cbranch_scc0 .LBB0_487
	s_and_b64 vcc, exec, s[34:35]
	s_cbranch_vccnz .LBB0_492
	s_lshl_b32 s11, s2, 8
	s_cmp_gt_i32 s2, 63
	s_mov_b64 s[68:69], -1
	s_cbranch_scc1 .LBB0_493

; #define PG8_STAGE(bufoff, gbase, voff) do { if constexpr (!pg8_noload<Epi>::value) { _Pragma("unroll") for (int _i = 0; _i < 2; ++_i) \
;         __builtin_amdgcn_global_load_lds((const unsigned*)((const char*)(gbase) + (size_t)_i * pstep + (voff)[0]), (PG8_LAS unsigned*)(lds + (bufoff) + ldsw + _i * 8192), 16, 0, 0); } } while (0)
; #define PG8_LDA(dst, b, h) do { _Pragma("unroll") for (int m = 0; m < 4; ++m) _Pragma("unroll") for (int k = 0; k < 2; ++k) dst[m][k] = *(const PG8_LAS bf16x8*)(lds + PG8_SA(b, h) + aoff + m * 2048 + k * 1024); } while (0)
; #define PG8_LDB(dst, b, h) do { _Pragma("unroll") for (int n = 0; n < 2; ++n) _Pragma("unroll") for (int k = 0; k < 2; ++k) dst[n][k] = *(const PG8_LAS bf16x8*)(lds + PG8_SB(b, h) + boff + n * 2048 + k * 1024); } while (0)
; #define PG8_MMA(ai, bj, At, Bt) do { __builtin_amdgcn_s_setprio(1); _Pragma("unroll") for (int m = 0; m < 4; ++m) _Pragma("unroll") for (int n = 0; n < 2; ++n) _Pragma("unroll") for (int k = 0; k < 2; ++k) \
;         acc[ai][bj][m][n] = __builtin_amdgcn_mfma_f32_16x16x32_bf16(Bt[n][k], At[m][k], acc[ai][bj][m][n], 0, 0, 0); __builtin_amdgcn_s_setprio(0); } while (0)
; #define PG8_BAR __builtin_amdgcn_s_barrier()
; template <class Epi, class Sched, bool ALIGN_EPI = false, bool SP2 = false, bool ABLK = false>
; __device__ __forceinline__ void gemm_phase(PG8_LAS unsigned char* lds, const Gemm g, const Sched& S, const Epi& E) {
;     ...
;         for (int t = 0; t < nt; t += 2) {
;             const bool last = (t == nt - 2);
;             const char* a1 = cA + (size_t)(t + 1) * kstep;
;             const char* a2 = last ? nA : cA + (size_t)(t + 2) * kstep; const char* b2 = last ? nB : cB + (size_t)(t + 2) * kstepB;
;             const char* a3 = a2 + kstep; const char* b3 = b2 + kstepB;
;             if (last && has_next) S.a_ready(nxt);
;             if constexpr (SP2) {
;             PG8_LDB(B0, 0, 0); PG8_LDB(B1, 0, 1); PG8_SCHED; PG8_LDA(At, 0, 0); PG8_STAGE(PG8_SA(1, 1), a1 + hstep, voffA);
;             PG8_WAIT_V(8); PG8_WAIT_L(0); PG8_BAR; PG8_MMA(0, 0, At, B0); PG8_MMA(0, 1, At, B1); PG8_BAR; PG8_SCHED;
;             PG8_LDA(At, 0, 1); PG8_STAGE(PG8_SB(0, 0), b2, voffB); PG8_STAGE(PG8_SB(0, 1), b2 + hstep, voffB); PG8_STAGE(PG8_SA(0, 0), a2, voffA);
;             PG8_WAIT_V(8); PG8_WAIT_L(0); PG8_BAR; PG8_MMA(1, 0, At, B0); PG8_MMA(1, 1, At, B1); PG8_BAR; PG8_SCHED;
.LBB0_619:
	s_or_b32 s28, s57, 1
	s_lshl_b64 s[58:59], s[28:29], 11
	s_add_u32 s58, s2, s58
	s_addc_u32 s59, s3, s59
	s_add_i32 s28, s57, 2
	v_add_u32_e32 v160, s78, v168
	v_add_u32_e32 v180, s79, v168
	s_lshl_b64 s[60:61], s[28:29], 11
	ds_read_b128 v[130:133], v160
	ds_read_b128 v[134:137], v160 offset:1024
	ds_read_b128 v[156:159], v160 offset:2048
	ds_read_b128 v[160:163], v160 offset:3072
	ds_read_b128 v[164:167], v180
	ds_read_b128 v[176:179], v180 offset:1024
	ds_read_b128 v[184:187], v180 offset:2048
	ds_read_b128 v[188:191], v180 offset:3072
	s_add_u32 s66, s2, s60
	s_addc_u32 s67, s3, s61
	s_and_b64 s[62:63], s[68:69], exec
	s_cselect_b32 s73, s67, s7
	s_cselect_b32 s72, s66, s15
	s_add_u32 s62, s16, s60
	s_addc_u32 s63, s17, s61
	s_and_b64 s[60:61], s[68:69], exec
	s_cselect_b32 s61, s63, s9
	s_cselect_b32 s60, s62, s56
	v_lshl_add_u64 v[180:181], s[58:59], 0, v[138:139]
	v_lshl_add_u64 v[224:225], v[180:181], 0, s[24:25]
	s_add_i32 m0, s70, 0xc000
	ds_read_b128 v[192:195], v173
	ds_read_b128 v[196:199], v173 offset:1024
	ds_read_b128 v[200:203], v173 offset:2048
	ds_read_b128 v[204:207], v173 offset:3072
	ds_read_b128 v[208:211], v173 offset:4096
	ds_read_b128 v[212:215], v173 offset:5120
	ds_read_b128 v[216:219], v173 offset:6144
	ds_read_b128 v[220:223], v173 offset:7168
	global_load_lds_dwordx4 v[224:225], off
	v_lshl_add_u64 v[180:181], v[180:181], 0, s[26:27]
	s_add_i32 m0, s70, 0xe000
	s_nop 0
	global_load_lds_dwordx4 v[180:181], off
	s_waitcnt vmcnt(8)
	s_waitcnt lgkmcnt(0)
	s_barrier
	s_setprio 1
	s_waitcnt lgkmcnt(0)
	v_mfma_f32_16x16x32_bf16 v[126:129], v[130:133], v[192:195], v[126:129]
	v_mfma_f32_16x16x32_bf16 v[126:129], v[134:137], v[196:199], v[126:129]
	v_mfma_f32_16x16x32_bf16 v[110:113], v[134:137], v[204:207], v[110:113]
	v_mfma_f32_16x16x32_bf16 v[110:113], v[130:133], v[200:203], v[110:113]
	v_mfma_f32_16x16x32_bf16 v[94:97], v[130:133], v[208:211], v[94:97]
	v_mfma_f32_16x16x32_bf16 v[94:97], v[134:137], v[212:215], v[94:97]
	v_mfma_f32_16x16x32_bf16 v[78:81], v[134:137], v[220:223], v[78:81]
	v_mfma_f32_16x16x32_bf16 v[78:81], v[130:133], v[216:219], v[78:81]
	v_mfma_f32_16x16x32_bf16 v[74:77], v[156:159], v[216:219], v[74:77]
	v_mfma_f32_16x16x32_bf16 v[74:77], v[160:163], v[220:223], v[74:77]
	v_mfma_f32_16x16x32_bf16 v[90:93], v[160:163], v[212:215], v[90:93]
	v_mfma_f32_16x16x32_bf16 v[90:93], v[156:159], v[208:211], v[90:93]
	v_mfma_f32_16x16x32_bf16 v[106:109], v[156:159], v[200:203], v[106:109]
	v_mfma_f32_16x16x32_bf16 v[106:109], v[160:163], v[204:207], v[106:109]
	v_mfma_f32_16x16x32_bf16 v[122:125], v[160:163], v[196:199], v[122:125]
	v_mfma_f32_16x16x32_bf16 v[122:125], v[156:159], v[192:195], v[122:125]
	v_mfma_f32_16x16x32_bf16 v[118:121], v[164:167], v[192:195], v[118:121]
	v_mfma_f32_16x16x32_bf16 v[118:121], v[176:179], v[196:199], v[118:121]
	v_mfma_f32_16x16x32_bf16 v[102:105], v[176:179], v[204:207], v[102:105]
	v_mfma_f32_16x16x32_bf16 v[102:105], v[164:167], v[200:203], v[102:105]
	v_mfma_f32_16x16x32_bf16 v[86:89], v[164:167], v[208:211], v[86:89]
	v_mfma_f32_16x16x32_bf16 v[86:89], v[176:179], v[212:215], v[86:89]
	v_mfma_f32_16x16x32_bf16 v[70:73], v[176:179], v[220:223], v[70:73]
	v_mfma_f32_16x16x32_bf16 v[70:73], v[164:167], v[216:219], v[70:73]
	v_mfma_f32_16x16x32_bf16 v[66:69], v[184:187], v[216:219], v[66:69]
	v_mfma_f32_16x16x32_bf16 v[66:69], v[188:191], v[220:223], v[66:69]
	v_mfma_f32_16x16x32_bf16 v[82:85], v[188:191], v[212:215], v[82:85]
	v_mfma_f32_16x16x32_bf16 v[82:85], v[184:187], v[208:211], v[82:85]
	s_barrier
	s_setprio 2
	v_mfma_f32_16x16x32_bf16 v[98:101], v[184:187], v[200:203], v[98:101]
	v_mfma_f32_16x16x32_bf16 v[98:101], v[188:191], v[204:207], v[98:101]
	v_mfma_f32_16x16x32_bf16 v[114:117], v[188:191], v[196:199], v[114:117]
	v_mfma_f32_16x16x32_bf16 v[114:117], v[184:187], v[192:195], v[114:117]
	s_setprio 3
	s_add_i32 s58, s78, s91
	v_lshl_add_u64 v[180:181], s[60:61], 0, v[138:139]
	s_mov_b32 m0, s58
	ds_read_b128 v[192:195], v173 offset:16384
	ds_read_b128 v[196:199], v173 offset:17408
	ds_read_b128 v[200:203], v173 offset:18432
	ds_read_b128 v[204:207], v173 offset:19456
	ds_read_b128 v[208:211], v173 offset:20480
	ds_read_b128 v[212:215], v173 offset:21504
	ds_read_b128 v[216:219], v173 offset:22528
	ds_read_b128 v[220:223], v173 offset:23552
	global_load_lds_dwordx4 v[180:181], off
	v_lshl_add_u64 v[224:225], v[180:181], 0, s[22:23]
	s_add_i32 m0, s58, 0x2000
	s_add_i32 s58, s79, s91
	global_load_lds_dwordx4 v[224:225], off
	v_lshl_add_u64 v[224:225], v[180:181], 0, s[24:25]
	s_mov_b32 m0, s58
	s_nop 0
	global_load_lds_dwordx4 v[224:225], off
	v_lshl_add_u64 v[224:225], v[180:181], 0, s[26:27]
	s_add_i32 m0, s58, 0x2000
	s_nop 0
	global_load_lds_dwordx4 v[224:225], off
	v_lshl_add_u64 v[224:225], s[72:73], 0, v[138:139]
	s_mov_b32 m0, s70
	v_lshl_add_u64 v[226:227], v[224:225], 0, s[22:23]
	global_load_lds_dwordx4 v[224:225], off
	s_mov_b32 m0, s71
	s_nop 0
	global_load_lds_dwordx4 v[226:227], off
	s_waitcnt vmcnt(8)
	s_waitcnt lgkmcnt(0)
	s_barrier
; #define PG8_STAGE(bufoff, gbase, voff) do { if constexpr (!pg8_noload<Epi>::value) { _Pragma("unroll") for (int _i = 0; _i < 2; ++_i) \
;         __builtin_amdgcn_global_load_lds((const unsigned*)((const char*)(gbase) + (size_t)_i * pstep + (voff)[0]), (PG8_LAS unsigned*)(lds + (bufoff) + ldsw + _i * 8192), 16, 0, 0); } } while (0)
; #define PG8_LDA(dst, b, h) do { _Pragma("unroll") for (int m = 0; m < 4; ++m) _Pragma("unroll") for (int k = 0; k < 2; ++k) dst[m][k] = *(const PG8_LAS bf16x8*)(lds + PG8_SA(b, h) + aoff + m * 2048 + k * 1024); } while (0)
; #define PG8_LDB(dst, b, h) do { _Pragma("unroll") for (int n = 0; n < 2; ++n) _Pragma("unroll") for (int k = 0; k < 2; ++k) dst[n][k] = *(const PG8_LAS bf16x8*)(lds + PG8_SB(b, h) + boff + n * 2048 + k * 1024); } while (0)
; #define PG8_MMA(ai, bj, At, Bt) do { __builtin_amdgcn_s_setprio(1); _Pragma("unroll") for (int m = 0; m < 4; ++m) _Pragma("unroll") for (int n = 0; n < 2; ++n) _Pragma("unroll") for (int k = 0; k < 2; ++k) \
;         acc[ai][bj][m][n] = __builtin_amdgcn_mfma_f32_16x16x32_bf16(Bt[n][k], At[m][k], acc[ai][bj][m][n], 0, 0, 0); __builtin_amdgcn_s_setprio(0); } while (0)
; #define PG8_WAIT_V(n) asm volatile("s_waitcnt vmcnt(" #n ")" ::: "memory")
; #define PG8_WAIT_L(n) asm volatile("s_waitcnt lgkmcnt(" #n ")" ::: "memory")
; #define PG8_BAR __builtin_amdgcn_s_barrier()
; #define PG8_SCHED __builtin_amdgcn_sched_barrier(0)
; template <class Epi, class Sched, bool ALIGN_EPI = false, bool SP2 = false, bool ABLK = false>
; __device__ __forceinline__ void gemm_phase(PG8_LAS unsigned char* lds, const Gemm g, const Sched& S, const Epi& E) {
;     ...
;             PG8_WAIT_V(8); PG8_WAIT_L(0); PG8_BAR; PG8_MMA(1, 0, At, B0); PG8_MMA(1, 1, At, B1); PG8_BAR; PG8_SCHED;
;             PG8_LDB(B0, 1, 0); PG8_LDB(B1, 1, 1); PG8_SCHED; PG8_LDA(At, 1, 0); PG8_STAGE(PG8_SA(0, 1), a2 + hstep, voffA);
;             PG8_WAIT_V(8); PG8_WAIT_L(0); PG8_BAR; PG8_MMA(0, 0, At, B0); PG8_MMA(0, 1, At, B1); PG8_BAR; PG8_SCHED;
	s_setprio 1
	s_waitcnt lgkmcnt(0)
	v_mfma_f32_16x16x32_bf16 v[62:65], v[130:133], v[192:195], v[62:65]
	v_mfma_f32_16x16x32_bf16 v[62:65], v[134:137], v[196:199], v[62:65]
	v_mfma_f32_16x16x32_bf16 v[46:49], v[134:137], v[204:207], v[46:49]
	v_mfma_f32_16x16x32_bf16 v[46:49], v[130:133], v[200:203], v[46:49]
	v_mfma_f32_16x16x32_bf16 v[30:33], v[130:133], v[208:211], v[30:33]
	v_mfma_f32_16x16x32_bf16 v[30:33], v[134:137], v[212:215], v[30:33]
	v_mfma_f32_16x16x32_bf16 v[14:17], v[134:137], v[220:223], v[14:17]
	v_mfma_f32_16x16x32_bf16 v[14:17], v[130:133], v[216:219], v[14:17]
	v_mfma_f32_16x16x32_bf16 v[10:13], v[156:159], v[216:219], v[10:13]
	v_mfma_f32_16x16x32_bf16 v[10:13], v[160:163], v[220:223], v[10:13]
	v_mfma_f32_16x16x32_bf16 v[26:29], v[160:163], v[212:215], v[26:29]
	v_mfma_f32_16x16x32_bf16 v[26:29], v[156:159], v[208:211], v[26:29]
	v_mfma_f32_16x16x32_bf16 v[42:45], v[156:159], v[200:203], v[42:45]
	v_mfma_f32_16x16x32_bf16 v[42:45], v[160:163], v[204:207], v[42:45]
	v_mfma_f32_16x16x32_bf16 v[58:61], v[160:163], v[196:199], v[58:61]
	v_mfma_f32_16x16x32_bf16 v[58:61], v[156:159], v[192:195], v[58:61]
	v_mfma_f32_16x16x32_bf16 v[54:57], v[164:167], v[192:195], v[54:57]
	v_mfma_f32_16x16x32_bf16 v[54:57], v[176:179], v[196:199], v[54:57]
	v_mfma_f32_16x16x32_bf16 v[38:41], v[176:179], v[204:207], v[38:41]
	v_mfma_f32_16x16x32_bf16 v[38:41], v[164:167], v[200:203], v[38:41]
	v_mfma_f32_16x16x32_bf16 v[22:25], v[164:167], v[208:211], v[22:25]
	v_mfma_f32_16x16x32_bf16 v[22:25], v[176:179], v[212:215], v[22:25]
	v_mfma_f32_16x16x32_bf16 v[6:9], v[176:179], v[220:223], v[6:9]
	v_mfma_f32_16x16x32_bf16 v[6:9], v[164:167], v[216:219], v[6:9]
	v_mfma_f32_16x16x32_bf16 v[2:5], v[184:187], v[216:219], v[2:5]
	v_mfma_f32_16x16x32_bf16 v[2:5], v[188:191], v[220:223], v[2:5]
	v_mfma_f32_16x16x32_bf16 v[18:21], v[188:191], v[212:215], v[18:21]
	v_mfma_f32_16x16x32_bf16 v[18:21], v[184:187], v[208:211], v[18:21]
	s_barrier
	s_setprio 2
	v_mfma_f32_16x16x32_bf16 v[34:37], v[184:187], v[200:203], v[34:37]
	v_mfma_f32_16x16x32_bf16 v[34:37], v[188:191], v[204:207], v[34:37]
	v_mfma_f32_16x16x32_bf16 v[50:53], v[188:191], v[196:199], v[50:53]
	v_mfma_f32_16x16x32_bf16 v[50:53], v[184:187], v[192:195], v[50:53]
	s_setprio 3
	s_add_i32 s58, 0, 0x18000
	s_add_i32 s59, 0, 0x1c000
	v_add_u32_e32 v160, s58, v168
	v_add_u32_e32 v188, s59, v168
	ds_read_b128 v[130:133], v160
	ds_read_b128 v[134:137], v160 offset:1024
	ds_read_b128 v[156:159], v160 offset:2048
	ds_read_b128 v[160:163], v160 offset:3072
	ds_read_b128 v[164:167], v188
	ds_read_b128 v[176:179], v188 offset:1024
	ds_read_b128 v[184:187], v188 offset:2048
	ds_read_b128 v[188:191], v188 offset:3072
	s_mov_b32 m0, s34
	v_lshl_add_u64 v[226:227], v[224:225], 0, s[24:25]
	ds_read_b128 v[192:195], v173 offset:32768
	ds_read_b128 v[196:199], v173 offset:33792
	ds_read_b128 v[200:203], v173 offset:34816
	ds_read_b128 v[204:207], v173 offset:35840
	ds_read_b128 v[208:211], v173 offset:36864
	ds_read_b128 v[212:215], v173 offset:37888
	ds_read_b128 v[216:219], v173 offset:38912
	ds_read_b128 v[220:223], v173 offset:39936
	global_load_lds_dwordx4 v[226:227], off
	v_lshl_add_u64 v[226:227], v[224:225], 0, s[26:27]
	s_mov_b32 m0, s35
	s_nop 0
	global_load_lds_dwordx4 v[226:227], off
	s_waitcnt vmcnt(8)
	s_waitcnt lgkmcnt(0)
	s_barrier
	s_setprio 1
	s_waitcnt lgkmcnt(0)
	v_mfma_f32_16x16x32_bf16 v[126:129], v[130:133], v[192:195], v[126:129]
	v_mfma_f32_16x16x32_bf16 v[126:129], v[134:137], v[196:199], v[126:129]
	v_mfma_f32_16x16x32_bf16 v[110:113], v[134:137], v[204:207], v[110:113]
	v_mfma_f32_16x16x32_bf16 v[110:113], v[130:133], v[200:203], v[110:113]
	v_mfma_f32_16x16x32_bf16 v[94:97], v[130:133], v[208:211], v[94:97]
	v_mfma_f32_16x16x32_bf16 v[94:97], v[134:137], v[212:215], v[94:97]
	v_mfma_f32_16x16x32_bf16 v[78:81], v[134:137], v[220:223], v[78:81]
	v_mfma_f32_16x16x32_bf16 v[78:81], v[130:133], v[216:219], v[78:81]
	v_mfma_f32_16x16x32_bf16 v[74:77], v[156:159], v[216:219], v[74:77]
	v_mfma_f32_16x16x32_bf16 v[74:77], v[160:163], v[220:223], v[74:77]
	v_mfma_f32_16x16x32_bf16 v[90:93], v[160:163], v[212:215], v[90:93]
	v_mfma_f32_16x16x32_bf16 v[90:93], v[156:159], v[208:211], v[90:93]
	v_mfma_f32_16x16x32_bf16 v[106:109], v[156:159], v[200:203], v[106:109]
	v_mfma_f32_16x16x32_bf16 v[106:109], v[160:163], v[204:207], v[106:109]
	v_mfma_f32_16x16x32_bf16 v[122:125], v[160:163], v[196:199], v[122:125]
	v_mfma_f32_16x16x32_bf16 v[122:125], v[156:159], v[192:195], v[122:125]
	v_mfma_f32_16x16x32_bf16 v[118:121], v[164:167], v[192:195], v[118:121]
	v_mfma_f32_16x16x32_bf16 v[118:121], v[176:179], v[196:199], v[118:121]
	v_mfma_f32_16x16x32_bf16 v[102:105], v[176:179], v[204:207], v[102:105]
	v_mfma_f32_16x16x32_bf16 v[102:105], v[164:167], v[200:203], v[102:105]
	v_mfma_f32_16x16x32_bf16 v[86:89], v[164:167], v[208:211], v[86:89]
	v_mfma_f32_16x16x32_bf16 v[86:89], v[176:179], v[212:215], v[86:89]
	v_mfma_f32_16x16x32_bf16 v[70:73], v[176:179], v[220:223], v[70:73]
	v_mfma_f32_16x16x32_bf16 v[70:73], v[164:167], v[216:219], v[70:73]
	v_mfma_f32_16x16x32_bf16 v[66:69], v[184:187], v[216:219], v[66:69]
	v_mfma_f32_16x16x32_bf16 v[66:69], v[188:191], v[220:223], v[66:69]
	v_mfma_f32_16x16x32_bf16 v[82:85], v[188:191], v[212:215], v[82:85]
	v_mfma_f32_16x16x32_bf16 v[82:85], v[184:187], v[208:211], v[82:85]
	s_barrier
; #define PG8_STAGE(bufoff, gbase, voff) do { if constexpr (!pg8_noload<Epi>::value) { _Pragma("unroll") for (int _i = 0; _i < 2; ++_i) \
;         __builtin_amdgcn_global_load_lds((const unsigned*)((const char*)(gbase) + (size_t)_i * pstep + (voff)[0]), (PG8_LAS unsigned*)(lds + (bufoff) + ldsw + _i * 8192), 16, 0, 0); } } while (0)
; #define PG8_LDA(dst, b, h) do { _Pragma("unroll") for (int m = 0; m < 4; ++m) _Pragma("unroll") for (int k = 0; k < 2; ++k) dst[m][k] = *(const PG8_LAS bf16x8*)(lds + PG8_SA(b, h) + aoff + m * 2048 + k * 1024); } while (0)
; #define PG8_MMA(ai, bj, At, Bt) do { __builtin_amdgcn_s_setprio(1); _Pragma("unroll") for (int m = 0; m < 4; ++m) _Pragma("unroll") for (int n = 0; n < 2; ++n) _Pragma("unroll") for (int k = 0; k < 2; ++k) \
;         acc[ai][bj][m][n] = __builtin_amdgcn_mfma_f32_16x16x32_bf16(Bt[n][k], At[m][k], acc[ai][bj][m][n], 0, 0, 0); __builtin_amdgcn_s_setprio(0); } while (0)
; #define PG8_WAIT_V(n) asm volatile("s_waitcnt vmcnt(" #n ")" ::: "memory")
; #define PG8_WAIT_L(n) asm volatile("s_waitcnt lgkmcnt(" #n ")" ::: "memory")
; #define PG8_BAR __builtin_amdgcn_s_barrier()
; #define PG8_SCHED __builtin_amdgcn_sched_barrier(0)
; template <class Epi, class Sched, bool ALIGN_EPI = false, bool SP2 = false, bool ABLK = false>
; __device__ __forceinline__ void gemm_phase(PG8_LAS unsigned char* lds, const Gemm g, const Sched& S, const Epi& E) {
;     ...
;             PG8_WAIT_V(8); PG8_WAIT_L(0); PG8_BAR; PG8_MMA(0, 0, At, B0); PG8_MMA(0, 1, At, B1); PG8_BAR; PG8_SCHED;
;             PG8_LDA(At, 1, 1); PG8_STAGE(PG8_SB(1, 0), b3, voffB); PG8_STAGE(PG8_SB(1, 1), b3 + hstep, voffB); PG8_STAGE(PG8_SA(1, 0), a3, voffA);
;             PG8_WAIT_V(8); PG8_WAIT_L(0); PG8_BAR; PG8_MMA(1, 0, At, B0); PG8_MMA(1, 1, At, B1); PG8_BAR; PG8_SCHED;
	s_setprio 2
	v_mfma_f32_16x16x32_bf16 v[98:101], v[184:187], v[200:203], v[98:101]
	v_mfma_f32_16x16x32_bf16 v[98:101], v[188:191], v[204:207], v[98:101]
	v_mfma_f32_16x16x32_bf16 v[114:117], v[188:191], v[196:199], v[114:117]
	v_mfma_f32_16x16x32_bf16 v[114:117], v[184:187], v[192:195], v[114:117]
	s_setprio 3
	s_add_i32 s58, s58, s91
	v_lshl_add_u64 v[226:227], v[180:181], 0, s[92:93]
	s_mov_b32 m0, s58
	ds_read_b128 v[192:195], v173 offset:49152
	ds_read_b128 v[196:199], v173 offset:50176
	ds_read_b128 v[200:203], v173 offset:51200
	ds_read_b128 v[204:207], v173 offset:52224
	ds_read_b128 v[208:211], v173 offset:53248
	ds_read_b128 v[212:215], v173 offset:54272
	ds_read_b128 v[216:219], v173 offset:55296
	ds_read_b128 v[220:223], v173 offset:56320
	global_load_lds_dwordx4 v[226:227], off
	v_lshl_add_u64 v[226:227], v[180:181], 0, s[94:95]
	s_add_i32 m0, s58, 0x2000
	s_add_i32 s58, s59, s91
	global_load_lds_dwordx4 v[226:227], off
	v_lshl_add_u64 v[226:227], v[180:181], 0, s[96:97]
	s_mov_b32 m0, s58
	v_lshl_add_u64 v[180:181], v[180:181], 0, s[88:89]
	global_load_lds_dwordx4 v[226:227], off
	s_add_i32 m0, s58, 0x2000
	s_nop 0
	global_load_lds_dwordx4 v[180:181], off
	v_lshl_add_u64 v[180:181], v[224:225], 0, s[92:93]
	s_mov_b32 m0, s10
	s_nop 0
	global_load_lds_dwordx4 v[180:181], off
	v_lshl_add_u64 v[180:181], v[224:225], 0, s[94:95]
	s_mov_b32 m0, s11
	s_nop 0
	global_load_lds_dwordx4 v[180:181], off
	s_waitcnt vmcnt(8)
	s_waitcnt lgkmcnt(0)
	s_barrier
	s_setprio 1
	s_waitcnt lgkmcnt(0)
	v_mfma_f32_16x16x32_bf16 v[62:65], v[130:133], v[192:195], v[62:65]
	v_mfma_f32_16x16x32_bf16 v[62:65], v[134:137], v[196:199], v[62:65]
	v_mfma_f32_16x16x32_bf16 v[46:49], v[134:137], v[204:207], v[46:49]
	v_mfma_f32_16x16x32_bf16 v[46:49], v[130:133], v[200:203], v[46:49]
	v_mfma_f32_16x16x32_bf16 v[30:33], v[130:133], v[208:211], v[30:33]
	v_mfma_f32_16x16x32_bf16 v[30:33], v[134:137], v[212:215], v[30:33]
	v_mfma_f32_16x16x32_bf16 v[14:17], v[134:137], v[220:223], v[14:17]
	v_mfma_f32_16x16x32_bf16 v[14:17], v[130:133], v[216:219], v[14:17]
	v_mfma_f32_16x16x32_bf16 v[10:13], v[156:159], v[216:219], v[10:13]
	v_mfma_f32_16x16x32_bf16 v[10:13], v[160:163], v[220:223], v[10:13]
	v_mfma_f32_16x16x32_bf16 v[26:29], v[160:163], v[212:215], v[26:29]
	v_mfma_f32_16x16x32_bf16 v[26:29], v[156:159], v[208:211], v[26:29]
	v_mfma_f32_16x16x32_bf16 v[42:45], v[156:159], v[200:203], v[42:45]
	v_mfma_f32_16x16x32_bf16 v[42:45], v[160:163], v[204:207], v[42:45]
	v_mfma_f32_16x16x32_bf16 v[58:61], v[160:163], v[196:199], v[58:61]
	v_mfma_f32_16x16x32_bf16 v[58:61], v[156:159], v[192:195], v[58:61]
	v_mfma_f32_16x16x32_bf16 v[54:57], v[164:167], v[192:195], v[54:57]
	v_mfma_f32_16x16x32_bf16 v[54:57], v[176:179], v[196:199], v[54:57]
	v_mfma_f32_16x16x32_bf16 v[38:41], v[176:179], v[204:207], v[38:41]
	v_mfma_f32_16x16x32_bf16 v[38:41], v[164:167], v[200:203], v[38:41]
	v_mfma_f32_16x16x32_bf16 v[22:25], v[164:167], v[208:211], v[22:25]
	v_mfma_f32_16x16x32_bf16 v[22:25], v[176:179], v[212:215], v[22:25]
	v_mfma_f32_16x16x32_bf16 v[6:9], v[176:179], v[220:223], v[6:9]
	v_mfma_f32_16x16x32_bf16 v[6:9], v[164:167], v[216:219], v[6:9]
	v_mfma_f32_16x16x32_bf16 v[2:5], v[184:187], v[216:219], v[2:5]
	v_mfma_f32_16x16x32_bf16 v[2:5], v[188:191], v[220:223], v[2:5]
	v_mfma_f32_16x16x32_bf16 v[18:21], v[188:191], v[212:215], v[18:21]
	v_mfma_f32_16x16x32_bf16 v[18:21], v[184:187], v[208:211], v[18:21]
	s_barrier
	s_setprio 2
	v_mfma_f32_16x16x32_bf16 v[34:37], v[184:187], v[200:203], v[34:37]
	v_mfma_f32_16x16x32_bf16 v[34:37], v[188:191], v[204:207], v[34:37]
	v_mfma_f32_16x16x32_bf16 v[50:53], v[188:191], v[196:199], v[50:53]
	v_mfma_f32_16x16x32_bf16 v[50:53], v[184:187], v[192:195], v[50:53]
	s_setprio 3
	s_cmp_gt_u32 s57, 29
	s_mov_b32 s57, s28
	s_cbranch_scc1 .LBB0_631

; #define PG8_STAGE(bufoff, gbase, voff) do { if constexpr (!pg8_noload<Epi>::value) { _Pragma("unroll") for (int _i = 0; _i < 2; ++_i) \
;         __builtin_amdgcn_global_load_lds((const unsigned*)((const char*)(gbase) + (size_t)_i * pstep + (voff)[0]), (PG8_LAS unsigned*)(lds + (bufoff) + ldsw + _i * 8192), 16, 0, 0); } } while (0)
; #define PG8_LDA(dst, b, h) do { _Pragma("unroll") for (int m = 0; m < 4; ++m) _Pragma("unroll") for (int k = 0; k < 2; ++k) dst[m][k] = *(const PG8_LAS bf16x8*)(lds + PG8_SA(b, h) + aoff + m * 2048 + k * 1024); } while (0)
; #define PG8_LDB(dst, b, h) do { _Pragma("unroll") for (int n = 0; n < 2; ++n) _Pragma("unroll") for (int k = 0; k < 2; ++k) dst[n][k] = *(const PG8_LAS bf16x8*)(lds + PG8_SB(b, h) + boff + n * 2048 + k * 1024); } while (0)
; #define PG8_MMA(ai, bj, At, Bt) do { __builtin_amdgcn_s_setprio(1); _Pragma("unroll") for (int m = 0; m < 4; ++m) _Pragma("unroll") for (int n = 0; n < 2; ++n) _Pragma("unroll") for (int k = 0; k < 2; ++k) \
;         acc[ai][bj][m][n] = __builtin_amdgcn_mfma_f32_16x16x32_bf16(Bt[n][k], At[m][k], acc[ai][bj][m][n], 0, 0, 0); __builtin_amdgcn_s_setprio(0); } while (0)
; #define PG8_BAR __builtin_amdgcn_s_barrier()
; template <class Epi, class Sched, bool ALIGN_EPI = false, bool SP2 = false, bool ABLK = false>
; __device__ __forceinline__ void gemm_phase(PG8_LAS unsigned char* lds, const Gemm g, const Sched& S, const Epi& E) {
;     ...
;         for (int t = 0; t < nt; t += 2) {
;             const bool last = (t == nt - 2);
;             const char* a1 = cA + (size_t)(t + 1) * kstep;
;             const char* a2 = last ? nA : cA + (size_t)(t + 2) * kstep; const char* b2 = last ? nB : cB + (size_t)(t + 2) * kstepB;
;             const char* a3 = a2 + kstep; const char* b3 = b2 + kstepB;
;             if (last && has_next) S.a_ready(nxt);
;             if constexpr (SP2) {
;             PG8_LDB(B0, 0, 0); PG8_LDB(B1, 0, 1); PG8_SCHED; PG8_LDA(At, 0, 0); PG8_STAGE(PG8_SA(1, 1), a1 + hstep, voffA);
;             PG8_WAIT_V(8); PG8_WAIT_L(0); PG8_BAR; PG8_MMA(0, 0, At, B0); PG8_MMA(0, 1, At, B1); PG8_BAR; PG8_SCHED;
;             PG8_LDA(At, 0, 1); PG8_STAGE(PG8_SB(0, 0), b2, voffB); PG8_STAGE(PG8_SB(0, 1), b2 + hstep, voffB); PG8_STAGE(PG8_SA(0, 0), a2, voffA);
;             PG8_WAIT_V(8); PG8_WAIT_L(0); PG8_BAR; PG8_MMA(1, 0, At, B0); PG8_MMA(1, 1, At, B1); PG8_BAR; PG8_SCHED;
.LBB0_1533:
	ds_read_b128 v[114:117], v167
	ds_read_b128 v[126:129], v167 offset:1024
	ds_read_b128 v[130:133], v167 offset:2048
	ds_read_b128 v[142:145], v167 offset:3072
	ds_read_b128 v[146:149], v168
	ds_read_b128 v[150:153], v168 offset:1024
	ds_read_b128 v[174:177], v168 offset:2048
	ds_read_b128 v[178:181], v168 offset:3072
	s_add_i32 s41, s39, 2
	s_add_u32 s70, s68, 0xfff00800
	s_addc_u32 s71, s69, -1
	s_cmp_eq_u32 s3, s39
	s_cselect_b32 s71, s43, s71
	s_cselect_b32 s70, s42, s70
	s_cselect_b32 s81, s65, s37
	s_cselect_b32 s80, s64, s11
	v_lshl_add_u64 v[162:163], s[68:69], 0, v[158:159]
	s_add_i32 m0, s56, 0xc000
	ds_read_b128 v[184:187], v169
	ds_read_b128 v[188:191], v169 offset:1024
	ds_read_b128 v[192:195], v169 offset:2048
	ds_read_b128 v[196:199], v169 offset:3072
	ds_read_b128 v[200:203], v169 offset:4096
	ds_read_b128 v[204:207], v169 offset:5120
	ds_read_b128 v[208:211], v169 offset:6144
	ds_read_b128 v[212:215], v169 offset:7168
	global_load_lds_dwordx4 v[162:163], off
	v_lshl_add_u64 v[162:163], v[162:163], 0, s[12:13]
	s_add_i32 m0, s56, 0xe000
	s_nop 0
	global_load_lds_dwordx4 v[162:163], off
	s_waitcnt vmcnt(8)
	s_waitcnt lgkmcnt(0)
	s_barrier
	s_setprio 1
	s_waitcnt lgkmcnt(0)
	v_mfma_f32_16x16x32_bf16 v[138:141], v[114:117], v[184:187], v[138:141]
	v_mfma_f32_16x16x32_bf16 v[138:141], v[126:129], v[188:191], v[138:141]
	v_mfma_f32_16x16x32_bf16 v[110:113], v[126:129], v[196:199], v[110:113]
	v_mfma_f32_16x16x32_bf16 v[110:113], v[114:117], v[192:195], v[110:113]
	v_mfma_f32_16x16x32_bf16 v[94:97], v[114:117], v[200:203], v[94:97]
	v_mfma_f32_16x16x32_bf16 v[94:97], v[126:129], v[204:207], v[94:97]
	v_mfma_f32_16x16x32_bf16 v[78:81], v[126:129], v[212:215], v[78:81]
	v_mfma_f32_16x16x32_bf16 v[78:81], v[114:117], v[208:211], v[78:81]
	v_mfma_f32_16x16x32_bf16 v[74:77], v[130:133], v[208:211], v[74:77]
	v_mfma_f32_16x16x32_bf16 v[74:77], v[142:145], v[212:215], v[74:77]
	v_mfma_f32_16x16x32_bf16 v[90:93], v[142:145], v[204:207], v[90:93]
	v_mfma_f32_16x16x32_bf16 v[90:93], v[130:133], v[200:203], v[90:93]
	v_mfma_f32_16x16x32_bf16 v[106:109], v[130:133], v[192:195], v[106:109]
	v_mfma_f32_16x16x32_bf16 v[106:109], v[142:145], v[196:199], v[106:109]
	v_mfma_f32_16x16x32_bf16 v[134:137], v[142:145], v[188:191], v[134:137]
	v_mfma_f32_16x16x32_bf16 v[134:137], v[130:133], v[184:187], v[134:137]
	v_mfma_f32_16x16x32_bf16 v[122:125], v[146:149], v[184:187], v[122:125]
	v_mfma_f32_16x16x32_bf16 v[122:125], v[150:153], v[188:191], v[122:125]
	v_mfma_f32_16x16x32_bf16 v[102:105], v[150:153], v[196:199], v[102:105]
	v_mfma_f32_16x16x32_bf16 v[102:105], v[146:149], v[192:195], v[102:105]
	v_mfma_f32_16x16x32_bf16 v[86:89], v[146:149], v[200:203], v[86:89]
	v_mfma_f32_16x16x32_bf16 v[86:89], v[150:153], v[204:207], v[86:89]
	v_mfma_f32_16x16x32_bf16 v[70:73], v[150:153], v[212:215], v[70:73]
	v_mfma_f32_16x16x32_bf16 v[70:73], v[146:149], v[208:211], v[70:73]
	v_mfma_f32_16x16x32_bf16 v[66:69], v[174:177], v[208:211], v[66:69]
	v_mfma_f32_16x16x32_bf16 v[66:69], v[178:181], v[212:215], v[66:69]
	v_mfma_f32_16x16x32_bf16 v[82:85], v[178:181], v[204:207], v[82:85]
	v_mfma_f32_16x16x32_bf16 v[82:85], v[174:177], v[200:203], v[82:85]
	s_barrier
	s_setprio 2
	v_mfma_f32_16x16x32_bf16 v[98:101], v[174:177], v[192:195], v[98:101]
	v_mfma_f32_16x16x32_bf16 v[98:101], v[178:181], v[196:199], v[98:101]
	v_mfma_f32_16x16x32_bf16 v[118:121], v[178:181], v[188:191], v[118:121]
	v_mfma_f32_16x16x32_bf16 v[118:121], v[174:177], v[184:187], v[118:121]
	s_setprio 3
	s_add_i32 s39, s74, s55
	v_lshl_add_u64 v[162:163], s[80:81], 0, v[154:155]
	s_mov_b32 m0, s39
	ds_read_b128 v[184:187], v169 offset:16384
	ds_read_b128 v[188:191], v169 offset:17408
	ds_read_b128 v[192:195], v169 offset:18432
	ds_read_b128 v[196:199], v169 offset:19456
	ds_read_b128 v[200:203], v169 offset:20480
	ds_read_b128 v[204:207], v169 offset:21504
	ds_read_b128 v[208:211], v169 offset:22528
	ds_read_b128 v[212:215], v169 offset:23552
	global_load_lds_dwordx4 v[162:163], off
	v_lshl_add_u64 v[216:217], v[162:163], 0, s[12:13]
	s_add_i32 m0, s39, 0x2000
	s_add_i32 s39, s75, s55
	global_load_lds_dwordx4 v[216:217], off
	v_lshl_add_u64 v[216:217], v[162:163], 0, s[14:15]
	s_mov_b32 m0, s39
	s_nop 0
	global_load_lds_dwordx4 v[216:217], off
	v_lshl_add_u64 v[216:217], v[162:163], 0, s[16:17]
	s_add_i32 m0, s39, 0x2000
	s_nop 0
	global_load_lds_dwordx4 v[216:217], off
	v_lshl_add_u64 v[216:217], s[70:71], 0, v[154:155]
	s_mov_b32 m0, s56
	v_lshl_add_u64 v[218:219], v[216:217], 0, s[12:13]
	global_load_lds_dwordx4 v[216:217], off
	s_mov_b32 m0, s57
	s_nop 0
	global_load_lds_dwordx4 v[218:219], off
	s_waitcnt vmcnt(8)
	s_waitcnt lgkmcnt(0)
	s_barrier
; #define PG8_STAGE(bufoff, gbase, voff) do { if constexpr (!pg8_noload<Epi>::value) { _Pragma("unroll") for (int _i = 0; _i < 2; ++_i) \
;         __builtin_amdgcn_global_load_lds((const unsigned*)((const char*)(gbase) + (size_t)_i * pstep + (voff)[0]), (PG8_LAS unsigned*)(lds + (bufoff) + ldsw + _i * 8192), 16, 0, 0); } } while (0)
; #define PG8_LDA(dst, b, h) do { _Pragma("unroll") for (int m = 0; m < 4; ++m) _Pragma("unroll") for (int k = 0; k < 2; ++k) dst[m][k] = *(const PG8_LAS bf16x8*)(lds + PG8_SA(b, h) + aoff + m * 2048 + k * 1024); } while (0)
; #define PG8_LDB(dst, b, h) do { _Pragma("unroll") for (int n = 0; n < 2; ++n) _Pragma("unroll") for (int k = 0; k < 2; ++k) dst[n][k] = *(const PG8_LAS bf16x8*)(lds + PG8_SB(b, h) + boff + n * 2048 + k * 1024); } while (0)
; #define PG8_MMA(ai, bj, At, Bt) do { __builtin_amdgcn_s_setprio(1); _Pragma("unroll") for (int m = 0; m < 4; ++m) _Pragma("unroll") for (int n = 0; n < 2; ++n) _Pragma("unroll") for (int k = 0; k < 2; ++k) \
;         acc[ai][bj][m][n] = __builtin_amdgcn_mfma_f32_16x16x32_bf16(Bt[n][k], At[m][k], acc[ai][bj][m][n], 0, 0, 0); __builtin_amdgcn_s_setprio(0); } while (0)
; #define PG8_WAIT_V(n) asm volatile("s_waitcnt vmcnt(" #n ")" ::: "memory")
; #define PG8_WAIT_L(n) asm volatile("s_waitcnt lgkmcnt(" #n ")" ::: "memory")
; #define PG8_BAR __builtin_amdgcn_s_barrier()
; #define PG8_SCHED __builtin_amdgcn_sched_barrier(0)
; template <class Epi, class Sched, bool ALIGN_EPI = false, bool SP2 = false, bool ABLK = false>
; __device__ __forceinline__ void gemm_phase(PG8_LAS unsigned char* lds, const Gemm g, const Sched& S, const Epi& E) {
;     ...
;             PG8_WAIT_V(8); PG8_WAIT_L(0); PG8_BAR; PG8_MMA(1, 0, At, B0); PG8_MMA(1, 1, At, B1); PG8_BAR; PG8_SCHED;
;             PG8_LDB(B0, 1, 0); PG8_LDB(B1, 1, 1); PG8_SCHED; PG8_LDA(At, 1, 0); PG8_STAGE(PG8_SA(0, 1), a2 + hstep, voffA);
;             PG8_WAIT_V(8); PG8_WAIT_L(0); PG8_BAR; PG8_MMA(0, 0, At, B0); PG8_MMA(0, 1, At, B1); PG8_BAR; PG8_SCHED;
	s_setprio 1
	s_waitcnt lgkmcnt(0)
	v_mfma_f32_16x16x32_bf16 v[62:65], v[114:117], v[184:187], v[62:65]
	v_mfma_f32_16x16x32_bf16 v[62:65], v[126:129], v[188:191], v[62:65]
	v_mfma_f32_16x16x32_bf16 v[46:49], v[126:129], v[196:199], v[46:49]
	v_mfma_f32_16x16x32_bf16 v[46:49], v[114:117], v[192:195], v[46:49]
	v_mfma_f32_16x16x32_bf16 v[30:33], v[114:117], v[200:203], v[30:33]
	v_mfma_f32_16x16x32_bf16 v[30:33], v[126:129], v[204:207], v[30:33]
	v_mfma_f32_16x16x32_bf16 v[14:17], v[126:129], v[212:215], v[14:17]
	v_mfma_f32_16x16x32_bf16 v[14:17], v[114:117], v[208:211], v[14:17]
	v_mfma_f32_16x16x32_bf16 v[10:13], v[130:133], v[208:211], v[10:13]
	v_mfma_f32_16x16x32_bf16 v[10:13], v[142:145], v[212:215], v[10:13]
	v_mfma_f32_16x16x32_bf16 v[26:29], v[142:145], v[204:207], v[26:29]
	v_mfma_f32_16x16x32_bf16 v[26:29], v[130:133], v[200:203], v[26:29]
	v_mfma_f32_16x16x32_bf16 v[42:45], v[130:133], v[192:195], v[42:45]
	v_mfma_f32_16x16x32_bf16 v[42:45], v[142:145], v[196:199], v[42:45]
	v_mfma_f32_16x16x32_bf16 v[58:61], v[142:145], v[188:191], v[58:61]
	v_mfma_f32_16x16x32_bf16 v[58:61], v[130:133], v[184:187], v[58:61]
	v_mfma_f32_16x16x32_bf16 v[54:57], v[146:149], v[184:187], v[54:57]
	v_mfma_f32_16x16x32_bf16 v[54:57], v[150:153], v[188:191], v[54:57]
	v_mfma_f32_16x16x32_bf16 v[38:41], v[150:153], v[196:199], v[38:41]
	v_mfma_f32_16x16x32_bf16 v[38:41], v[146:149], v[192:195], v[38:41]
	v_mfma_f32_16x16x32_bf16 v[22:25], v[146:149], v[200:203], v[22:25]
	v_mfma_f32_16x16x32_bf16 v[22:25], v[150:153], v[204:207], v[22:25]
	v_mfma_f32_16x16x32_bf16 v[6:9], v[150:153], v[212:215], v[6:9]
	v_mfma_f32_16x16x32_bf16 v[6:9], v[146:149], v[208:211], v[6:9]
	v_mfma_f32_16x16x32_bf16 v[2:5], v[174:177], v[208:211], v[2:5]
	v_mfma_f32_16x16x32_bf16 v[2:5], v[178:181], v[212:215], v[2:5]
	v_mfma_f32_16x16x32_bf16 v[18:21], v[178:181], v[204:207], v[18:21]
	v_mfma_f32_16x16x32_bf16 v[18:21], v[174:177], v[200:203], v[18:21]
	s_barrier
	s_setprio 2
	v_mfma_f32_16x16x32_bf16 v[34:37], v[174:177], v[192:195], v[34:37]
	v_mfma_f32_16x16x32_bf16 v[34:37], v[178:181], v[196:199], v[34:37]
	v_mfma_f32_16x16x32_bf16 v[50:53], v[178:181], v[188:191], v[50:53]
	v_mfma_f32_16x16x32_bf16 v[50:53], v[174:177], v[184:187], v[50:53]
	s_setprio 3
	s_add_i32 s39, 0, 0x18000
	s_add_i32 s70, 0, 0x1c000
	v_add_u32_e32 v142, s39, v1
	v_add_u32_e32 v173, s70, v1
	ds_read_b128 v[114:117], v142
	ds_read_b128 v[126:129], v142 offset:1024
	ds_read_b128 v[130:133], v142 offset:2048
	ds_read_b128 v[142:145], v142 offset:3072
	ds_read_b128 v[146:149], v173
	ds_read_b128 v[150:153], v173 offset:1024
	ds_read_b128 v[174:177], v173 offset:2048
	ds_read_b128 v[178:181], v173 offset:3072
	s_mov_b32 m0, s58
	v_lshl_add_u64 v[218:219], v[216:217], 0, s[14:15]
	ds_read_b128 v[184:187], v169 offset:32768
	ds_read_b128 v[188:191], v169 offset:33792
	ds_read_b128 v[192:195], v169 offset:34816
	ds_read_b128 v[196:199], v169 offset:35840
	ds_read_b128 v[200:203], v169 offset:36864
	ds_read_b128 v[204:207], v169 offset:37888
	ds_read_b128 v[208:211], v169 offset:38912
	ds_read_b128 v[212:215], v169 offset:39936
	global_load_lds_dwordx4 v[218:219], off
	v_lshl_add_u64 v[218:219], v[216:217], 0, s[16:17]
	s_mov_b32 m0, s59
	s_nop 0
	global_load_lds_dwordx4 v[218:219], off
	s_waitcnt vmcnt(8)
	s_waitcnt lgkmcnt(0)
	s_barrier
	s_setprio 1
	s_waitcnt lgkmcnt(0)
	v_mfma_f32_16x16x32_bf16 v[138:141], v[114:117], v[184:187], v[138:141]
	v_mfma_f32_16x16x32_bf16 v[138:141], v[126:129], v[188:191], v[138:141]
	v_mfma_f32_16x16x32_bf16 v[110:113], v[126:129], v[196:199], v[110:113]
	v_mfma_f32_16x16x32_bf16 v[110:113], v[114:117], v[192:195], v[110:113]
	v_mfma_f32_16x16x32_bf16 v[94:97], v[114:117], v[200:203], v[94:97]
	v_mfma_f32_16x16x32_bf16 v[94:97], v[126:129], v[204:207], v[94:97]
	v_mfma_f32_16x16x32_bf16 v[78:81], v[126:129], v[212:215], v[78:81]
	v_mfma_f32_16x16x32_bf16 v[78:81], v[114:117], v[208:211], v[78:81]
	v_mfma_f32_16x16x32_bf16 v[74:77], v[130:133], v[208:211], v[74:77]
	v_mfma_f32_16x16x32_bf16 v[74:77], v[142:145], v[212:215], v[74:77]
	v_mfma_f32_16x16x32_bf16 v[90:93], v[142:145], v[204:207], v[90:93]
	v_mfma_f32_16x16x32_bf16 v[90:93], v[130:133], v[200:203], v[90:93]
	v_mfma_f32_16x16x32_bf16 v[106:109], v[130:133], v[192:195], v[106:109]
	v_mfma_f32_16x16x32_bf16 v[106:109], v[142:145], v[196:199], v[106:109]
	v_mfma_f32_16x16x32_bf16 v[134:137], v[142:145], v[188:191], v[134:137]
	v_mfma_f32_16x16x32_bf16 v[134:137], v[130:133], v[184:187], v[134:137]
	v_mfma_f32_16x16x32_bf16 v[122:125], v[146:149], v[184:187], v[122:125]
	v_mfma_f32_16x16x32_bf16 v[122:125], v[150:153], v[188:191], v[122:125]
	v_mfma_f32_16x16x32_bf16 v[102:105], v[150:153], v[196:199], v[102:105]
	v_mfma_f32_16x16x32_bf16 v[102:105], v[146:149], v[192:195], v[102:105]
	v_mfma_f32_16x16x32_bf16 v[86:89], v[146:149], v[200:203], v[86:89]
	v_mfma_f32_16x16x32_bf16 v[86:89], v[150:153], v[204:207], v[86:89]
	v_mfma_f32_16x16x32_bf16 v[70:73], v[150:153], v[212:215], v[70:73]
	v_mfma_f32_16x16x32_bf16 v[70:73], v[146:149], v[208:211], v[70:73]
	v_mfma_f32_16x16x32_bf16 v[66:69], v[174:177], v[208:211], v[66:69]
	v_mfma_f32_16x16x32_bf16 v[66:69], v[178:181], v[212:215], v[66:69]
	v_mfma_f32_16x16x32_bf16 v[82:85], v[178:181], v[204:207], v[82:85]
	v_mfma_f32_16x16x32_bf16 v[82:85], v[174:177], v[200:203], v[82:85]
	s_barrier
; #define PG8_STAGE(bufoff, gbase, voff) do { if constexpr (!pg8_noload<Epi>::value) { _Pragma("unroll") for (int _i = 0; _i < 2; ++_i) \
;         __builtin_amdgcn_global_load_lds((const unsigned*)((const char*)(gbase) + (size_t)_i * pstep + (voff)[0]), (PG8_LAS unsigned*)(lds + (bufoff) + ldsw + _i * 8192), 16, 0, 0); } } while (0)
; #define PG8_LDA(dst, b, h) do { _Pragma("unroll") for (int m = 0; m < 4; ++m) _Pragma("unroll") for (int k = 0; k < 2; ++k) dst[m][k] = *(const PG8_LAS bf16x8*)(lds + PG8_SA(b, h) + aoff + m * 2048 + k * 1024); } while (0)
; #define PG8_MMA(ai, bj, At, Bt) do { __builtin_amdgcn_s_setprio(1); _Pragma("unroll") for (int m = 0; m < 4; ++m) _Pragma("unroll") for (int n = 0; n < 2; ++n) _Pragma("unroll") for (int k = 0; k < 2; ++k) \
;         acc[ai][bj][m][n] = __builtin_amdgcn_mfma_f32_16x16x32_bf16(Bt[n][k], At[m][k], acc[ai][bj][m][n], 0, 0, 0); __builtin_amdgcn_s_setprio(0); } while (0)
; #define PG8_WAIT_V(n) asm volatile("s_waitcnt vmcnt(" #n ")" ::: "memory")
; #define PG8_WAIT_L(n) asm volatile("s_waitcnt lgkmcnt(" #n ")" ::: "memory")
; #define PG8_BAR __builtin_amdgcn_s_barrier()
; #define PG8_SCHED __builtin_amdgcn_sched_barrier(0)
; template <class Epi, class Sched, bool ALIGN_EPI = false, bool SP2 = false, bool ABLK = false>
; __device__ __forceinline__ void gemm_phase(PG8_LAS unsigned char* lds, const Gemm g, const Sched& S, const Epi& E) {
;     ...
;             PG8_WAIT_V(8); PG8_WAIT_L(0); PG8_BAR; PG8_MMA(0, 0, At, B0); PG8_MMA(0, 1, At, B1); PG8_BAR; PG8_SCHED;
;             PG8_LDA(At, 1, 1); PG8_STAGE(PG8_SB(1, 0), b3, voffB); PG8_STAGE(PG8_SB(1, 1), b3 + hstep, voffB); PG8_STAGE(PG8_SA(1, 0), a3, voffA);
;             PG8_WAIT_V(8); PG8_WAIT_L(0); PG8_BAR; PG8_MMA(1, 0, At, B0); PG8_MMA(1, 1, At, B1); PG8_BAR; PG8_SCHED;
	s_setprio 2
	v_mfma_f32_16x16x32_bf16 v[98:101], v[174:177], v[192:195], v[98:101]
	v_mfma_f32_16x16x32_bf16 v[98:101], v[178:181], v[196:199], v[98:101]
	v_mfma_f32_16x16x32_bf16 v[118:121], v[178:181], v[188:191], v[118:121]
	v_mfma_f32_16x16x32_bf16 v[118:121], v[174:177], v[184:187], v[118:121]
	s_setprio 3
	s_add_i32 s39, s39, s55
	v_lshl_add_u64 v[218:219], v[162:163], 0, s[24:25]
	s_mov_b32 m0, s39
	ds_read_b128 v[184:187], v169 offset:49152
	ds_read_b128 v[188:191], v169 offset:50176
	ds_read_b128 v[192:195], v169 offset:51200
	ds_read_b128 v[196:199], v169 offset:52224
	ds_read_b128 v[200:203], v169 offset:53248
	ds_read_b128 v[204:207], v169 offset:54272
	ds_read_b128 v[208:211], v169 offset:55296
	ds_read_b128 v[212:215], v169 offset:56320
	global_load_lds_dwordx4 v[218:219], off
	v_lshl_add_u64 v[218:219], v[162:163], 0, s[26:27]
	s_add_i32 m0, s39, 0x2000
	s_add_i32 s39, s70, s55
	global_load_lds_dwordx4 v[218:219], off
	v_lshl_add_u64 v[218:219], v[162:163], 0, s[28:29]
	s_mov_b32 m0, s39
	v_lshl_add_u64 v[162:163], v[162:163], 0, s[30:31]
	global_load_lds_dwordx4 v[218:219], off
	s_add_i32 m0, s39, 0x2000
	s_nop 0
	global_load_lds_dwordx4 v[162:163], off
	v_lshl_add_u64 v[162:163], v[216:217], 0, s[24:25]
	s_mov_b32 m0, s62
	s_nop 0
	global_load_lds_dwordx4 v[162:163], off
	v_lshl_add_u64 v[162:163], v[216:217], 0, s[26:27]
	s_mov_b32 m0, s63
	s_nop 0
	global_load_lds_dwordx4 v[162:163], off
	s_waitcnt vmcnt(8)
	s_waitcnt lgkmcnt(0)
	s_barrier
	s_setprio 1
	s_waitcnt lgkmcnt(0)
	v_mfma_f32_16x16x32_bf16 v[62:65], v[114:117], v[184:187], v[62:65]
	v_mfma_f32_16x16x32_bf16 v[62:65], v[126:129], v[188:191], v[62:65]
	v_mfma_f32_16x16x32_bf16 v[46:49], v[126:129], v[196:199], v[46:49]
	v_mfma_f32_16x16x32_bf16 v[46:49], v[114:117], v[192:195], v[46:49]
	v_mfma_f32_16x16x32_bf16 v[30:33], v[114:117], v[200:203], v[30:33]
	v_mfma_f32_16x16x32_bf16 v[30:33], v[126:129], v[204:207], v[30:33]
	v_mfma_f32_16x16x32_bf16 v[14:17], v[126:129], v[212:215], v[14:17]
	v_mfma_f32_16x16x32_bf16 v[14:17], v[114:117], v[208:211], v[14:17]
	v_mfma_f32_16x16x32_bf16 v[10:13], v[130:133], v[208:211], v[10:13]
	v_mfma_f32_16x16x32_bf16 v[10:13], v[142:145], v[212:215], v[10:13]
	v_mfma_f32_16x16x32_bf16 v[26:29], v[142:145], v[204:207], v[26:29]
	v_mfma_f32_16x16x32_bf16 v[26:29], v[130:133], v[200:203], v[26:29]
	v_mfma_f32_16x16x32_bf16 v[42:45], v[130:133], v[192:195], v[42:45]
	v_mfma_f32_16x16x32_bf16 v[42:45], v[142:145], v[196:199], v[42:45]
	v_mfma_f32_16x16x32_bf16 v[58:61], v[142:145], v[188:191], v[58:61]
	v_mfma_f32_16x16x32_bf16 v[58:61], v[130:133], v[184:187], v[58:61]
	v_mfma_f32_16x16x32_bf16 v[54:57], v[146:149], v[184:187], v[54:57]
	v_mfma_f32_16x16x32_bf16 v[54:57], v[150:153], v[188:191], v[54:57]
	v_mfma_f32_16x16x32_bf16 v[38:41], v[150:153], v[196:199], v[38:41]
	v_mfma_f32_16x16x32_bf16 v[38:41], v[146:149], v[192:195], v[38:41]
	v_mfma_f32_16x16x32_bf16 v[22:25], v[146:149], v[200:203], v[22:25]
	v_mfma_f32_16x16x32_bf16 v[22:25], v[150:153], v[204:207], v[22:25]
	v_mfma_f32_16x16x32_bf16 v[6:9], v[150:153], v[212:215], v[6:9]
	v_mfma_f32_16x16x32_bf16 v[6:9], v[146:149], v[208:211], v[6:9]
	v_mfma_f32_16x16x32_bf16 v[2:5], v[174:177], v[208:211], v[2:5]
	v_mfma_f32_16x16x32_bf16 v[2:5], v[178:181], v[212:215], v[2:5]
	v_mfma_f32_16x16x32_bf16 v[18:21], v[178:181], v[204:207], v[18:21]
	v_mfma_f32_16x16x32_bf16 v[18:21], v[174:177], v[200:203], v[18:21]
	s_barrier
	s_setprio 2
	v_mfma_f32_16x16x32_bf16 v[34:37], v[174:177], v[192:195], v[34:37]
	v_mfma_f32_16x16x32_bf16 v[34:37], v[178:181], v[196:199], v[34:37]
	v_mfma_f32_16x16x32_bf16 v[50:53], v[178:181], v[188:191], v[50:53]
	v_mfma_f32_16x16x32_bf16 v[50:53], v[174:177], v[184:187], v[50:53]
	s_setprio 3
	s_add_u32 s68, s68, 0x1000
	s_addc_u32 s69, s69, 0
	s_add_u32 s11, s11, 0x1000
	s_addc_u32 s37, s37, 0
	s_cmp_ge_i32 s41, s79
	s_mov_b32 s39, s41
	s_cbranch_scc0 .LBB0_1533
	s_and_b64 vcc, exec, s[34:35]
	s_cbranch_vccnz .LBB0_1538
	s_lshl_b32 s11, s2, 8
	s_cmp_gt_i32 s2, 63
	s_mov_b64 s[68:69], -1
	s_cbranch_scc1 .LBB0_1539

; #define PG8_STAGE(bufoff, gbase, voff) do { if constexpr (!pg8_noload<Epi>::value) { _Pragma("unroll") for (int _i = 0; _i < 2; ++_i) \
;         __builtin_amdgcn_global_load_lds((const unsigned*)((const char*)(gbase) + (size_t)_i * pstep + (voff)[0]), (PG8_LAS unsigned*)(lds + (bufoff) + ldsw + _i * 8192), 16, 0, 0); } } while (0)
; #define PG8_LDA(dst, b, h) do { _Pragma("unroll") for (int m = 0; m < 4; ++m) _Pragma("unroll") for (int k = 0; k < 2; ++k) dst[m][k] = *(const PG8_LAS bf16x8*)(lds + PG8_SA(b, h) + aoff + m * 2048 + k * 1024); } while (0)
; #define PG8_LDB(dst, b, h) do { _Pragma("unroll") for (int n = 0; n < 2; ++n) _Pragma("unroll") for (int k = 0; k < 2; ++k) dst[n][k] = *(const PG8_LAS bf16x8*)(lds + PG8_SB(b, h) + boff + n * 2048 + k * 1024); } while (0)
; #define PG8_MMA(ai, bj, At, Bt) do { __builtin_amdgcn_s_setprio(1); _Pragma("unroll") for (int m = 0; m < 4; ++m) _Pragma("unroll") for (int n = 0; n < 2; ++n) _Pragma("unroll") for (int k = 0; k < 2; ++k) \
;         acc[ai][bj][m][n] = __builtin_amdgcn_mfma_f32_16x16x32_bf16(Bt[n][k], At[m][k], acc[ai][bj][m][n], 0, 0, 0); __builtin_amdgcn_s_setprio(0); } while (0)
; #define PG8_BAR __builtin_amdgcn_s_barrier()
; template <class Epi, class Sched, bool ALIGN_EPI = false, bool SP2 = false, bool ABLK = false>
; __device__ __forceinline__ void gemm_phase(PG8_LAS unsigned char* lds, const Gemm g, const Sched& S, const Epi& E) {
;     ...
;         for (int t = 0; t < nt; t += 2) {
;             const bool last = (t == nt - 2);
;             const char* a1 = cA + (size_t)(t + 1) * kstep;
;             const char* a2 = last ? nA : cA + (size_t)(t + 2) * kstep; const char* b2 = last ? nB : cB + (size_t)(t + 2) * kstepB;
;             const char* a3 = a2 + kstep; const char* b3 = b2 + kstepB;
;             if (last && has_next) S.a_ready(nxt);
;             if constexpr (SP2) {
;             PG8_LDB(B0, 0, 0); PG8_LDB(B1, 0, 1); PG8_SCHED; PG8_LDA(At, 0, 0); PG8_STAGE(PG8_SA(1, 1), a1 + hstep, voffA);
;             PG8_WAIT_V(8); PG8_WAIT_L(0); PG8_BAR; PG8_MMA(0, 0, At, B0); PG8_MMA(0, 1, At, B1); PG8_BAR; PG8_SCHED;
;             PG8_LDA(At, 0, 1); PG8_STAGE(PG8_SB(0, 0), b2, voffB); PG8_STAGE(PG8_SB(0, 1), b2 + hstep, voffB); PG8_STAGE(PG8_SA(0, 0), a2, voffA);
;             PG8_WAIT_V(8); PG8_WAIT_L(0); PG8_BAR; PG8_MMA(1, 0, At, B0); PG8_MMA(1, 1, At, B1); PG8_BAR; PG8_SCHED;
.LBB0_1657:
	s_or_b32 s26, s94, 1
	s_lshl_b64 s[82:83], s[26:27], 11
	s_add_u32 s88, s74, s82
	v_add_u32_e32 v140, s12, v173
	s_addc_u32 s89, s75, s83
	s_add_i32 s26, s94, 2
	ds_read_b128 v[130:133], v140
	ds_read_b128 v[134:137], v140 offset:1024
	ds_read_b128 v[154:157], v140 offset:2048
	ds_read_b128 v[158:161], v140 offset:3072
	v_add_u32_e32 v140, s13, v173
	s_lshl_b64 s[90:91], s[26:27], 11
	ds_read_b128 v[162:165], v140
	ds_read_b128 v[166:169], v140 offset:1024
	ds_read_b128 v[184:187], v140 offset:2048
	ds_read_b128 v[188:191], v140 offset:3072
	s_add_u32 s92, s74, s90
	s_addc_u32 s93, s75, s91
	s_and_b64 s[82:83], s[80:81], exec
	s_cselect_b32 s83, s93, s3
	s_cselect_b32 s82, s92, s25
	s_add_u32 s90, s76, s90
	s_addc_u32 s91, s77, s91
	s_and_b64 s[80:81], s[80:81], exec
	s_cselect_b32 s81, s91, s65
	s_cselect_b32 s80, s90, s67
	v_lshl_add_u64 v[170:171], s[88:89], 0, v[138:139]
	v_lshl_add_u64 v[224:225], v[170:171], 0, s[20:21]
	s_add_i32 m0, s56, 0xc000
	ds_read_b128 v[192:195], v178
	ds_read_b128 v[196:199], v178 offset:1024
	ds_read_b128 v[200:203], v178 offset:2048
	ds_read_b128 v[204:207], v178 offset:3072
	ds_read_b128 v[208:211], v178 offset:4096
	ds_read_b128 v[212:215], v178 offset:5120
	ds_read_b128 v[216:219], v178 offset:6144
	ds_read_b128 v[220:223], v178 offset:7168
	global_load_lds_dwordx4 v[224:225], off
	v_lshl_add_u64 v[170:171], v[170:171], 0, s[22:23]
	s_add_i32 m0, s56, 0xe000
	s_nop 0
	global_load_lds_dwordx4 v[170:171], off
	s_waitcnt vmcnt(8)
	s_waitcnt lgkmcnt(0)
	s_barrier
	s_setprio 1
	s_waitcnt lgkmcnt(0)
	v_mfma_f32_16x16x32_bf16 v[126:129], v[130:133], v[192:195], v[126:129]
	v_mfma_f32_16x16x32_bf16 v[126:129], v[134:137], v[196:199], v[126:129]
	v_mfma_f32_16x16x32_bf16 v[110:113], v[134:137], v[204:207], v[110:113]
	v_mfma_f32_16x16x32_bf16 v[110:113], v[130:133], v[200:203], v[110:113]
	v_mfma_f32_16x16x32_bf16 v[94:97], v[130:133], v[208:211], v[94:97]
	v_mfma_f32_16x16x32_bf16 v[94:97], v[134:137], v[212:215], v[94:97]
	v_mfma_f32_16x16x32_bf16 v[78:81], v[134:137], v[220:223], v[78:81]
	v_mfma_f32_16x16x32_bf16 v[78:81], v[130:133], v[216:219], v[78:81]
	v_mfma_f32_16x16x32_bf16 v[74:77], v[154:157], v[216:219], v[74:77]
	v_mfma_f32_16x16x32_bf16 v[74:77], v[158:161], v[220:223], v[74:77]
	v_mfma_f32_16x16x32_bf16 v[90:93], v[158:161], v[212:215], v[90:93]
	v_mfma_f32_16x16x32_bf16 v[90:93], v[154:157], v[208:211], v[90:93]
	v_mfma_f32_16x16x32_bf16 v[106:109], v[154:157], v[200:203], v[106:109]
	v_mfma_f32_16x16x32_bf16 v[106:109], v[158:161], v[204:207], v[106:109]
	v_mfma_f32_16x16x32_bf16 v[122:125], v[158:161], v[196:199], v[122:125]
	v_mfma_f32_16x16x32_bf16 v[122:125], v[154:157], v[192:195], v[122:125]
	v_mfma_f32_16x16x32_bf16 v[118:121], v[162:165], v[192:195], v[118:121]
	v_mfma_f32_16x16x32_bf16 v[118:121], v[166:169], v[196:199], v[118:121]
	v_mfma_f32_16x16x32_bf16 v[102:105], v[166:169], v[204:207], v[102:105]
	v_mfma_f32_16x16x32_bf16 v[102:105], v[162:165], v[200:203], v[102:105]
	v_mfma_f32_16x16x32_bf16 v[86:89], v[162:165], v[208:211], v[86:89]
	v_mfma_f32_16x16x32_bf16 v[86:89], v[166:169], v[212:215], v[86:89]
	v_mfma_f32_16x16x32_bf16 v[70:73], v[166:169], v[220:223], v[70:73]
	v_mfma_f32_16x16x32_bf16 v[70:73], v[162:165], v[216:219], v[70:73]
	v_mfma_f32_16x16x32_bf16 v[66:69], v[184:187], v[216:219], v[66:69]
	v_mfma_f32_16x16x32_bf16 v[66:69], v[188:191], v[220:223], v[66:69]
	v_mfma_f32_16x16x32_bf16 v[82:85], v[188:191], v[212:215], v[82:85]
	v_mfma_f32_16x16x32_bf16 v[82:85], v[184:187], v[208:211], v[82:85]
	s_barrier
	s_setprio 2
	v_mfma_f32_16x16x32_bf16 v[98:101], v[184:187], v[200:203], v[98:101]
	v_mfma_f32_16x16x32_bf16 v[98:101], v[188:191], v[204:207], v[98:101]
	v_mfma_f32_16x16x32_bf16 v[114:117], v[188:191], v[196:199], v[114:117]
	v_mfma_f32_16x16x32_bf16 v[114:117], v[184:187], v[192:195], v[114:117]
	s_setprio 3
	v_lshl_add_u64 v[170:171], s[80:81], 0, v[138:139]
	s_add_i32 s80, s12, s55
	s_mov_b32 m0, s80
	ds_read_b128 v[192:195], v178 offset:16384
	ds_read_b128 v[196:199], v178 offset:17408
	ds_read_b128 v[200:203], v178 offset:18432
	ds_read_b128 v[204:207], v178 offset:19456
	ds_read_b128 v[208:211], v178 offset:20480
	ds_read_b128 v[212:215], v178 offset:21504
	ds_read_b128 v[216:219], v178 offset:22528
	ds_read_b128 v[220:223], v178 offset:23552
	global_load_lds_dwordx4 v[170:171], off
	v_lshl_add_u64 v[224:225], v[170:171], 0, s[18:19]
	s_add_i32 m0, s80, 0x2000
	s_add_i32 s80, s13, s55
	global_load_lds_dwordx4 v[224:225], off
	v_lshl_add_u64 v[224:225], v[170:171], 0, s[20:21]
	s_mov_b32 m0, s80
	s_nop 0
	global_load_lds_dwordx4 v[224:225], off
	v_lshl_add_u64 v[224:225], v[170:171], 0, s[22:23]
	s_add_i32 m0, s80, 0x2000
	s_nop 0
	global_load_lds_dwordx4 v[224:225], off
	v_lshl_add_u64 v[224:225], s[82:83], 0, v[138:139]
	s_mov_b32 m0, s56
	v_lshl_add_u64 v[226:227], v[224:225], 0, s[18:19]
	global_load_lds_dwordx4 v[224:225], off
	s_mov_b32 m0, s57
	s_nop 0
	global_load_lds_dwordx4 v[226:227], off
	s_waitcnt vmcnt(8)
	s_waitcnt lgkmcnt(0)
	s_barrier
; #define PG8_STAGE(bufoff, gbase, voff) do { if constexpr (!pg8_noload<Epi>::value) { _Pragma("unroll") for (int _i = 0; _i < 2; ++_i) \
;         __builtin_amdgcn_global_load_lds((const unsigned*)((const char*)(gbase) + (size_t)_i * pstep + (voff)[0]), (PG8_LAS unsigned*)(lds + (bufoff) + ldsw + _i * 8192), 16, 0, 0); } } while (0)
; #define PG8_LDA(dst, b, h) do { _Pragma("unroll") for (int m = 0; m < 4; ++m) _Pragma("unroll") for (int k = 0; k < 2; ++k) dst[m][k] = *(const PG8_LAS bf16x8*)(lds + PG8_SA(b, h) + aoff + m * 2048 + k * 1024); } while (0)
; #define PG8_LDB(dst, b, h) do { _Pragma("unroll") for (int n = 0; n < 2; ++n) _Pragma("unroll") for (int k = 0; k < 2; ++k) dst[n][k] = *(const PG8_LAS bf16x8*)(lds + PG8_SB(b, h) + boff + n * 2048 + k * 1024); } while (0)
; #define PG8_MMA(ai, bj, At, Bt) do { __builtin_amdgcn_s_setprio(1); _Pragma("unroll") for (int m = 0; m < 4; ++m) _Pragma("unroll") for (int n = 0; n < 2; ++n) _Pragma("unroll") for (int k = 0; k < 2; ++k) \
;         acc[ai][bj][m][n] = __builtin_amdgcn_mfma_f32_16x16x32_bf16(Bt[n][k], At[m][k], acc[ai][bj][m][n], 0, 0, 0); __builtin_amdgcn_s_setprio(0); } while (0)
; #define PG8_WAIT_V(n) asm volatile("s_waitcnt vmcnt(" #n ")" ::: "memory")
; #define PG8_WAIT_L(n) asm volatile("s_waitcnt lgkmcnt(" #n ")" ::: "memory")
; #define PG8_BAR __builtin_amdgcn_s_barrier()
; #define PG8_SCHED __builtin_amdgcn_sched_barrier(0)
; template <class Epi, class Sched, bool ALIGN_EPI = false, bool SP2 = false, bool ABLK = false>
; __device__ __forceinline__ void gemm_phase(PG8_LAS unsigned char* lds, const Gemm g, const Sched& S, const Epi& E) {
;     ...
;             PG8_WAIT_V(8); PG8_WAIT_L(0); PG8_BAR; PG8_MMA(1, 0, At, B0); PG8_MMA(1, 1, At, B1); PG8_BAR; PG8_SCHED;
;             PG8_LDB(B0, 1, 0); PG8_LDB(B1, 1, 1); PG8_SCHED; PG8_LDA(At, 1, 0); PG8_STAGE(PG8_SA(0, 1), a2 + hstep, voffA);
;             PG8_WAIT_V(8); PG8_WAIT_L(0); PG8_BAR; PG8_MMA(0, 0, At, B0); PG8_MMA(0, 1, At, B1); PG8_BAR; PG8_SCHED;
	s_setprio 1
	s_waitcnt lgkmcnt(0)
	v_mfma_f32_16x16x32_bf16 v[62:65], v[130:133], v[192:195], v[62:65]
	v_mfma_f32_16x16x32_bf16 v[62:65], v[134:137], v[196:199], v[62:65]
	v_mfma_f32_16x16x32_bf16 v[46:49], v[134:137], v[204:207], v[46:49]
	v_mfma_f32_16x16x32_bf16 v[46:49], v[130:133], v[200:203], v[46:49]
	v_mfma_f32_16x16x32_bf16 v[30:33], v[130:133], v[208:211], v[30:33]
	v_mfma_f32_16x16x32_bf16 v[30:33], v[134:137], v[212:215], v[30:33]
	v_mfma_f32_16x16x32_bf16 v[14:17], v[134:137], v[220:223], v[14:17]
	v_mfma_f32_16x16x32_bf16 v[14:17], v[130:133], v[216:219], v[14:17]
	v_mfma_f32_16x16x32_bf16 v[10:13], v[154:157], v[216:219], v[10:13]
	v_mfma_f32_16x16x32_bf16 v[10:13], v[158:161], v[220:223], v[10:13]
	v_mfma_f32_16x16x32_bf16 v[26:29], v[158:161], v[212:215], v[26:29]
	v_mfma_f32_16x16x32_bf16 v[26:29], v[154:157], v[208:211], v[26:29]
	v_mfma_f32_16x16x32_bf16 v[42:45], v[154:157], v[200:203], v[42:45]
	v_mfma_f32_16x16x32_bf16 v[42:45], v[158:161], v[204:207], v[42:45]
	v_mfma_f32_16x16x32_bf16 v[58:61], v[158:161], v[196:199], v[58:61]
	v_mfma_f32_16x16x32_bf16 v[58:61], v[154:157], v[192:195], v[58:61]
	v_mfma_f32_16x16x32_bf16 v[54:57], v[162:165], v[192:195], v[54:57]
	v_mfma_f32_16x16x32_bf16 v[54:57], v[166:169], v[196:199], v[54:57]
	v_mfma_f32_16x16x32_bf16 v[38:41], v[166:169], v[204:207], v[38:41]
	v_mfma_f32_16x16x32_bf16 v[38:41], v[162:165], v[200:203], v[38:41]
	v_mfma_f32_16x16x32_bf16 v[22:25], v[162:165], v[208:211], v[22:25]
	v_mfma_f32_16x16x32_bf16 v[22:25], v[166:169], v[212:215], v[22:25]
	v_mfma_f32_16x16x32_bf16 v[6:9], v[166:169], v[220:223], v[6:9]
	v_mfma_f32_16x16x32_bf16 v[6:9], v[162:165], v[216:219], v[6:9]
	v_mfma_f32_16x16x32_bf16 v[2:5], v[184:187], v[216:219], v[2:5]
	v_mfma_f32_16x16x32_bf16 v[2:5], v[188:191], v[220:223], v[2:5]
	v_mfma_f32_16x16x32_bf16 v[18:21], v[188:191], v[212:215], v[18:21]
	v_mfma_f32_16x16x32_bf16 v[18:21], v[184:187], v[208:211], v[18:21]
	s_barrier
	s_setprio 2
	v_mfma_f32_16x16x32_bf16 v[34:37], v[184:187], v[200:203], v[34:37]
	v_mfma_f32_16x16x32_bf16 v[34:37], v[188:191], v[204:207], v[34:37]
	v_mfma_f32_16x16x32_bf16 v[50:53], v[188:191], v[196:199], v[50:53]
	v_mfma_f32_16x16x32_bf16 v[50:53], v[184:187], v[192:195], v[50:53]
	s_setprio 3
	s_add_i32 s80, 0, 0x18000
	v_add_u32_e32 v140, s80, v173
	s_add_i32 s81, 0, 0x1c000
	ds_read_b128 v[130:133], v140
	ds_read_b128 v[134:137], v140 offset:1024
	ds_read_b128 v[154:157], v140 offset:2048
	ds_read_b128 v[158:161], v140 offset:3072
	v_add_u32_e32 v140, s81, v173
	ds_read_b128 v[162:165], v140
	ds_read_b128 v[166:169], v140 offset:1024
	ds_read_b128 v[184:187], v140 offset:2048
	ds_read_b128 v[188:191], v140 offset:3072
	s_mov_b32 m0, s58
	v_lshl_add_u64 v[226:227], v[224:225], 0, s[20:21]
	ds_read_b128 v[192:195], v178 offset:32768
	ds_read_b128 v[196:199], v178 offset:33792
	ds_read_b128 v[200:203], v178 offset:34816
	ds_read_b128 v[204:207], v178 offset:35840
	ds_read_b128 v[208:211], v178 offset:36864
	ds_read_b128 v[212:215], v178 offset:37888
	ds_read_b128 v[216:219], v178 offset:38912
	ds_read_b128 v[220:223], v178 offset:39936
	global_load_lds_dwordx4 v[226:227], off
	v_lshl_add_u64 v[226:227], v[224:225], 0, s[22:23]
	s_mov_b32 m0, s59
	s_nop 0
	global_load_lds_dwordx4 v[226:227], off
	s_waitcnt vmcnt(8)
	s_waitcnt lgkmcnt(0)
	s_barrier
	s_setprio 1
	s_waitcnt lgkmcnt(0)
	v_mfma_f32_16x16x32_bf16 v[126:129], v[130:133], v[192:195], v[126:129]
	v_mfma_f32_16x16x32_bf16 v[126:129], v[134:137], v[196:199], v[126:129]
	v_mfma_f32_16x16x32_bf16 v[110:113], v[134:137], v[204:207], v[110:113]
	v_mfma_f32_16x16x32_bf16 v[110:113], v[130:133], v[200:203], v[110:113]
	v_mfma_f32_16x16x32_bf16 v[94:97], v[130:133], v[208:211], v[94:97]
	v_mfma_f32_16x16x32_bf16 v[94:97], v[134:137], v[212:215], v[94:97]
	v_mfma_f32_16x16x32_bf16 v[78:81], v[134:137], v[220:223], v[78:81]
	v_mfma_f32_16x16x32_bf16 v[78:81], v[130:133], v[216:219], v[78:81]
	v_mfma_f32_16x16x32_bf16 v[74:77], v[154:157], v[216:219], v[74:77]
	v_mfma_f32_16x16x32_bf16 v[74:77], v[158:161], v[220:223], v[74:77]
	v_mfma_f32_16x16x32_bf16 v[90:93], v[158:161], v[212:215], v[90:93]
	v_mfma_f32_16x16x32_bf16 v[90:93], v[154:157], v[208:211], v[90:93]
	v_mfma_f32_16x16x32_bf16 v[106:109], v[154:157], v[200:203], v[106:109]
	v_mfma_f32_16x16x32_bf16 v[106:109], v[158:161], v[204:207], v[106:109]
	v_mfma_f32_16x16x32_bf16 v[122:125], v[158:161], v[196:199], v[122:125]
	v_mfma_f32_16x16x32_bf16 v[122:125], v[154:157], v[192:195], v[122:125]
	v_mfma_f32_16x16x32_bf16 v[118:121], v[162:165], v[192:195], v[118:121]
	v_mfma_f32_16x16x32_bf16 v[118:121], v[166:169], v[196:199], v[118:121]
	v_mfma_f32_16x16x32_bf16 v[102:105], v[166:169], v[204:207], v[102:105]
	v_mfma_f32_16x16x32_bf16 v[102:105], v[162:165], v[200:203], v[102:105]
	v_mfma_f32_16x16x32_bf16 v[86:89], v[162:165], v[208:211], v[86:89]
	v_mfma_f32_16x16x32_bf16 v[86:89], v[166:169], v[212:215], v[86:89]
	v_mfma_f32_16x16x32_bf16 v[70:73], v[166:169], v[220:223], v[70:73]
	v_mfma_f32_16x16x32_bf16 v[70:73], v[162:165], v[216:219], v[70:73]
	v_mfma_f32_16x16x32_bf16 v[66:69], v[184:187], v[216:219], v[66:69]
	v_mfma_f32_16x16x32_bf16 v[66:69], v[188:191], v[220:223], v[66:69]
	v_mfma_f32_16x16x32_bf16 v[82:85], v[188:191], v[212:215], v[82:85]
	v_mfma_f32_16x16x32_bf16 v[82:85], v[184:187], v[208:211], v[82:85]
	s_barrier
; #define PG8_STAGE(bufoff, gbase, voff) do { if constexpr (!pg8_noload<Epi>::value) { _Pragma("unroll") for (int _i = 0; _i < 2; ++_i) \
;         __builtin_amdgcn_global_load_lds((const unsigned*)((const char*)(gbase) + (size_t)_i * pstep + (voff)[0]), (PG8_LAS unsigned*)(lds + (bufoff) + ldsw + _i * 8192), 16, 0, 0); } } while (0)
; #define PG8_LDA(dst, b, h) do { _Pragma("unroll") for (int m = 0; m < 4; ++m) _Pragma("unroll") for (int k = 0; k < 2; ++k) dst[m][k] = *(const PG8_LAS bf16x8*)(lds + PG8_SA(b, h) + aoff + m * 2048 + k * 1024); } while (0)
; #define PG8_MMA(ai, bj, At, Bt) do { __builtin_amdgcn_s_setprio(1); _Pragma("unroll") for (int m = 0; m < 4; ++m) _Pragma("unroll") for (int n = 0; n < 2; ++n) _Pragma("unroll") for (int k = 0; k < 2; ++k) \
;         acc[ai][bj][m][n] = __builtin_amdgcn_mfma_f32_16x16x32_bf16(Bt[n][k], At[m][k], acc[ai][bj][m][n], 0, 0, 0); __builtin_amdgcn_s_setprio(0); } while (0)
; #define PG8_WAIT_V(n) asm volatile("s_waitcnt vmcnt(" #n ")" ::: "memory")
; #define PG8_WAIT_L(n) asm volatile("s_waitcnt lgkmcnt(" #n ")" ::: "memory")
; #define PG8_BAR __builtin_amdgcn_s_barrier()
; #define PG8_SCHED __builtin_amdgcn_sched_barrier(0)
; template <class Epi, class Sched, bool ALIGN_EPI = false, bool SP2 = false, bool ABLK = false>
; __device__ __forceinline__ void gemm_phase(PG8_LAS unsigned char* lds, const Gemm g, const Sched& S, const Epi& E) {
;     ...
;             PG8_WAIT_V(8); PG8_WAIT_L(0); PG8_BAR; PG8_MMA(0, 0, At, B0); PG8_MMA(0, 1, At, B1); PG8_BAR; PG8_SCHED;
;             PG8_LDA(At, 1, 1); PG8_STAGE(PG8_SB(1, 0), b3, voffB); PG8_STAGE(PG8_SB(1, 1), b3 + hstep, voffB); PG8_STAGE(PG8_SA(1, 0), a3, voffA);
;             PG8_WAIT_V(8); PG8_WAIT_L(0); PG8_BAR; PG8_MMA(1, 0, At, B0); PG8_MMA(1, 1, At, B1); PG8_BAR; PG8_SCHED;
	s_setprio 2
	v_mfma_f32_16x16x32_bf16 v[98:101], v[184:187], v[200:203], v[98:101]
	v_mfma_f32_16x16x32_bf16 v[98:101], v[188:191], v[204:207], v[98:101]
	v_mfma_f32_16x16x32_bf16 v[114:117], v[188:191], v[196:199], v[114:117]
	v_mfma_f32_16x16x32_bf16 v[114:117], v[184:187], v[192:195], v[114:117]
	s_setprio 3
	s_add_i32 s80, s80, s55
	v_lshl_add_u64 v[226:227], v[170:171], 0, s[30:31]
	s_mov_b32 m0, s80
	ds_read_b128 v[192:195], v178 offset:49152
	ds_read_b128 v[196:199], v178 offset:50176
	ds_read_b128 v[200:203], v178 offset:51200
	ds_read_b128 v[204:207], v178 offset:52224
	ds_read_b128 v[208:211], v178 offset:53248
	ds_read_b128 v[212:215], v178 offset:54272
	ds_read_b128 v[216:219], v178 offset:55296
	ds_read_b128 v[220:223], v178 offset:56320
	global_load_lds_dwordx4 v[226:227], off
	v_lshl_add_u64 v[226:227], v[170:171], 0, s[34:35]
	s_add_i32 m0, s80, 0x2000
	s_add_i32 s80, s81, s55
	global_load_lds_dwordx4 v[226:227], off
	v_lshl_add_u64 v[226:227], v[170:171], 0, s[36:37]
	s_mov_b32 m0, s80
	v_lshl_add_u64 v[170:171], v[170:171], 0, s[38:39]
	global_load_lds_dwordx4 v[226:227], off
	s_add_i32 m0, s80, 0x2000
	s_nop 0
	global_load_lds_dwordx4 v[170:171], off
	v_lshl_add_u64 v[170:171], v[224:225], 0, s[30:31]
	s_mov_b32 m0, s63
	s_nop 0
	global_load_lds_dwordx4 v[170:171], off
	v_lshl_add_u64 v[170:171], v[224:225], 0, s[34:35]
	s_mov_b32 m0, s73
	s_nop 0
	global_load_lds_dwordx4 v[170:171], off
	s_waitcnt vmcnt(8)
	s_waitcnt lgkmcnt(0)
	s_barrier
	s_setprio 1
	s_waitcnt lgkmcnt(0)
	v_mfma_f32_16x16x32_bf16 v[62:65], v[130:133], v[192:195], v[62:65]
	v_mfma_f32_16x16x32_bf16 v[62:65], v[134:137], v[196:199], v[62:65]
	v_mfma_f32_16x16x32_bf16 v[46:49], v[134:137], v[204:207], v[46:49]
	v_mfma_f32_16x16x32_bf16 v[46:49], v[130:133], v[200:203], v[46:49]
	v_mfma_f32_16x16x32_bf16 v[30:33], v[130:133], v[208:211], v[30:33]
	v_mfma_f32_16x16x32_bf16 v[30:33], v[134:137], v[212:215], v[30:33]
	v_mfma_f32_16x16x32_bf16 v[14:17], v[134:137], v[220:223], v[14:17]
	v_mfma_f32_16x16x32_bf16 v[14:17], v[130:133], v[216:219], v[14:17]
	v_mfma_f32_16x16x32_bf16 v[10:13], v[154:157], v[216:219], v[10:13]
	v_mfma_f32_16x16x32_bf16 v[10:13], v[158:161], v[220:223], v[10:13]
	v_mfma_f32_16x16x32_bf16 v[26:29], v[158:161], v[212:215], v[26:29]
	v_mfma_f32_16x16x32_bf16 v[26:29], v[154:157], v[208:211], v[26:29]
	v_mfma_f32_16x16x32_bf16 v[42:45], v[154:157], v[200:203], v[42:45]
	v_mfma_f32_16x16x32_bf16 v[42:45], v[158:161], v[204:207], v[42:45]
	v_mfma_f32_16x16x32_bf16 v[58:61], v[158:161], v[196:199], v[58:61]
	v_mfma_f32_16x16x32_bf16 v[58:61], v[154:157], v[192:195], v[58:61]
	v_mfma_f32_16x16x32_bf16 v[54:57], v[162:165], v[192:195], v[54:57]
	v_mfma_f32_16x16x32_bf16 v[54:57], v[166:169], v[196:199], v[54:57]
	v_mfma_f32_16x16x32_bf16 v[38:41], v[166:169], v[204:207], v[38:41]
	v_mfma_f32_16x16x32_bf16 v[38:41], v[162:165], v[200:203], v[38:41]
	v_mfma_f32_16x16x32_bf16 v[22:25], v[162:165], v[208:211], v[22:25]
	v_mfma_f32_16x16x32_bf16 v[22:25], v[166:169], v[212:215], v[22:25]
	v_mfma_f32_16x16x32_bf16 v[6:9], v[166:169], v[220:223], v[6:9]
	v_mfma_f32_16x16x32_bf16 v[6:9], v[162:165], v[216:219], v[6:9]
	v_mfma_f32_16x16x32_bf16 v[2:5], v[184:187], v[216:219], v[2:5]
	v_mfma_f32_16x16x32_bf16 v[2:5], v[188:191], v[220:223], v[2:5]
	v_mfma_f32_16x16x32_bf16 v[18:21], v[188:191], v[212:215], v[18:21]
	v_mfma_f32_16x16x32_bf16 v[18:21], v[184:187], v[208:211], v[18:21]
	s_barrier
	s_setprio 2
	v_mfma_f32_16x16x32_bf16 v[34:37], v[184:187], v[200:203], v[34:37]
	v_mfma_f32_16x16x32_bf16 v[34:37], v[188:191], v[204:207], v[34:37]
	v_mfma_f32_16x16x32_bf16 v[50:53], v[188:191], v[196:199], v[50:53]
	v_mfma_f32_16x16x32_bf16 v[50:53], v[184:187], v[192:195], v[50:53]
	s_setprio 3
	s_cmp_gt_u32 s94, 29
	s_mov_b32 s94, s26
	s_cbranch_scc1 .LBB0_1669

; #define PG8_STAGE(bufoff, gbase, voff) do { if constexpr (!pg8_noload<Epi>::value) { _Pragma("unroll") for (int _i = 0; _i < 2; ++_i) \
;         __builtin_amdgcn_global_load_lds((const unsigned*)((const char*)(gbase) + (size_t)_i * pstep + (voff)[0]), (PG8_LAS unsigned*)(lds + (bufoff) + ldsw + _i * 8192), 16, 0, 0); } } while (0)
; #define PG8_LDA(dst, b, h) do { _Pragma("unroll") for (int m = 0; m < 4; ++m) _Pragma("unroll") for (int k = 0; k < 2; ++k) dst[m][k] = *(const PG8_LAS bf16x8*)(lds + PG8_SA(b, h) + aoff + m * 2048 + k * 1024); } while (0)
; #define PG8_LDB(dst, b, h) do { _Pragma("unroll") for (int n = 0; n < 2; ++n) _Pragma("unroll") for (int k = 0; k < 2; ++k) dst[n][k] = *(const PG8_LAS bf16x8*)(lds + PG8_SB(b, h) + boff + n * 2048 + k * 1024); } while (0)
; #define PG8_MMA(ai, bj, At, Bt) do { __builtin_amdgcn_s_setprio(1); _Pragma("unroll") for (int m = 0; m < 4; ++m) _Pragma("unroll") for (int n = 0; n < 2; ++n) _Pragma("unroll") for (int k = 0; k < 2; ++k) \
;         acc[ai][bj][m][n] = __builtin_amdgcn_mfma_f32_16x16x32_bf16(Bt[n][k], At[m][k], acc[ai][bj][m][n], 0, 0, 0); __builtin_amdgcn_s_setprio(0); } while (0)
; #define PG8_BAR __builtin_amdgcn_s_barrier()
; template <class Epi, class Sched, bool ALIGN_EPI = false, bool SP2 = false, bool ABLK = false>
; __device__ __forceinline__ void gemm_phase(PG8_LAS unsigned char* lds, const Gemm g, const Sched& S, const Epi& E) {
;     ...
;         for (int t = 0; t < nt; t += 2) {
;             const bool last = (t == nt - 2);
;             const char* a1 = cA + (size_t)(t + 1) * kstep;
;             const char* a2 = last ? nA : cA + (size_t)(t + 2) * kstep; const char* b2 = last ? nB : cB + (size_t)(t + 2) * kstepB;
;             const char* a3 = a2 + kstep; const char* b3 = b2 + kstepB;
;             if (last && has_next) S.a_ready(nxt);
;             if constexpr (SP2) {
;             PG8_LDB(B0, 0, 0); PG8_LDB(B1, 0, 1); PG8_SCHED; PG8_LDA(At, 0, 0); PG8_STAGE(PG8_SA(1, 1), a1 + hstep, voffA);
;             PG8_WAIT_V(8); PG8_WAIT_L(0); PG8_BAR; PG8_MMA(0, 0, At, B0); PG8_MMA(0, 1, At, B1); PG8_BAR; PG8_SCHED;
;             PG8_LDA(At, 0, 1); PG8_STAGE(PG8_SB(0, 0), b2, voffB); PG8_STAGE(PG8_SB(0, 1), b2 + hstep, voffB); PG8_STAGE(PG8_SA(0, 0), a2, voffA);
;             PG8_WAIT_V(8); PG8_WAIT_L(0); PG8_BAR; PG8_MMA(1, 0, At, B0); PG8_MMA(1, 1, At, B1); PG8_BAR; PG8_SCHED;
.LBB0_1997:
	ds_read_b128 v[130:133], v175
	ds_read_b128 v[134:137], v175 offset:1024
	ds_read_b128 v[138:141], v175 offset:2048
	ds_read_b128 v[142:145], v175 offset:3072
	ds_read_b128 v[146:149], v176
	ds_read_b128 v[150:153], v176 offset:1024
	ds_read_b128 v[154:157], v176 offset:2048
	ds_read_b128 v[158:161], v176 offset:3072
	s_add_i32 s43, s41, 2
	s_add_u32 s62, s52, 0xfff80800
	s_addc_u32 s63, s53, -1
	s_cmp_eq_u32 s3, s41
	s_cselect_b32 s63, s45, s63
	s_cselect_b32 s62, s44, s62
	s_cselect_b32 s77, s47, s39
	s_cselect_b32 s76, s46, s11
	v_lshl_add_u64 v[170:171], s[52:53], 0, v[166:167]
	s_add_i32 m0, s49, 0xc000
	ds_read_b128 v[184:187], v177
	ds_read_b128 v[188:191], v177 offset:1024
	ds_read_b128 v[192:195], v177 offset:2048
	ds_read_b128 v[196:199], v177 offset:3072
	ds_read_b128 v[200:203], v177 offset:4096
	ds_read_b128 v[204:207], v177 offset:5120
	ds_read_b128 v[208:211], v177 offset:6144
	ds_read_b128 v[212:215], v177 offset:7168
	global_load_lds_dwordx4 v[170:171], off
	v_lshl_add_u64 v[170:171], v[170:171], 0, s[12:13]
	s_add_i32 m0, s49, 0xe000
	s_nop 0
	global_load_lds_dwordx4 v[170:171], off
	s_waitcnt vmcnt(8)
	s_waitcnt lgkmcnt(0)
	s_barrier
	s_setprio 1
	s_waitcnt lgkmcnt(0)
	v_mfma_f32_16x16x32_bf16 v[126:129], v[130:133], v[184:187], v[126:129]
	v_mfma_f32_16x16x32_bf16 v[126:129], v[134:137], v[188:191], v[126:129]
	v_mfma_f32_16x16x32_bf16 v[110:113], v[134:137], v[196:199], v[110:113]
	v_mfma_f32_16x16x32_bf16 v[110:113], v[130:133], v[192:195], v[110:113]
	v_mfma_f32_16x16x32_bf16 v[94:97], v[130:133], v[200:203], v[94:97]
	v_mfma_f32_16x16x32_bf16 v[94:97], v[134:137], v[204:207], v[94:97]
	v_mfma_f32_16x16x32_bf16 v[78:81], v[134:137], v[212:215], v[78:81]
	v_mfma_f32_16x16x32_bf16 v[78:81], v[130:133], v[208:211], v[78:81]
	v_mfma_f32_16x16x32_bf16 v[74:77], v[138:141], v[208:211], v[74:77]
	v_mfma_f32_16x16x32_bf16 v[74:77], v[142:145], v[212:215], v[74:77]
	v_mfma_f32_16x16x32_bf16 v[90:93], v[142:145], v[204:207], v[90:93]
	v_mfma_f32_16x16x32_bf16 v[90:93], v[138:141], v[200:203], v[90:93]
	v_mfma_f32_16x16x32_bf16 v[106:109], v[138:141], v[192:195], v[106:109]
	v_mfma_f32_16x16x32_bf16 v[106:109], v[142:145], v[196:199], v[106:109]
	v_mfma_f32_16x16x32_bf16 v[122:125], v[142:145], v[188:191], v[122:125]
	v_mfma_f32_16x16x32_bf16 v[122:125], v[138:141], v[184:187], v[122:125]
	v_mfma_f32_16x16x32_bf16 v[118:121], v[146:149], v[184:187], v[118:121]
	v_mfma_f32_16x16x32_bf16 v[118:121], v[150:153], v[188:191], v[118:121]
	v_mfma_f32_16x16x32_bf16 v[102:105], v[150:153], v[196:199], v[102:105]
	v_mfma_f32_16x16x32_bf16 v[102:105], v[146:149], v[192:195], v[102:105]
	v_mfma_f32_16x16x32_bf16 v[86:89], v[146:149], v[200:203], v[86:89]
	v_mfma_f32_16x16x32_bf16 v[86:89], v[150:153], v[204:207], v[86:89]
	v_mfma_f32_16x16x32_bf16 v[70:73], v[150:153], v[212:215], v[70:73]
	v_mfma_f32_16x16x32_bf16 v[70:73], v[146:149], v[208:211], v[70:73]
	v_mfma_f32_16x16x32_bf16 v[66:69], v[154:157], v[208:211], v[66:69]
	v_mfma_f32_16x16x32_bf16 v[66:69], v[158:161], v[212:215], v[66:69]
	v_mfma_f32_16x16x32_bf16 v[82:85], v[158:161], v[204:207], v[82:85]
	v_mfma_f32_16x16x32_bf16 v[82:85], v[154:157], v[200:203], v[82:85]
	s_barrier
	s_setprio 2
	v_mfma_f32_16x16x32_bf16 v[98:101], v[154:157], v[192:195], v[98:101]
	v_mfma_f32_16x16x32_bf16 v[98:101], v[158:161], v[196:199], v[98:101]
	v_mfma_f32_16x16x32_bf16 v[114:117], v[158:161], v[188:191], v[114:117]
	v_mfma_f32_16x16x32_bf16 v[114:117], v[154:157], v[184:187], v[114:117]
	s_setprio 3
	s_add_i32 s41, s70, s57
	v_lshl_add_u64 v[170:171], s[76:77], 0, v[162:163]
	s_mov_b32 m0, s41
	ds_read_b128 v[184:187], v177 offset:16384
	ds_read_b128 v[188:191], v177 offset:17408
	ds_read_b128 v[192:195], v177 offset:18432
	ds_read_b128 v[196:199], v177 offset:19456
	ds_read_b128 v[200:203], v177 offset:20480
	ds_read_b128 v[204:207], v177 offset:21504
	ds_read_b128 v[208:211], v177 offset:22528
	ds_read_b128 v[212:215], v177 offset:23552
	global_load_lds_dwordx4 v[170:171], off
	v_lshl_add_u64 v[216:217], v[170:171], 0, s[12:13]
	s_add_i32 m0, s41, 0x2000
	s_add_i32 s41, s71, s57
	global_load_lds_dwordx4 v[216:217], off
	v_lshl_add_u64 v[216:217], v[170:171], 0, s[14:15]
	s_mov_b32 m0, s41
	s_nop 0
	global_load_lds_dwordx4 v[216:217], off
	v_lshl_add_u64 v[216:217], v[170:171], 0, s[16:17]
	s_add_i32 m0, s41, 0x2000
	s_nop 0
	global_load_lds_dwordx4 v[216:217], off
	v_lshl_add_u64 v[216:217], s[62:63], 0, v[162:163]
	s_mov_b32 m0, s49
	v_lshl_add_u64 v[218:219], v[216:217], 0, s[12:13]
	global_load_lds_dwordx4 v[216:217], off
	s_mov_b32 m0, s58
	s_nop 0
	global_load_lds_dwordx4 v[218:219], off
	s_waitcnt vmcnt(8)
	s_waitcnt lgkmcnt(0)
	s_barrier
; #define PG8_STAGE(bufoff, gbase, voff) do { if constexpr (!pg8_noload<Epi>::value) { _Pragma("unroll") for (int _i = 0; _i < 2; ++_i) \
;         __builtin_amdgcn_global_load_lds((const unsigned*)((const char*)(gbase) + (size_t)_i * pstep + (voff)[0]), (PG8_LAS unsigned*)(lds + (bufoff) + ldsw + _i * 8192), 16, 0, 0); } } while (0)
; #define PG8_LDA(dst, b, h) do { _Pragma("unroll") for (int m = 0; m < 4; ++m) _Pragma("unroll") for (int k = 0; k < 2; ++k) dst[m][k] = *(const PG8_LAS bf16x8*)(lds + PG8_SA(b, h) + aoff + m * 2048 + k * 1024); } while (0)
; #define PG8_LDB(dst, b, h) do { _Pragma("unroll") for (int n = 0; n < 2; ++n) _Pragma("unroll") for (int k = 0; k < 2; ++k) dst[n][k] = *(const PG8_LAS bf16x8*)(lds + PG8_SB(b, h) + boff + n * 2048 + k * 1024); } while (0)
; #define PG8_MMA(ai, bj, At, Bt) do { __builtin_amdgcn_s_setprio(1); _Pragma("unroll") for (int m = 0; m < 4; ++m) _Pragma("unroll") for (int n = 0; n < 2; ++n) _Pragma("unroll") for (int k = 0; k < 2; ++k) \
;         acc[ai][bj][m][n] = __builtin_amdgcn_mfma_f32_16x16x32_bf16(Bt[n][k], At[m][k], acc[ai][bj][m][n], 0, 0, 0); __builtin_amdgcn_s_setprio(0); } while (0)
; #define PG8_WAIT_V(n) asm volatile("s_waitcnt vmcnt(" #n ")" ::: "memory")
; #define PG8_WAIT_L(n) asm volatile("s_waitcnt lgkmcnt(" #n ")" ::: "memory")
; #define PG8_BAR __builtin_amdgcn_s_barrier()
; #define PG8_SCHED __builtin_amdgcn_sched_barrier(0)
; template <class Epi, class Sched, bool ALIGN_EPI = false, bool SP2 = false, bool ABLK = false>
; __device__ __forceinline__ void gemm_phase(PG8_LAS unsigned char* lds, const Gemm g, const Sched& S, const Epi& E) {
;     ...
;             PG8_WAIT_V(8); PG8_WAIT_L(0); PG8_BAR; PG8_MMA(1, 0, At, B0); PG8_MMA(1, 1, At, B1); PG8_BAR; PG8_SCHED;
;             PG8_LDB(B0, 1, 0); PG8_LDB(B1, 1, 1); PG8_SCHED; PG8_LDA(At, 1, 0); PG8_STAGE(PG8_SA(0, 1), a2 + hstep, voffA);
;             PG8_WAIT_V(8); PG8_WAIT_L(0); PG8_BAR; PG8_MMA(0, 0, At, B0); PG8_MMA(0, 1, At, B1); PG8_BAR; PG8_SCHED;
	s_setprio 1
	s_waitcnt lgkmcnt(0)
	v_mfma_f32_16x16x32_bf16 v[62:65], v[130:133], v[184:187], v[62:65]
	v_mfma_f32_16x16x32_bf16 v[62:65], v[134:137], v[188:191], v[62:65]
	v_mfma_f32_16x16x32_bf16 v[46:49], v[134:137], v[196:199], v[46:49]
	v_mfma_f32_16x16x32_bf16 v[46:49], v[130:133], v[192:195], v[46:49]
	v_mfma_f32_16x16x32_bf16 v[30:33], v[130:133], v[200:203], v[30:33]
	v_mfma_f32_16x16x32_bf16 v[30:33], v[134:137], v[204:207], v[30:33]
	v_mfma_f32_16x16x32_bf16 v[14:17], v[134:137], v[212:215], v[14:17]
	v_mfma_f32_16x16x32_bf16 v[14:17], v[130:133], v[208:211], v[14:17]
	v_mfma_f32_16x16x32_bf16 v[10:13], v[138:141], v[208:211], v[10:13]
	v_mfma_f32_16x16x32_bf16 v[10:13], v[142:145], v[212:215], v[10:13]
	v_mfma_f32_16x16x32_bf16 v[26:29], v[142:145], v[204:207], v[26:29]
	v_mfma_f32_16x16x32_bf16 v[26:29], v[138:141], v[200:203], v[26:29]
	v_mfma_f32_16x16x32_bf16 v[42:45], v[138:141], v[192:195], v[42:45]
	v_mfma_f32_16x16x32_bf16 v[42:45], v[142:145], v[196:199], v[42:45]
	v_mfma_f32_16x16x32_bf16 v[58:61], v[142:145], v[188:191], v[58:61]
	v_mfma_f32_16x16x32_bf16 v[58:61], v[138:141], v[184:187], v[58:61]
	v_mfma_f32_16x16x32_bf16 v[54:57], v[146:149], v[184:187], v[54:57]
	v_mfma_f32_16x16x32_bf16 v[54:57], v[150:153], v[188:191], v[54:57]
	v_mfma_f32_16x16x32_bf16 v[38:41], v[150:153], v[196:199], v[38:41]
	v_mfma_f32_16x16x32_bf16 v[38:41], v[146:149], v[192:195], v[38:41]
	v_mfma_f32_16x16x32_bf16 v[22:25], v[146:149], v[200:203], v[22:25]
	v_mfma_f32_16x16x32_bf16 v[22:25], v[150:153], v[204:207], v[22:25]
	v_mfma_f32_16x16x32_bf16 v[6:9], v[150:153], v[212:215], v[6:9]
	v_mfma_f32_16x16x32_bf16 v[6:9], v[146:149], v[208:211], v[6:9]
	v_mfma_f32_16x16x32_bf16 v[2:5], v[154:157], v[208:211], v[2:5]
	v_mfma_f32_16x16x32_bf16 v[2:5], v[158:161], v[212:215], v[2:5]
	v_mfma_f32_16x16x32_bf16 v[18:21], v[158:161], v[204:207], v[18:21]
	v_mfma_f32_16x16x32_bf16 v[18:21], v[154:157], v[200:203], v[18:21]
	s_barrier
	s_setprio 2
	v_mfma_f32_16x16x32_bf16 v[34:37], v[154:157], v[192:195], v[34:37]
	v_mfma_f32_16x16x32_bf16 v[34:37], v[158:161], v[196:199], v[34:37]
	v_mfma_f32_16x16x32_bf16 v[50:53], v[158:161], v[188:191], v[50:53]
	v_mfma_f32_16x16x32_bf16 v[50:53], v[154:157], v[184:187], v[50:53]
	s_setprio 3
	s_add_i32 s41, 0, 0x18000
	s_add_i32 s62, 0, 0x1c000
	v_add_u32_e32 v142, s41, v1
	v_add_u32_e32 v158, s62, v1
	ds_read_b128 v[130:133], v142
	ds_read_b128 v[134:137], v142 offset:1024
	ds_read_b128 v[138:141], v142 offset:2048
	ds_read_b128 v[142:145], v142 offset:3072
	ds_read_b128 v[146:149], v158
	ds_read_b128 v[150:153], v158 offset:1024
	ds_read_b128 v[154:157], v158 offset:2048
	ds_read_b128 v[158:161], v158 offset:3072
	s_mov_b32 m0, s59
	v_lshl_add_u64 v[218:219], v[216:217], 0, s[14:15]
	ds_read_b128 v[184:187], v177 offset:32768
	ds_read_b128 v[188:191], v177 offset:33792
	ds_read_b128 v[192:195], v177 offset:34816
	ds_read_b128 v[196:199], v177 offset:35840
	ds_read_b128 v[200:203], v177 offset:36864
	ds_read_b128 v[204:207], v177 offset:37888
	ds_read_b128 v[208:211], v177 offset:38912
	ds_read_b128 v[212:215], v177 offset:39936
	global_load_lds_dwordx4 v[218:219], off
	v_lshl_add_u64 v[218:219], v[216:217], 0, s[16:17]
	s_mov_b32 m0, s60
	s_nop 0
	global_load_lds_dwordx4 v[218:219], off
	s_waitcnt vmcnt(8)
	s_waitcnt lgkmcnt(0)
	s_barrier
	s_setprio 1
	s_waitcnt lgkmcnt(0)
	v_mfma_f32_16x16x32_bf16 v[126:129], v[130:133], v[184:187], v[126:129]
	v_mfma_f32_16x16x32_bf16 v[126:129], v[134:137], v[188:191], v[126:129]
	v_mfma_f32_16x16x32_bf16 v[110:113], v[134:137], v[196:199], v[110:113]
	v_mfma_f32_16x16x32_bf16 v[110:113], v[130:133], v[192:195], v[110:113]
	v_mfma_f32_16x16x32_bf16 v[94:97], v[130:133], v[200:203], v[94:97]
	v_mfma_f32_16x16x32_bf16 v[94:97], v[134:137], v[204:207], v[94:97]
	v_mfma_f32_16x16x32_bf16 v[78:81], v[134:137], v[212:215], v[78:81]
	v_mfma_f32_16x16x32_bf16 v[78:81], v[130:133], v[208:211], v[78:81]
	v_mfma_f32_16x16x32_bf16 v[74:77], v[138:141], v[208:211], v[74:77]
	v_mfma_f32_16x16x32_bf16 v[74:77], v[142:145], v[212:215], v[74:77]
	v_mfma_f32_16x16x32_bf16 v[90:93], v[142:145], v[204:207], v[90:93]
	v_mfma_f32_16x16x32_bf16 v[90:93], v[138:141], v[200:203], v[90:93]
	v_mfma_f32_16x16x32_bf16 v[106:109], v[138:141], v[192:195], v[106:109]
	v_mfma_f32_16x16x32_bf16 v[106:109], v[142:145], v[196:199], v[106:109]
	v_mfma_f32_16x16x32_bf16 v[122:125], v[142:145], v[188:191], v[122:125]
	v_mfma_f32_16x16x32_bf16 v[122:125], v[138:141], v[184:187], v[122:125]
	v_mfma_f32_16x16x32_bf16 v[118:121], v[146:149], v[184:187], v[118:121]
	v_mfma_f32_16x16x32_bf16 v[118:121], v[150:153], v[188:191], v[118:121]
	v_mfma_f32_16x16x32_bf16 v[102:105], v[150:153], v[196:199], v[102:105]
	v_mfma_f32_16x16x32_bf16 v[102:105], v[146:149], v[192:195], v[102:105]
	v_mfma_f32_16x16x32_bf16 v[86:89], v[146:149], v[200:203], v[86:89]
	v_mfma_f32_16x16x32_bf16 v[86:89], v[150:153], v[204:207], v[86:89]
	v_mfma_f32_16x16x32_bf16 v[70:73], v[150:153], v[212:215], v[70:73]
	v_mfma_f32_16x16x32_bf16 v[70:73], v[146:149], v[208:211], v[70:73]
	v_mfma_f32_16x16x32_bf16 v[66:69], v[154:157], v[208:211], v[66:69]
	v_mfma_f32_16x16x32_bf16 v[66:69], v[158:161], v[212:215], v[66:69]
	v_mfma_f32_16x16x32_bf16 v[82:85], v[158:161], v[204:207], v[82:85]
	v_mfma_f32_16x16x32_bf16 v[82:85], v[154:157], v[200:203], v[82:85]
	s_barrier
; #define PG8_STAGE(bufoff, gbase, voff) do { if constexpr (!pg8_noload<Epi>::value) { _Pragma("unroll") for (int _i = 0; _i < 2; ++_i) \
;         __builtin_amdgcn_global_load_lds((const unsigned*)((const char*)(gbase) + (size_t)_i * pstep + (voff)[0]), (PG8_LAS unsigned*)(lds + (bufoff) + ldsw + _i * 8192), 16, 0, 0); } } while (0)
; #define PG8_LDA(dst, b, h) do { _Pragma("unroll") for (int m = 0; m < 4; ++m) _Pragma("unroll") for (int k = 0; k < 2; ++k) dst[m][k] = *(const PG8_LAS bf16x8*)(lds + PG8_SA(b, h) + aoff + m * 2048 + k * 1024); } while (0)
; #define PG8_MMA(ai, bj, At, Bt) do { __builtin_amdgcn_s_setprio(1); _Pragma("unroll") for (int m = 0; m < 4; ++m) _Pragma("unroll") for (int n = 0; n < 2; ++n) _Pragma("unroll") for (int k = 0; k < 2; ++k) \
;         acc[ai][bj][m][n] = __builtin_amdgcn_mfma_f32_16x16x32_bf16(Bt[n][k], At[m][k], acc[ai][bj][m][n], 0, 0, 0); __builtin_amdgcn_s_setprio(0); } while (0)
; #define PG8_WAIT_V(n) asm volatile("s_waitcnt vmcnt(" #n ")" ::: "memory")
; #define PG8_WAIT_L(n) asm volatile("s_waitcnt lgkmcnt(" #n ")" ::: "memory")
; #define PG8_BAR __builtin_amdgcn_s_barrier()
; #define PG8_SCHED __builtin_amdgcn_sched_barrier(0)
; template <class Epi, class Sched, bool ALIGN_EPI = false, bool SP2 = false, bool ABLK = false>
; __device__ __forceinline__ void gemm_phase(PG8_LAS unsigned char* lds, const Gemm g, const Sched& S, const Epi& E) {
;     ...
;             PG8_WAIT_V(8); PG8_WAIT_L(0); PG8_BAR; PG8_MMA(0, 0, At, B0); PG8_MMA(0, 1, At, B1); PG8_BAR; PG8_SCHED;
;             PG8_LDA(At, 1, 1); PG8_STAGE(PG8_SB(1, 0), b3, voffB); PG8_STAGE(PG8_SB(1, 1), b3 + hstep, voffB); PG8_STAGE(PG8_SA(1, 0), a3, voffA);
;             PG8_WAIT_V(8); PG8_WAIT_L(0); PG8_BAR; PG8_MMA(1, 0, At, B0); PG8_MMA(1, 1, At, B1); PG8_BAR; PG8_SCHED;
	s_setprio 2
	v_mfma_f32_16x16x32_bf16 v[98:101], v[154:157], v[192:195], v[98:101]
	v_mfma_f32_16x16x32_bf16 v[98:101], v[158:161], v[196:199], v[98:101]
	v_mfma_f32_16x16x32_bf16 v[114:117], v[158:161], v[188:191], v[114:117]
	v_mfma_f32_16x16x32_bf16 v[114:117], v[154:157], v[184:187], v[114:117]
	s_setprio 3
	s_add_i32 s41, s41, s57
	v_lshl_add_u64 v[218:219], v[170:171], 0, s[24:25]
	s_mov_b32 m0, s41
	ds_read_b128 v[184:187], v177 offset:49152
	ds_read_b128 v[188:191], v177 offset:50176
	ds_read_b128 v[192:195], v177 offset:51200
	ds_read_b128 v[196:199], v177 offset:52224
	ds_read_b128 v[200:203], v177 offset:53248
	ds_read_b128 v[204:207], v177 offset:54272
	ds_read_b128 v[208:211], v177 offset:55296
	ds_read_b128 v[212:215], v177 offset:56320
	global_load_lds_dwordx4 v[218:219], off
	v_lshl_add_u64 v[218:219], v[170:171], 0, s[26:27]
	s_add_i32 m0, s41, 0x2000
	s_add_i32 s41, s62, s57
	global_load_lds_dwordx4 v[218:219], off
	v_lshl_add_u64 v[218:219], v[170:171], 0, s[28:29]
	s_mov_b32 m0, s41
	v_lshl_add_u64 v[170:171], v[170:171], 0, s[30:31]
	global_load_lds_dwordx4 v[218:219], off
	s_add_i32 m0, s41, 0x2000
	s_nop 0
	global_load_lds_dwordx4 v[170:171], off
	v_lshl_add_u64 v[170:171], v[216:217], 0, s[24:25]
	s_mov_b32 m0, s65
	s_nop 0
	global_load_lds_dwordx4 v[170:171], off
	v_lshl_add_u64 v[170:171], v[216:217], 0, s[26:27]
	s_mov_b32 m0, s66
	s_nop 0
	global_load_lds_dwordx4 v[170:171], off
	s_waitcnt vmcnt(8)
	s_waitcnt lgkmcnt(0)
	s_barrier
	s_setprio 1
	s_waitcnt lgkmcnt(0)
	v_mfma_f32_16x16x32_bf16 v[62:65], v[130:133], v[184:187], v[62:65]
	v_mfma_f32_16x16x32_bf16 v[62:65], v[134:137], v[188:191], v[62:65]
	v_mfma_f32_16x16x32_bf16 v[46:49], v[134:137], v[196:199], v[46:49]
	v_mfma_f32_16x16x32_bf16 v[46:49], v[130:133], v[192:195], v[46:49]
	v_mfma_f32_16x16x32_bf16 v[30:33], v[130:133], v[200:203], v[30:33]
	v_mfma_f32_16x16x32_bf16 v[30:33], v[134:137], v[204:207], v[30:33]
	v_mfma_f32_16x16x32_bf16 v[14:17], v[134:137], v[212:215], v[14:17]
	v_mfma_f32_16x16x32_bf16 v[14:17], v[130:133], v[208:211], v[14:17]
	v_mfma_f32_16x16x32_bf16 v[10:13], v[138:141], v[208:211], v[10:13]
	v_mfma_f32_16x16x32_bf16 v[10:13], v[142:145], v[212:215], v[10:13]
	v_mfma_f32_16x16x32_bf16 v[26:29], v[142:145], v[204:207], v[26:29]
	v_mfma_f32_16x16x32_bf16 v[26:29], v[138:141], v[200:203], v[26:29]
	v_mfma_f32_16x16x32_bf16 v[42:45], v[138:141], v[192:195], v[42:45]
	v_mfma_f32_16x16x32_bf16 v[42:45], v[142:145], v[196:199], v[42:45]
	v_mfma_f32_16x16x32_bf16 v[58:61], v[142:145], v[188:191], v[58:61]
	v_mfma_f32_16x16x32_bf16 v[58:61], v[138:141], v[184:187], v[58:61]
	v_mfma_f32_16x16x32_bf16 v[54:57], v[146:149], v[184:187], v[54:57]
	v_mfma_f32_16x16x32_bf16 v[54:57], v[150:153], v[188:191], v[54:57]
	v_mfma_f32_16x16x32_bf16 v[38:41], v[150:153], v[196:199], v[38:41]
	v_mfma_f32_16x16x32_bf16 v[38:41], v[146:149], v[192:195], v[38:41]
	v_mfma_f32_16x16x32_bf16 v[22:25], v[146:149], v[200:203], v[22:25]
	v_mfma_f32_16x16x32_bf16 v[22:25], v[150:153], v[204:207], v[22:25]
	v_mfma_f32_16x16x32_bf16 v[6:9], v[150:153], v[212:215], v[6:9]
	v_mfma_f32_16x16x32_bf16 v[6:9], v[146:149], v[208:211], v[6:9]
	v_mfma_f32_16x16x32_bf16 v[2:5], v[154:157], v[208:211], v[2:5]
	v_mfma_f32_16x16x32_bf16 v[2:5], v[158:161], v[212:215], v[2:5]
	v_mfma_f32_16x16x32_bf16 v[18:21], v[158:161], v[204:207], v[18:21]
	v_mfma_f32_16x16x32_bf16 v[18:21], v[154:157], v[200:203], v[18:21]
	s_barrier
	s_setprio 2
	v_mfma_f32_16x16x32_bf16 v[34:37], v[154:157], v[192:195], v[34:37]
	v_mfma_f32_16x16x32_bf16 v[34:37], v[158:161], v[196:199], v[34:37]
	v_mfma_f32_16x16x32_bf16 v[50:53], v[158:161], v[188:191], v[50:53]
	v_mfma_f32_16x16x32_bf16 v[50:53], v[154:157], v[184:187], v[50:53]
	s_setprio 3
	s_add_u32 s52, s52, 0x1000
	s_addc_u32 s53, s53, 0
	s_add_u32 s11, s11, 0x1000
	s_addc_u32 s39, s39, 0
	s_cmp_ge_i32 s43, s75
	s_mov_b32 s41, s43
	s_cbranch_scc0 .LBB0_1997
	s_and_b64 vcc, exec, s[34:35]
	s_cbranch_vccnz .LBB0_2002
	s_lshl_b32 s11, s2, 8
	s_cmp_gt_i32 s2, 63
	s_mov_b64 s[52:53], -1
	s_cbranch_scc1 .LBB0_2003

; #define PG8_STAGE(bufoff, gbase, voff) do { if constexpr (!pg8_noload<Epi>::value) { _Pragma("unroll") for (int _i = 0; _i < 2; ++_i) \
;         __builtin_amdgcn_global_load_lds((const unsigned*)((const char*)(gbase) + (size_t)_i * pstep + (voff)[0]), (PG8_LAS unsigned*)(lds + (bufoff) + ldsw + _i * 8192), 16, 0, 0); } } while (0)
; #define PG8_LDA(dst, b, h) do { _Pragma("unroll") for (int m = 0; m < 4; ++m) _Pragma("unroll") for (int k = 0; k < 2; ++k) dst[m][k] = *(const PG8_LAS bf16x8*)(lds + PG8_SA(b, h) + aoff + m * 2048 + k * 1024); } while (0)
; #define PG8_LDB(dst, b, h) do { _Pragma("unroll") for (int n = 0; n < 2; ++n) _Pragma("unroll") for (int k = 0; k < 2; ++k) dst[n][k] = *(const PG8_LAS bf16x8*)(lds + PG8_SB(b, h) + boff + n * 2048 + k * 1024); } while (0)
; #define PG8_MMA(ai, bj, At, Bt) do { __builtin_amdgcn_s_setprio(1); _Pragma("unroll") for (int m = 0; m < 4; ++m) _Pragma("unroll") for (int n = 0; n < 2; ++n) _Pragma("unroll") for (int k = 0; k < 2; ++k) \
;         acc[ai][bj][m][n] = __builtin_amdgcn_mfma_f32_16x16x32_bf16(Bt[n][k], At[m][k], acc[ai][bj][m][n], 0, 0, 0); __builtin_amdgcn_s_setprio(0); } while (0)
; #define PG8_BAR __builtin_amdgcn_s_barrier()
; template <class Epi, class Sched, bool ALIGN_EPI = false, bool SP2 = false, bool ABLK = false>
; __device__ __forceinline__ void gemm_phase(PG8_LAS unsigned char* lds, const Gemm g, const Sched& S, const Epi& E) {
;     ...
;         for (int t = 0; t < nt; t += 2) {
;             const bool last = (t == nt - 2);
;             const char* a1 = cA + (size_t)(t + 1) * kstep;
;             const char* a2 = last ? nA : cA + (size_t)(t + 2) * kstep; const char* b2 = last ? nB : cB + (size_t)(t + 2) * kstepB;
;             const char* a3 = a2 + kstep; const char* b3 = b2 + kstepB;
;             if (last && has_next) S.a_ready(nxt);
;             if constexpr (SP2) {
;             PG8_LDB(B0, 0, 0); PG8_LDB(B1, 0, 1); PG8_SCHED; PG8_LDA(At, 0, 0); PG8_STAGE(PG8_SA(1, 1), a1 + hstep, voffA);
;             PG8_WAIT_V(8); PG8_WAIT_L(0); PG8_BAR; PG8_MMA(0, 0, At, B0); PG8_MMA(0, 1, At, B1); PG8_BAR; PG8_SCHED;
;             PG8_LDA(At, 0, 1); PG8_STAGE(PG8_SB(0, 0), b2, voffB); PG8_STAGE(PG8_SB(0, 1), b2 + hstep, voffB); PG8_STAGE(PG8_SA(0, 0), a2, voffA);
;             PG8_WAIT_V(8); PG8_WAIT_L(0); PG8_BAR; PG8_MMA(1, 0, At, B0); PG8_MMA(1, 1, At, B1); PG8_BAR; PG8_SCHED;
.LBB0_2119:
	s_or_b32 s30, s59, 1
	s_lshl_b64 s[14:15], s[30:31], 11
	s_add_u32 s14, s82, s14
	v_add_u32_e32 v133, s71, v148
	s_addc_u32 s15, s83, s15
	s_add_i32 s30, s59, 2
	ds_read_b128 v[144:147], v133
	ds_read_b128 v[184:187], v133 offset:1024
	ds_read_b128 v[188:191], v133 offset:2048
	ds_read_b128 v[192:195], v133 offset:3072
	v_add_u32_e32 v133, s73, v148
	s_lshl_b64 s[34:35], s[30:31], 11
	ds_read_b128 v[196:199], v133
	ds_read_b128 v[200:203], v133 offset:1024
	ds_read_b128 v[204:207], v133 offset:2048
	ds_read_b128 v[208:211], v133 offset:3072
	s_add_u32 s96, s82, s34
	s_addc_u32 s97, s83, s35
	s_and_b64 s[94:95], s[92:93], exec
	s_cselect_b32 s95, s97, s77
	s_cselect_b32 s94, s96, s28
	s_add_u32 s96, s88, s34
	s_addc_u32 s97, s89, s35
	s_and_b64 s[34:35], s[92:93], exec
	s_cselect_b32 s35, s97, s29
	s_cselect_b32 s34, s96, s75
	v_lshl_add_u64 v[180:181], s[14:15], 0, v[130:131]
	v_lshl_add_u64 v[244:245], v[180:181], 0, s[24:25]
	s_add_i32 m0, s17, 0xc000
	ds_read_b128 v[212:215], v168
	ds_read_b128 v[216:219], v168 offset:1024
	ds_read_b128 v[220:223], v168 offset:2048
	ds_read_b128 v[224:227], v168 offset:3072
	ds_read_b128 v[228:231], v168 offset:4096
	ds_read_b128 v[232:235], v168 offset:5120
	ds_read_b128 v[236:239], v168 offset:6144
	ds_read_b128 v[240:243], v168 offset:7168
	global_load_lds_dwordx4 v[244:245], off
	v_lshl_add_u64 v[180:181], v[180:181], 0, s[26:27]
	s_add_i32 m0, s17, 0xe000
	s_nop 0
	global_load_lds_dwordx4 v[180:181], off
	s_waitcnt vmcnt(8)
	s_waitcnt lgkmcnt(0)
	s_barrier
	s_setprio 1
	s_waitcnt lgkmcnt(0)
	v_mfma_f32_16x16x32_bf16 v[126:129], v[144:147], v[212:215], v[126:129]
	v_mfma_f32_16x16x32_bf16 v[126:129], v[184:187], v[216:219], v[126:129]
	v_mfma_f32_16x16x32_bf16 v[110:113], v[184:187], v[224:227], v[110:113]
	v_mfma_f32_16x16x32_bf16 v[110:113], v[144:147], v[220:223], v[110:113]
	v_mfma_f32_16x16x32_bf16 v[94:97], v[144:147], v[228:231], v[94:97]
	v_mfma_f32_16x16x32_bf16 v[94:97], v[184:187], v[232:235], v[94:97]
	v_mfma_f32_16x16x32_bf16 v[78:81], v[184:187], v[240:243], v[78:81]
	v_mfma_f32_16x16x32_bf16 v[78:81], v[144:147], v[236:239], v[78:81]
	v_mfma_f32_16x16x32_bf16 v[74:77], v[188:191], v[236:239], v[74:77]
	v_mfma_f32_16x16x32_bf16 v[74:77], v[192:195], v[240:243], v[74:77]
	v_mfma_f32_16x16x32_bf16 v[90:93], v[192:195], v[232:235], v[90:93]
	v_mfma_f32_16x16x32_bf16 v[90:93], v[188:191], v[228:231], v[90:93]
	v_mfma_f32_16x16x32_bf16 v[106:109], v[188:191], v[220:223], v[106:109]
	v_mfma_f32_16x16x32_bf16 v[106:109], v[192:195], v[224:227], v[106:109]
	v_mfma_f32_16x16x32_bf16 v[122:125], v[192:195], v[216:219], v[122:125]
	v_mfma_f32_16x16x32_bf16 v[122:125], v[188:191], v[212:215], v[122:125]
	v_mfma_f32_16x16x32_bf16 v[118:121], v[196:199], v[212:215], v[118:121]
	v_mfma_f32_16x16x32_bf16 v[118:121], v[200:203], v[216:219], v[118:121]
	v_mfma_f32_16x16x32_bf16 v[102:105], v[200:203], v[224:227], v[102:105]
	v_mfma_f32_16x16x32_bf16 v[102:105], v[196:199], v[220:223], v[102:105]
	v_mfma_f32_16x16x32_bf16 v[86:89], v[196:199], v[228:231], v[86:89]
	v_mfma_f32_16x16x32_bf16 v[86:89], v[200:203], v[232:235], v[86:89]
	v_mfma_f32_16x16x32_bf16 v[70:73], v[200:203], v[240:243], v[70:73]
	v_mfma_f32_16x16x32_bf16 v[70:73], v[196:199], v[236:239], v[70:73]
	v_mfma_f32_16x16x32_bf16 v[66:69], v[204:207], v[236:239], v[66:69]
	v_mfma_f32_16x16x32_bf16 v[66:69], v[208:211], v[240:243], v[66:69]
	v_mfma_f32_16x16x32_bf16 v[82:85], v[208:211], v[232:235], v[82:85]
	v_mfma_f32_16x16x32_bf16 v[82:85], v[204:207], v[228:231], v[82:85]
	s_barrier
	s_setprio 2
	v_mfma_f32_16x16x32_bf16 v[98:101], v[204:207], v[220:223], v[98:101]
	v_mfma_f32_16x16x32_bf16 v[98:101], v[208:211], v[224:227], v[98:101]
	v_mfma_f32_16x16x32_bf16 v[114:117], v[208:211], v[216:219], v[114:117]
	v_mfma_f32_16x16x32_bf16 v[114:117], v[204:207], v[212:215], v[114:117]
	s_setprio 3
	s_add_i32 s14, s71, s3
	v_lshl_add_u64 v[180:181], s[34:35], 0, v[130:131]
	s_mov_b32 m0, s14
	ds_read_b128 v[212:215], v168 offset:16384
	ds_read_b128 v[216:219], v168 offset:17408
	ds_read_b128 v[220:223], v168 offset:18432
	ds_read_b128 v[224:227], v168 offset:19456
	ds_read_b128 v[228:231], v168 offset:20480
	ds_read_b128 v[232:235], v168 offset:21504
	ds_read_b128 v[236:239], v168 offset:22528
	ds_read_b128 v[240:243], v168 offset:23552
	global_load_lds_dwordx4 v[180:181], off
	v_lshl_add_u64 v[244:245], v[180:181], 0, s[22:23]
	s_add_i32 m0, s14, 0x2000
	s_add_i32 s14, s73, s3
	global_load_lds_dwordx4 v[244:245], off
	v_lshl_add_u64 v[244:245], v[180:181], 0, s[24:25]
	s_mov_b32 m0, s14
	s_nop 0
	global_load_lds_dwordx4 v[244:245], off
	v_lshl_add_u64 v[244:245], v[180:181], 0, s[26:27]
	s_add_i32 m0, s14, 0x2000
	s_nop 0
	global_load_lds_dwordx4 v[244:245], off
	v_lshl_add_u64 v[244:245], s[94:95], 0, v[130:131]
	s_mov_b32 m0, s17
	v_lshl_add_u64 v[246:247], v[244:245], 0, s[22:23]
	global_load_lds_dwordx4 v[244:245], off
	s_mov_b32 m0, s56
	s_nop 0
	global_load_lds_dwordx4 v[246:247], off
	s_waitcnt vmcnt(8)
	s_waitcnt lgkmcnt(0)
	s_barrier
; #define PG8_STAGE(bufoff, gbase, voff) do { if constexpr (!pg8_noload<Epi>::value) { _Pragma("unroll") for (int _i = 0; _i < 2; ++_i) \
;         __builtin_amdgcn_global_load_lds((const unsigned*)((const char*)(gbase) + (size_t)_i * pstep + (voff)[0]), (PG8_LAS unsigned*)(lds + (bufoff) + ldsw + _i * 8192), 16, 0, 0); } } while (0)
; #define PG8_LDA(dst, b, h) do { _Pragma("unroll") for (int m = 0; m < 4; ++m) _Pragma("unroll") for (int k = 0; k < 2; ++k) dst[m][k] = *(const PG8_LAS bf16x8*)(lds + PG8_SA(b, h) + aoff + m * 2048 + k * 1024); } while (0)
; #define PG8_LDB(dst, b, h) do { _Pragma("unroll") for (int n = 0; n < 2; ++n) _Pragma("unroll") for (int k = 0; k < 2; ++k) dst[n][k] = *(const PG8_LAS bf16x8*)(lds + PG8_SB(b, h) + boff + n * 2048 + k * 1024); } while (0)
; #define PG8_MMA(ai, bj, At, Bt) do { __builtin_amdgcn_s_setprio(1); _Pragma("unroll") for (int m = 0; m < 4; ++m) _Pragma("unroll") for (int n = 0; n < 2; ++n) _Pragma("unroll") for (int k = 0; k < 2; ++k) \
;         acc[ai][bj][m][n] = __builtin_amdgcn_mfma_f32_16x16x32_bf16(Bt[n][k], At[m][k], acc[ai][bj][m][n], 0, 0, 0); __builtin_amdgcn_s_setprio(0); } while (0)
; #define PG8_WAIT_V(n) asm volatile("s_waitcnt vmcnt(" #n ")" ::: "memory")
; #define PG8_WAIT_L(n) asm volatile("s_waitcnt lgkmcnt(" #n ")" ::: "memory")
; #define PG8_BAR __builtin_amdgcn_s_barrier()
; #define PG8_SCHED __builtin_amdgcn_sched_barrier(0)
; template <class Epi, class Sched, bool ALIGN_EPI = false, bool SP2 = false, bool ABLK = false>
; __device__ __forceinline__ void gemm_phase(PG8_LAS unsigned char* lds, const Gemm g, const Sched& S, const Epi& E) {
;     ...
;             PG8_WAIT_V(8); PG8_WAIT_L(0); PG8_BAR; PG8_MMA(1, 0, At, B0); PG8_MMA(1, 1, At, B1); PG8_BAR; PG8_SCHED;
;             PG8_LDB(B0, 1, 0); PG8_LDB(B1, 1, 1); PG8_SCHED; PG8_LDA(At, 1, 0); PG8_STAGE(PG8_SA(0, 1), a2 + hstep, voffA);
;             PG8_WAIT_V(8); PG8_WAIT_L(0); PG8_BAR; PG8_MMA(0, 0, At, B0); PG8_MMA(0, 1, At, B1); PG8_BAR; PG8_SCHED;
	s_setprio 1
	s_waitcnt lgkmcnt(0)
	v_mfma_f32_16x16x32_bf16 v[62:65], v[144:147], v[212:215], v[62:65]
	v_mfma_f32_16x16x32_bf16 v[62:65], v[184:187], v[216:219], v[62:65]
	v_mfma_f32_16x16x32_bf16 v[46:49], v[184:187], v[224:227], v[46:49]
	v_mfma_f32_16x16x32_bf16 v[46:49], v[144:147], v[220:223], v[46:49]
	v_mfma_f32_16x16x32_bf16 v[30:33], v[144:147], v[228:231], v[30:33]
	v_mfma_f32_16x16x32_bf16 v[30:33], v[184:187], v[232:235], v[30:33]
	v_mfma_f32_16x16x32_bf16 v[14:17], v[184:187], v[240:243], v[14:17]
	v_mfma_f32_16x16x32_bf16 v[14:17], v[144:147], v[236:239], v[14:17]
	v_mfma_f32_16x16x32_bf16 v[10:13], v[188:191], v[236:239], v[10:13]
	v_mfma_f32_16x16x32_bf16 v[10:13], v[192:195], v[240:243], v[10:13]
	v_mfma_f32_16x16x32_bf16 v[26:29], v[192:195], v[232:235], v[26:29]
	v_mfma_f32_16x16x32_bf16 v[26:29], v[188:191], v[228:231], v[26:29]
	v_mfma_f32_16x16x32_bf16 v[42:45], v[188:191], v[220:223], v[42:45]
	v_mfma_f32_16x16x32_bf16 v[42:45], v[192:195], v[224:227], v[42:45]
	v_mfma_f32_16x16x32_bf16 v[58:61], v[192:195], v[216:219], v[58:61]
	v_mfma_f32_16x16x32_bf16 v[58:61], v[188:191], v[212:215], v[58:61]
	v_mfma_f32_16x16x32_bf16 v[54:57], v[196:199], v[212:215], v[54:57]
	v_mfma_f32_16x16x32_bf16 v[54:57], v[200:203], v[216:219], v[54:57]
	v_mfma_f32_16x16x32_bf16 v[38:41], v[200:203], v[224:227], v[38:41]
	v_mfma_f32_16x16x32_bf16 v[38:41], v[196:199], v[220:223], v[38:41]
	v_mfma_f32_16x16x32_bf16 v[22:25], v[196:199], v[228:231], v[22:25]
	v_mfma_f32_16x16x32_bf16 v[22:25], v[200:203], v[232:235], v[22:25]
	v_mfma_f32_16x16x32_bf16 v[6:9], v[200:203], v[240:243], v[6:9]
	v_mfma_f32_16x16x32_bf16 v[6:9], v[196:199], v[236:239], v[6:9]
	v_mfma_f32_16x16x32_bf16 v[2:5], v[204:207], v[236:239], v[2:5]
	v_mfma_f32_16x16x32_bf16 v[2:5], v[208:211], v[240:243], v[2:5]
	v_mfma_f32_16x16x32_bf16 v[18:21], v[208:211], v[232:235], v[18:21]
	v_mfma_f32_16x16x32_bf16 v[18:21], v[204:207], v[228:231], v[18:21]
	s_barrier
	s_setprio 2
	v_mfma_f32_16x16x32_bf16 v[34:37], v[204:207], v[220:223], v[34:37]
	v_mfma_f32_16x16x32_bf16 v[34:37], v[208:211], v[224:227], v[34:37]
	v_mfma_f32_16x16x32_bf16 v[50:53], v[208:211], v[216:219], v[50:53]
	v_mfma_f32_16x16x32_bf16 v[50:53], v[204:207], v[212:215], v[50:53]
	s_setprio 3
	s_add_i32 s14, 0, 0x18000
	v_add_u32_e32 v133, s14, v148
	s_add_i32 s15, 0, 0x1c000
	ds_read_b128 v[144:147], v133
	ds_read_b128 v[184:187], v133 offset:1024
	ds_read_b128 v[188:191], v133 offset:2048
	ds_read_b128 v[192:195], v133 offset:3072
	v_add_u32_e32 v133, s15, v148
	ds_read_b128 v[196:199], v133
	ds_read_b128 v[200:203], v133 offset:1024
	ds_read_b128 v[204:207], v133 offset:2048
	ds_read_b128 v[208:211], v133 offset:3072
	s_mov_b32 m0, s57
	v_lshl_add_u64 v[246:247], v[244:245], 0, s[24:25]
	ds_read_b128 v[212:215], v168 offset:32768
	ds_read_b128 v[216:219], v168 offset:33792
	ds_read_b128 v[220:223], v168 offset:34816
	ds_read_b128 v[224:227], v168 offset:35840
	ds_read_b128 v[228:231], v168 offset:36864
	ds_read_b128 v[232:235], v168 offset:37888
	ds_read_b128 v[236:239], v168 offset:38912
	ds_read_b128 v[240:243], v168 offset:39936
	global_load_lds_dwordx4 v[246:247], off
	v_lshl_add_u64 v[246:247], v[244:245], 0, s[26:27]
	s_mov_b32 m0, s58
	s_nop 0
	global_load_lds_dwordx4 v[246:247], off
	s_waitcnt vmcnt(8)
	s_waitcnt lgkmcnt(0)
	s_barrier
	s_setprio 1
	s_waitcnt lgkmcnt(0)
	v_mfma_f32_16x16x32_bf16 v[126:129], v[144:147], v[212:215], v[126:129]
	v_mfma_f32_16x16x32_bf16 v[126:129], v[184:187], v[216:219], v[126:129]
	v_mfma_f32_16x16x32_bf16 v[110:113], v[184:187], v[224:227], v[110:113]
	v_mfma_f32_16x16x32_bf16 v[110:113], v[144:147], v[220:223], v[110:113]
	v_mfma_f32_16x16x32_bf16 v[94:97], v[144:147], v[228:231], v[94:97]
	v_mfma_f32_16x16x32_bf16 v[94:97], v[184:187], v[232:235], v[94:97]
	v_mfma_f32_16x16x32_bf16 v[78:81], v[184:187], v[240:243], v[78:81]
	v_mfma_f32_16x16x32_bf16 v[78:81], v[144:147], v[236:239], v[78:81]
	v_mfma_f32_16x16x32_bf16 v[74:77], v[188:191], v[236:239], v[74:77]
	v_mfma_f32_16x16x32_bf16 v[74:77], v[192:195], v[240:243], v[74:77]
	v_mfma_f32_16x16x32_bf16 v[90:93], v[192:195], v[232:235], v[90:93]
	v_mfma_f32_16x16x32_bf16 v[90:93], v[188:191], v[228:231], v[90:93]
	v_mfma_f32_16x16x32_bf16 v[106:109], v[188:191], v[220:223], v[106:109]
	v_mfma_f32_16x16x32_bf16 v[106:109], v[192:195], v[224:227], v[106:109]
	v_mfma_f32_16x16x32_bf16 v[122:125], v[192:195], v[216:219], v[122:125]
	v_mfma_f32_16x16x32_bf16 v[122:125], v[188:191], v[212:215], v[122:125]
	v_mfma_f32_16x16x32_bf16 v[118:121], v[196:199], v[212:215], v[118:121]
	v_mfma_f32_16x16x32_bf16 v[118:121], v[200:203], v[216:219], v[118:121]
	v_mfma_f32_16x16x32_bf16 v[102:105], v[200:203], v[224:227], v[102:105]
	v_mfma_f32_16x16x32_bf16 v[102:105], v[196:199], v[220:223], v[102:105]
	v_mfma_f32_16x16x32_bf16 v[86:89], v[196:199], v[228:231], v[86:89]
	v_mfma_f32_16x16x32_bf16 v[86:89], v[200:203], v[232:235], v[86:89]
	v_mfma_f32_16x16x32_bf16 v[70:73], v[200:203], v[240:243], v[70:73]
	v_mfma_f32_16x16x32_bf16 v[70:73], v[196:199], v[236:239], v[70:73]
	v_mfma_f32_16x16x32_bf16 v[66:69], v[204:207], v[236:239], v[66:69]
	v_mfma_f32_16x16x32_bf16 v[66:69], v[208:211], v[240:243], v[66:69]
	v_mfma_f32_16x16x32_bf16 v[82:85], v[208:211], v[232:235], v[82:85]
	v_mfma_f32_16x16x32_bf16 v[82:85], v[204:207], v[228:231], v[82:85]
	s_barrier
; #define PG8_STAGE(bufoff, gbase, voff) do { if constexpr (!pg8_noload<Epi>::value) { _Pragma("unroll") for (int _i = 0; _i < 2; ++_i) \
;         __builtin_amdgcn_global_load_lds((const unsigned*)((const char*)(gbase) + (size_t)_i * pstep + (voff)[0]), (PG8_LAS unsigned*)(lds + (bufoff) + ldsw + _i * 8192), 16, 0, 0); } } while (0)
; #define PG8_LDA(dst, b, h) do { _Pragma("unroll") for (int m = 0; m < 4; ++m) _Pragma("unroll") for (int k = 0; k < 2; ++k) dst[m][k] = *(const PG8_LAS bf16x8*)(lds + PG8_SA(b, h) + aoff + m * 2048 + k * 1024); } while (0)
; #define PG8_MMA(ai, bj, At, Bt) do { __builtin_amdgcn_s_setprio(1); _Pragma("unroll") for (int m = 0; m < 4; ++m) _Pragma("unroll") for (int n = 0; n < 2; ++n) _Pragma("unroll") for (int k = 0; k < 2; ++k) \
;         acc[ai][bj][m][n] = __builtin_amdgcn_mfma_f32_16x16x32_bf16(Bt[n][k], At[m][k], acc[ai][bj][m][n], 0, 0, 0); __builtin_amdgcn_s_setprio(0); } while (0)
; #define PG8_WAIT_V(n) asm volatile("s_waitcnt vmcnt(" #n ")" ::: "memory")
; #define PG8_WAIT_L(n) asm volatile("s_waitcnt lgkmcnt(" #n ")" ::: "memory")
; #define PG8_BAR __builtin_amdgcn_s_barrier()
; #define PG8_SCHED __builtin_amdgcn_sched_barrier(0)
; template <class Epi, class Sched, bool ALIGN_EPI = false, bool SP2 = false, bool ABLK = false>
; __device__ __forceinline__ void gemm_phase(PG8_LAS unsigned char* lds, const Gemm g, const Sched& S, const Epi& E) {
;     ...
;             PG8_WAIT_V(8); PG8_WAIT_L(0); PG8_BAR; PG8_MMA(0, 0, At, B0); PG8_MMA(0, 1, At, B1); PG8_BAR; PG8_SCHED;
;             PG8_LDA(At, 1, 1); PG8_STAGE(PG8_SB(1, 0), b3, voffB); PG8_STAGE(PG8_SB(1, 1), b3 + hstep, voffB); PG8_STAGE(PG8_SA(1, 0), a3, voffA);
;             PG8_WAIT_V(8); PG8_WAIT_L(0); PG8_BAR; PG8_MMA(1, 0, At, B0); PG8_MMA(1, 1, At, B1); PG8_BAR; PG8_SCHED;
	s_setprio 2
	v_mfma_f32_16x16x32_bf16 v[98:101], v[204:207], v[220:223], v[98:101]
	v_mfma_f32_16x16x32_bf16 v[98:101], v[208:211], v[224:227], v[98:101]
	v_mfma_f32_16x16x32_bf16 v[114:117], v[208:211], v[216:219], v[114:117]
	v_mfma_f32_16x16x32_bf16 v[114:117], v[204:207], v[212:215], v[114:117]
	s_setprio 3
	s_add_i32 s14, s14, s3
	v_lshl_add_u64 v[246:247], v[180:181], 0, s[38:39]
	s_mov_b32 m0, s14
	ds_read_b128 v[212:215], v168 offset:49152
	ds_read_b128 v[216:219], v168 offset:50176
	ds_read_b128 v[220:223], v168 offset:51200
	ds_read_b128 v[224:227], v168 offset:52224
	ds_read_b128 v[228:231], v168 offset:53248
	ds_read_b128 v[232:235], v168 offset:54272
	ds_read_b128 v[236:239], v168 offset:55296
	ds_read_b128 v[240:243], v168 offset:56320
	global_load_lds_dwordx4 v[246:247], off
	v_lshl_add_u64 v[246:247], v[180:181], 0, s[40:41]
	s_add_i32 m0, s14, 0x2000
	s_add_i32 s14, s15, s3
	global_load_lds_dwordx4 v[246:247], off
	v_lshl_add_u64 v[246:247], v[180:181], 0, s[42:43]
	s_mov_b32 m0, s14
	v_lshl_add_u64 v[180:181], v[180:181], 0, s[44:45]
	global_load_lds_dwordx4 v[246:247], off
	s_add_i32 m0, s14, 0x2000
	s_nop 0
	global_load_lds_dwordx4 v[180:181], off
	v_lshl_add_u64 v[180:181], v[244:245], 0, s[38:39]
	s_mov_b32 m0, s61
	s_nop 0
	global_load_lds_dwordx4 v[180:181], off
	v_lshl_add_u64 v[180:181], v[244:245], 0, s[40:41]
	s_mov_b32 m0, s63
	s_nop 0
	global_load_lds_dwordx4 v[180:181], off
	s_waitcnt vmcnt(8)
	s_waitcnt lgkmcnt(0)
	s_barrier
	s_setprio 1
	s_waitcnt lgkmcnt(0)
	v_mfma_f32_16x16x32_bf16 v[62:65], v[144:147], v[212:215], v[62:65]
	v_mfma_f32_16x16x32_bf16 v[62:65], v[184:187], v[216:219], v[62:65]
	v_mfma_f32_16x16x32_bf16 v[46:49], v[184:187], v[224:227], v[46:49]
	v_mfma_f32_16x16x32_bf16 v[46:49], v[144:147], v[220:223], v[46:49]
	v_mfma_f32_16x16x32_bf16 v[30:33], v[144:147], v[228:231], v[30:33]
	v_mfma_f32_16x16x32_bf16 v[30:33], v[184:187], v[232:235], v[30:33]
	v_mfma_f32_16x16x32_bf16 v[14:17], v[184:187], v[240:243], v[14:17]
	v_mfma_f32_16x16x32_bf16 v[14:17], v[144:147], v[236:239], v[14:17]
	v_mfma_f32_16x16x32_bf16 v[10:13], v[188:191], v[236:239], v[10:13]
	v_mfma_f32_16x16x32_bf16 v[10:13], v[192:195], v[240:243], v[10:13]
	v_mfma_f32_16x16x32_bf16 v[26:29], v[192:195], v[232:235], v[26:29]
	v_mfma_f32_16x16x32_bf16 v[26:29], v[188:191], v[228:231], v[26:29]
	v_mfma_f32_16x16x32_bf16 v[42:45], v[188:191], v[220:223], v[42:45]
	v_mfma_f32_16x16x32_bf16 v[42:45], v[192:195], v[224:227], v[42:45]
	v_mfma_f32_16x16x32_bf16 v[58:61], v[192:195], v[216:219], v[58:61]
	v_mfma_f32_16x16x32_bf16 v[58:61], v[188:191], v[212:215], v[58:61]
	v_mfma_f32_16x16x32_bf16 v[54:57], v[196:199], v[212:215], v[54:57]
	v_mfma_f32_16x16x32_bf16 v[54:57], v[200:203], v[216:219], v[54:57]
	v_mfma_f32_16x16x32_bf16 v[38:41], v[200:203], v[224:227], v[38:41]
	v_mfma_f32_16x16x32_bf16 v[38:41], v[196:199], v[220:223], v[38:41]
	v_mfma_f32_16x16x32_bf16 v[22:25], v[196:199], v[228:231], v[22:25]
	v_mfma_f32_16x16x32_bf16 v[22:25], v[200:203], v[232:235], v[22:25]
	v_mfma_f32_16x16x32_bf16 v[6:9], v[200:203], v[240:243], v[6:9]
	v_mfma_f32_16x16x32_bf16 v[6:9], v[196:199], v[236:239], v[6:9]
	v_mfma_f32_16x16x32_bf16 v[2:5], v[204:207], v[236:239], v[2:5]
	v_mfma_f32_16x16x32_bf16 v[2:5], v[208:211], v[240:243], v[2:5]
	v_mfma_f32_16x16x32_bf16 v[18:21], v[208:211], v[232:235], v[18:21]
	v_mfma_f32_16x16x32_bf16 v[18:21], v[204:207], v[228:231], v[18:21]
	s_barrier
	s_setprio 2
	v_mfma_f32_16x16x32_bf16 v[34:37], v[204:207], v[220:223], v[34:37]
	v_mfma_f32_16x16x32_bf16 v[34:37], v[208:211], v[224:227], v[34:37]
	v_mfma_f32_16x16x32_bf16 v[50:53], v[208:211], v[216:219], v[50:53]
	v_mfma_f32_16x16x32_bf16 v[50:53], v[204:207], v[212:215], v[50:53]
	s_setprio 3
	s_cmp_gt_u32 s59, 29
	s_mov_b32 s59, s30
	s_cbranch_scc1 .LBB0_2131

; #define PG8_STAGE(bufoff, gbase, voff) do { if constexpr (!pg8_noload<Epi>::value) { _Pragma("unroll") for (int _i = 0; _i < 2; ++_i) \
;         __builtin_amdgcn_global_load_lds((const unsigned*)((const char*)(gbase) + (size_t)_i * pstep + (voff)[0]), (PG8_LAS unsigned*)(lds + (bufoff) + ldsw + _i * 8192), 16, 0, 0); } } while (0)
; #define PG8_LDA(dst, b, h) do { _Pragma("unroll") for (int m = 0; m < 4; ++m) _Pragma("unroll") for (int k = 0; k < 2; ++k) dst[m][k] = *(const PG8_LAS bf16x8*)(lds + PG8_SA(b, h) + aoff + m * 2048 + k * 1024); } while (0)
; #define PG8_LDB(dst, b, h) do { _Pragma("unroll") for (int n = 0; n < 2; ++n) _Pragma("unroll") for (int k = 0; k < 2; ++k) dst[n][k] = *(const PG8_LAS bf16x8*)(lds + PG8_SB(b, h) + boff + n * 2048 + k * 1024); } while (0)
; #define PG8_MMA(ai, bj, At, Bt) do { __builtin_amdgcn_s_setprio(1); _Pragma("unroll") for (int m = 0; m < 4; ++m) _Pragma("unroll") for (int n = 0; n < 2; ++n) _Pragma("unroll") for (int k = 0; k < 2; ++k) \
;         acc[ai][bj][m][n] = __builtin_amdgcn_mfma_f32_16x16x32_bf16(Bt[n][k], At[m][k], acc[ai][bj][m][n], 0, 0, 0); __builtin_amdgcn_s_setprio(0); } while (0)
; #define PG8_BAR __builtin_amdgcn_s_barrier()
; template <class Epi, class Sched, bool ALIGN_EPI = false, bool SP2 = false, bool ABLK = false>
; __device__ __forceinline__ void gemm_phase(PG8_LAS unsigned char* lds, const Gemm g, const Sched& S, const Epi& E) {
;     ...
;         for (int t = 0; t < nt; t += 2) {
;             const bool last = (t == nt - 2);
;             const char* a1 = cA + (size_t)(t + 1) * kstep;
;             const char* a2 = last ? nA : cA + (size_t)(t + 2) * kstep; const char* b2 = last ? nB : cB + (size_t)(t + 2) * kstepB;
;             const char* a3 = a2 + kstep; const char* b3 = b2 + kstepB;
;             if (last && has_next) S.a_ready(nxt);
;             if constexpr (SP2) {
;             PG8_LDB(B0, 0, 0); PG8_LDB(B1, 0, 1); PG8_SCHED; PG8_LDA(At, 0, 0); PG8_STAGE(PG8_SA(1, 1), a1 + hstep, voffA);
;             PG8_WAIT_V(8); PG8_WAIT_L(0); PG8_BAR; PG8_MMA(0, 0, At, B0); PG8_MMA(0, 1, At, B1); PG8_BAR; PG8_SCHED;
;             PG8_LDA(At, 0, 1); PG8_STAGE(PG8_SB(0, 0), b2, voffB); PG8_STAGE(PG8_SB(0, 1), b2 + hstep, voffB); PG8_STAGE(PG8_SA(0, 0), a2, voffA);
;             PG8_WAIT_V(8); PG8_WAIT_L(0); PG8_BAR; PG8_MMA(1, 0, At, B0); PG8_MMA(1, 1, At, B1); PG8_BAR; PG8_SCHED;
.LBB0_2399:
	ds_read_b128 v[130:133], v175
	ds_read_b128 v[134:137], v175 offset:1024
	ds_read_b128 v[138:141], v175 offset:2048
	ds_read_b128 v[142:145], v175 offset:3072
	ds_read_b128 v[146:149], v176
	ds_read_b128 v[150:153], v176 offset:1024
	ds_read_b128 v[154:157], v176 offset:2048
	ds_read_b128 v[158:161], v176 offset:3072
	s_add_i32 s55, s53, 2
	s_add_u32 s64, s62, 0xfff00800
	s_addc_u32 s65, s63, -1
	s_cmp_eq_u32 s3, s53
	s_cselect_b32 s65, s57, s65
	s_cselect_b32 s64, s56, s64
	s_cselect_b32 s91, s59, s49
	s_cselect_b32 s90, s58, s11
	v_lshl_add_u64 v[170:171], s[62:63], 0, v[166:167]
	s_add_i32 m0, s61, 0xc000
	ds_read_b128 v[184:187], v177
	ds_read_b128 v[188:191], v177 offset:1024
	ds_read_b128 v[192:195], v177 offset:2048
	ds_read_b128 v[196:199], v177 offset:3072
	ds_read_b128 v[200:203], v177 offset:4096
	ds_read_b128 v[204:207], v177 offset:5120
	ds_read_b128 v[208:211], v177 offset:6144
	ds_read_b128 v[212:215], v177 offset:7168
	global_load_lds_dwordx4 v[170:171], off
	v_lshl_add_u64 v[170:171], v[170:171], 0, s[12:13]
	s_add_i32 m0, s61, 0xe000
	s_nop 0
	global_load_lds_dwordx4 v[170:171], off
	s_waitcnt vmcnt(8)
	s_waitcnt lgkmcnt(0)
	s_barrier
	s_setprio 1
	s_waitcnt lgkmcnt(0)
	v_mfma_f32_16x16x32_bf16 v[126:129], v[130:133], v[184:187], v[126:129]
	v_mfma_f32_16x16x32_bf16 v[126:129], v[134:137], v[188:191], v[126:129]
	v_mfma_f32_16x16x32_bf16 v[110:113], v[134:137], v[196:199], v[110:113]
	v_mfma_f32_16x16x32_bf16 v[110:113], v[130:133], v[192:195], v[110:113]
	v_mfma_f32_16x16x32_bf16 v[94:97], v[130:133], v[200:203], v[94:97]
	v_mfma_f32_16x16x32_bf16 v[94:97], v[134:137], v[204:207], v[94:97]
	v_mfma_f32_16x16x32_bf16 v[78:81], v[134:137], v[212:215], v[78:81]
	v_mfma_f32_16x16x32_bf16 v[78:81], v[130:133], v[208:211], v[78:81]
	v_mfma_f32_16x16x32_bf16 v[74:77], v[138:141], v[208:211], v[74:77]
	v_mfma_f32_16x16x32_bf16 v[74:77], v[142:145], v[212:215], v[74:77]
	v_mfma_f32_16x16x32_bf16 v[90:93], v[142:145], v[204:207], v[90:93]
	v_mfma_f32_16x16x32_bf16 v[90:93], v[138:141], v[200:203], v[90:93]
	v_mfma_f32_16x16x32_bf16 v[106:109], v[138:141], v[192:195], v[106:109]
	v_mfma_f32_16x16x32_bf16 v[106:109], v[142:145], v[196:199], v[106:109]
	v_mfma_f32_16x16x32_bf16 v[122:125], v[142:145], v[188:191], v[122:125]
	v_mfma_f32_16x16x32_bf16 v[122:125], v[138:141], v[184:187], v[122:125]
	v_mfma_f32_16x16x32_bf16 v[118:121], v[146:149], v[184:187], v[118:121]
	v_mfma_f32_16x16x32_bf16 v[118:121], v[150:153], v[188:191], v[118:121]
	v_mfma_f32_16x16x32_bf16 v[102:105], v[150:153], v[196:199], v[102:105]
	v_mfma_f32_16x16x32_bf16 v[102:105], v[146:149], v[192:195], v[102:105]
	v_mfma_f32_16x16x32_bf16 v[86:89], v[146:149], v[200:203], v[86:89]
	v_mfma_f32_16x16x32_bf16 v[86:89], v[150:153], v[204:207], v[86:89]
	v_mfma_f32_16x16x32_bf16 v[70:73], v[150:153], v[212:215], v[70:73]
	v_mfma_f32_16x16x32_bf16 v[70:73], v[146:149], v[208:211], v[70:73]
	v_mfma_f32_16x16x32_bf16 v[66:69], v[154:157], v[208:211], v[66:69]
	v_mfma_f32_16x16x32_bf16 v[66:69], v[158:161], v[212:215], v[66:69]
	v_mfma_f32_16x16x32_bf16 v[82:85], v[158:161], v[204:207], v[82:85]
	v_mfma_f32_16x16x32_bf16 v[82:85], v[154:157], v[200:203], v[82:85]
	s_barrier
	s_setprio 2
	v_mfma_f32_16x16x32_bf16 v[98:101], v[154:157], v[192:195], v[98:101]
	v_mfma_f32_16x16x32_bf16 v[98:101], v[158:161], v[196:199], v[98:101]
	v_mfma_f32_16x16x32_bf16 v[114:117], v[158:161], v[188:191], v[114:117]
	v_mfma_f32_16x16x32_bf16 v[114:117], v[154:157], v[184:187], v[114:117]
	s_setprio 3
	s_add_i32 s53, s80, s69
	v_lshl_add_u64 v[170:171], s[90:91], 0, v[162:163]
	s_mov_b32 m0, s53
	ds_read_b128 v[184:187], v177 offset:16384
	ds_read_b128 v[188:191], v177 offset:17408
	ds_read_b128 v[192:195], v177 offset:18432
	ds_read_b128 v[196:199], v177 offset:19456
	ds_read_b128 v[200:203], v177 offset:20480
	ds_read_b128 v[204:207], v177 offset:21504
	ds_read_b128 v[208:211], v177 offset:22528
	ds_read_b128 v[212:215], v177 offset:23552
	global_load_lds_dwordx4 v[170:171], off
	v_lshl_add_u64 v[216:217], v[170:171], 0, s[12:13]
	s_add_i32 m0, s53, 0x2000
	s_add_i32 s53, s81, s69
	global_load_lds_dwordx4 v[216:217], off
	v_lshl_add_u64 v[216:217], v[170:171], 0, s[14:15]
	s_mov_b32 m0, s53
	s_nop 0
	global_load_lds_dwordx4 v[216:217], off
	v_lshl_add_u64 v[216:217], v[170:171], 0, s[16:17]
	s_add_i32 m0, s53, 0x2000
	s_nop 0
	global_load_lds_dwordx4 v[216:217], off
	v_lshl_add_u64 v[216:217], s[64:65], 0, v[162:163]
	s_mov_b32 m0, s61
	v_lshl_add_u64 v[218:219], v[216:217], 0, s[12:13]
	global_load_lds_dwordx4 v[216:217], off
	s_mov_b32 m0, s70
	s_nop 0
	global_load_lds_dwordx4 v[218:219], off
	s_waitcnt vmcnt(8)
	s_waitcnt lgkmcnt(0)
	s_barrier
; #define PG8_STAGE(bufoff, gbase, voff) do { if constexpr (!pg8_noload<Epi>::value) { _Pragma("unroll") for (int _i = 0; _i < 2; ++_i) \
;         __builtin_amdgcn_global_load_lds((const unsigned*)((const char*)(gbase) + (size_t)_i * pstep + (voff)[0]), (PG8_LAS unsigned*)(lds + (bufoff) + ldsw + _i * 8192), 16, 0, 0); } } while (0)
; #define PG8_LDA(dst, b, h) do { _Pragma("unroll") for (int m = 0; m < 4; ++m) _Pragma("unroll") for (int k = 0; k < 2; ++k) dst[m][k] = *(const PG8_LAS bf16x8*)(lds + PG8_SA(b, h) + aoff + m * 2048 + k * 1024); } while (0)
; #define PG8_LDB(dst, b, h) do { _Pragma("unroll") for (int n = 0; n < 2; ++n) _Pragma("unroll") for (int k = 0; k < 2; ++k) dst[n][k] = *(const PG8_LAS bf16x8*)(lds + PG8_SB(b, h) + boff + n * 2048 + k * 1024); } while (0)
; #define PG8_MMA(ai, bj, At, Bt) do { __builtin_amdgcn_s_setprio(1); _Pragma("unroll") for (int m = 0; m < 4; ++m) _Pragma("unroll") for (int n = 0; n < 2; ++n) _Pragma("unroll") for (int k = 0; k < 2; ++k) \
;         acc[ai][bj][m][n] = __builtin_amdgcn_mfma_f32_16x16x32_bf16(Bt[n][k], At[m][k], acc[ai][bj][m][n], 0, 0, 0); __builtin_amdgcn_s_setprio(0); } while (0)
; #define PG8_WAIT_V(n) asm volatile("s_waitcnt vmcnt(" #n ")" ::: "memory")
; #define PG8_WAIT_L(n) asm volatile("s_waitcnt lgkmcnt(" #n ")" ::: "memory")
; #define PG8_BAR __builtin_amdgcn_s_barrier()
; #define PG8_SCHED __builtin_amdgcn_sched_barrier(0)
; template <class Epi, class Sched, bool ALIGN_EPI = false, bool SP2 = false, bool ABLK = false>
; __device__ __forceinline__ void gemm_phase(PG8_LAS unsigned char* lds, const Gemm g, const Sched& S, const Epi& E) {
;     ...
;             PG8_WAIT_V(8); PG8_WAIT_L(0); PG8_BAR; PG8_MMA(1, 0, At, B0); PG8_MMA(1, 1, At, B1); PG8_BAR; PG8_SCHED;
;             PG8_LDB(B0, 1, 0); PG8_LDB(B1, 1, 1); PG8_SCHED; PG8_LDA(At, 1, 0); PG8_STAGE(PG8_SA(0, 1), a2 + hstep, voffA);
;             PG8_WAIT_V(8); PG8_WAIT_L(0); PG8_BAR; PG8_MMA(0, 0, At, B0); PG8_MMA(0, 1, At, B1); PG8_BAR; PG8_SCHED;
	s_setprio 1
	s_waitcnt lgkmcnt(0)
	v_mfma_f32_16x16x32_bf16 v[62:65], v[130:133], v[184:187], v[62:65]
	v_mfma_f32_16x16x32_bf16 v[62:65], v[134:137], v[188:191], v[62:65]
	v_mfma_f32_16x16x32_bf16 v[46:49], v[134:137], v[196:199], v[46:49]
	v_mfma_f32_16x16x32_bf16 v[46:49], v[130:133], v[192:195], v[46:49]
	v_mfma_f32_16x16x32_bf16 v[30:33], v[130:133], v[200:203], v[30:33]
	v_mfma_f32_16x16x32_bf16 v[30:33], v[134:137], v[204:207], v[30:33]
	v_mfma_f32_16x16x32_bf16 v[14:17], v[134:137], v[212:215], v[14:17]
	v_mfma_f32_16x16x32_bf16 v[14:17], v[130:133], v[208:211], v[14:17]
	v_mfma_f32_16x16x32_bf16 v[10:13], v[138:141], v[208:211], v[10:13]
	v_mfma_f32_16x16x32_bf16 v[10:13], v[142:145], v[212:215], v[10:13]
	v_mfma_f32_16x16x32_bf16 v[26:29], v[142:145], v[204:207], v[26:29]
	v_mfma_f32_16x16x32_bf16 v[26:29], v[138:141], v[200:203], v[26:29]
	v_mfma_f32_16x16x32_bf16 v[42:45], v[138:141], v[192:195], v[42:45]
	v_mfma_f32_16x16x32_bf16 v[42:45], v[142:145], v[196:199], v[42:45]
	v_mfma_f32_16x16x32_bf16 v[58:61], v[142:145], v[188:191], v[58:61]
	v_mfma_f32_16x16x32_bf16 v[58:61], v[138:141], v[184:187], v[58:61]
	v_mfma_f32_16x16x32_bf16 v[54:57], v[146:149], v[184:187], v[54:57]
	v_mfma_f32_16x16x32_bf16 v[54:57], v[150:153], v[188:191], v[54:57]
	v_mfma_f32_16x16x32_bf16 v[38:41], v[150:153], v[196:199], v[38:41]
	v_mfma_f32_16x16x32_bf16 v[38:41], v[146:149], v[192:195], v[38:41]
	v_mfma_f32_16x16x32_bf16 v[22:25], v[146:149], v[200:203], v[22:25]
	v_mfma_f32_16x16x32_bf16 v[22:25], v[150:153], v[204:207], v[22:25]
	v_mfma_f32_16x16x32_bf16 v[6:9], v[150:153], v[212:215], v[6:9]
	v_mfma_f32_16x16x32_bf16 v[6:9], v[146:149], v[208:211], v[6:9]
	v_mfma_f32_16x16x32_bf16 v[2:5], v[154:157], v[208:211], v[2:5]
	v_mfma_f32_16x16x32_bf16 v[2:5], v[158:161], v[212:215], v[2:5]
	v_mfma_f32_16x16x32_bf16 v[18:21], v[158:161], v[204:207], v[18:21]
	v_mfma_f32_16x16x32_bf16 v[18:21], v[154:157], v[200:203], v[18:21]
	s_barrier
	s_setprio 2
	v_mfma_f32_16x16x32_bf16 v[34:37], v[154:157], v[192:195], v[34:37]
	v_mfma_f32_16x16x32_bf16 v[34:37], v[158:161], v[196:199], v[34:37]
	v_mfma_f32_16x16x32_bf16 v[50:53], v[158:161], v[188:191], v[50:53]
	v_mfma_f32_16x16x32_bf16 v[50:53], v[154:157], v[184:187], v[50:53]
	s_setprio 3
	s_add_i32 s53, 0, 0x18000
	s_add_i32 s64, 0, 0x1c000
	v_add_u32_e32 v142, s53, v1
	v_add_u32_e32 v158, s64, v1
	ds_read_b128 v[130:133], v142
	ds_read_b128 v[134:137], v142 offset:1024
	ds_read_b128 v[138:141], v142 offset:2048
	ds_read_b128 v[142:145], v142 offset:3072
	ds_read_b128 v[146:149], v158
	ds_read_b128 v[150:153], v158 offset:1024
	ds_read_b128 v[154:157], v158 offset:2048
	ds_read_b128 v[158:161], v158 offset:3072
	s_mov_b32 m0, s71
	v_lshl_add_u64 v[218:219], v[216:217], 0, s[14:15]
	ds_read_b128 v[184:187], v177 offset:32768
	ds_read_b128 v[188:191], v177 offset:33792
	ds_read_b128 v[192:195], v177 offset:34816
	ds_read_b128 v[196:199], v177 offset:35840
	ds_read_b128 v[200:203], v177 offset:36864
	ds_read_b128 v[204:207], v177 offset:37888
	ds_read_b128 v[208:211], v177 offset:38912
	ds_read_b128 v[212:215], v177 offset:39936
	global_load_lds_dwordx4 v[218:219], off
	v_lshl_add_u64 v[218:219], v[216:217], 0, s[16:17]
	s_mov_b32 m0, s72
	s_nop 0
	global_load_lds_dwordx4 v[218:219], off
	s_waitcnt vmcnt(8)
	s_waitcnt lgkmcnt(0)
	s_barrier
	s_setprio 1
	s_waitcnt lgkmcnt(0)
	v_mfma_f32_16x16x32_bf16 v[126:129], v[130:133], v[184:187], v[126:129]
	v_mfma_f32_16x16x32_bf16 v[126:129], v[134:137], v[188:191], v[126:129]
	v_mfma_f32_16x16x32_bf16 v[110:113], v[134:137], v[196:199], v[110:113]
	v_mfma_f32_16x16x32_bf16 v[110:113], v[130:133], v[192:195], v[110:113]
	v_mfma_f32_16x16x32_bf16 v[94:97], v[130:133], v[200:203], v[94:97]
	v_mfma_f32_16x16x32_bf16 v[94:97], v[134:137], v[204:207], v[94:97]
	v_mfma_f32_16x16x32_bf16 v[78:81], v[134:137], v[212:215], v[78:81]
	v_mfma_f32_16x16x32_bf16 v[78:81], v[130:133], v[208:211], v[78:81]
	v_mfma_f32_16x16x32_bf16 v[74:77], v[138:141], v[208:211], v[74:77]
	v_mfma_f32_16x16x32_bf16 v[74:77], v[142:145], v[212:215], v[74:77]
	v_mfma_f32_16x16x32_bf16 v[90:93], v[142:145], v[204:207], v[90:93]
	v_mfma_f32_16x16x32_bf16 v[90:93], v[138:141], v[200:203], v[90:93]
	v_mfma_f32_16x16x32_bf16 v[106:109], v[138:141], v[192:195], v[106:109]
	v_mfma_f32_16x16x32_bf16 v[106:109], v[142:145], v[196:199], v[106:109]
	v_mfma_f32_16x16x32_bf16 v[122:125], v[142:145], v[188:191], v[122:125]
	v_mfma_f32_16x16x32_bf16 v[122:125], v[138:141], v[184:187], v[122:125]
	v_mfma_f32_16x16x32_bf16 v[118:121], v[146:149], v[184:187], v[118:121]
	v_mfma_f32_16x16x32_bf16 v[118:121], v[150:153], v[188:191], v[118:121]
	v_mfma_f32_16x16x32_bf16 v[102:105], v[150:153], v[196:199], v[102:105]
	v_mfma_f32_16x16x32_bf16 v[102:105], v[146:149], v[192:195], v[102:105]
	v_mfma_f32_16x16x32_bf16 v[86:89], v[146:149], v[200:203], v[86:89]
	v_mfma_f32_16x16x32_bf16 v[86:89], v[150:153], v[204:207], v[86:89]
	v_mfma_f32_16x16x32_bf16 v[70:73], v[150:153], v[212:215], v[70:73]
	v_mfma_f32_16x16x32_bf16 v[70:73], v[146:149], v[208:211], v[70:73]
	v_mfma_f32_16x16x32_bf16 v[66:69], v[154:157], v[208:211], v[66:69]
	v_mfma_f32_16x16x32_bf16 v[66:69], v[158:161], v[212:215], v[66:69]
	v_mfma_f32_16x16x32_bf16 v[82:85], v[158:161], v[204:207], v[82:85]
	v_mfma_f32_16x16x32_bf16 v[82:85], v[154:157], v[200:203], v[82:85]
	s_barrier
; #define PG8_STAGE(bufoff, gbase, voff) do { if constexpr (!pg8_noload<Epi>::value) { _Pragma("unroll") for (int _i = 0; _i < 2; ++_i) \
;         __builtin_amdgcn_global_load_lds((const unsigned*)((const char*)(gbase) + (size_t)_i * pstep + (voff)[0]), (PG8_LAS unsigned*)(lds + (bufoff) + ldsw + _i * 8192), 16, 0, 0); } } while (0)
; #define PG8_LDA(dst, b, h) do { _Pragma("unroll") for (int m = 0; m < 4; ++m) _Pragma("unroll") for (int k = 0; k < 2; ++k) dst[m][k] = *(const PG8_LAS bf16x8*)(lds + PG8_SA(b, h) + aoff + m * 2048 + k * 1024); } while (0)
; #define PG8_MMA(ai, bj, At, Bt) do { __builtin_amdgcn_s_setprio(1); _Pragma("unroll") for (int m = 0; m < 4; ++m) _Pragma("unroll") for (int n = 0; n < 2; ++n) _Pragma("unroll") for (int k = 0; k < 2; ++k) \
;         acc[ai][bj][m][n] = __builtin_amdgcn_mfma_f32_16x16x32_bf16(Bt[n][k], At[m][k], acc[ai][bj][m][n], 0, 0, 0); __builtin_amdgcn_s_setprio(0); } while (0)
; #define PG8_WAIT_V(n) asm volatile("s_waitcnt vmcnt(" #n ")" ::: "memory")
; #define PG8_WAIT_L(n) asm volatile("s_waitcnt lgkmcnt(" #n ")" ::: "memory")
; #define PG8_BAR __builtin_amdgcn_s_barrier()
; #define PG8_SCHED __builtin_amdgcn_sched_barrier(0)
; template <class Epi, class Sched, bool ALIGN_EPI = false, bool SP2 = false, bool ABLK = false>
; __device__ __forceinline__ void gemm_phase(PG8_LAS unsigned char* lds, const Gemm g, const Sched& S, const Epi& E) {
;     ...
;             PG8_WAIT_V(8); PG8_WAIT_L(0); PG8_BAR; PG8_MMA(0, 0, At, B0); PG8_MMA(0, 1, At, B1); PG8_BAR; PG8_SCHED;
;             PG8_LDA(At, 1, 1); PG8_STAGE(PG8_SB(1, 0), b3, voffB); PG8_STAGE(PG8_SB(1, 1), b3 + hstep, voffB); PG8_STAGE(PG8_SA(1, 0), a3, voffA);
;             PG8_WAIT_V(8); PG8_WAIT_L(0); PG8_BAR; PG8_MMA(1, 0, At, B0); PG8_MMA(1, 1, At, B1); PG8_BAR; PG8_SCHED;
	s_setprio 2
	v_mfma_f32_16x16x32_bf16 v[98:101], v[154:157], v[192:195], v[98:101]
	v_mfma_f32_16x16x32_bf16 v[98:101], v[158:161], v[196:199], v[98:101]
	v_mfma_f32_16x16x32_bf16 v[114:117], v[158:161], v[188:191], v[114:117]
	v_mfma_f32_16x16x32_bf16 v[114:117], v[154:157], v[184:187], v[114:117]
	s_setprio 3
	s_add_i32 s53, s53, s69
	v_lshl_add_u64 v[218:219], v[170:171], 0, s[24:25]
	s_mov_b32 m0, s53
	ds_read_b128 v[184:187], v177 offset:49152
	ds_read_b128 v[188:191], v177 offset:50176
	ds_read_b128 v[192:195], v177 offset:51200
	ds_read_b128 v[196:199], v177 offset:52224
	ds_read_b128 v[200:203], v177 offset:53248
	ds_read_b128 v[204:207], v177 offset:54272
	ds_read_b128 v[208:211], v177 offset:55296
	ds_read_b128 v[212:215], v177 offset:56320
	global_load_lds_dwordx4 v[218:219], off
	v_lshl_add_u64 v[218:219], v[170:171], 0, s[26:27]
	s_add_i32 m0, s53, 0x2000
	s_add_i32 s53, s64, s69
	global_load_lds_dwordx4 v[218:219], off
	v_lshl_add_u64 v[218:219], v[170:171], 0, s[28:29]
	s_mov_b32 m0, s53
	v_lshl_add_u64 v[170:171], v[170:171], 0, s[30:31]
	global_load_lds_dwordx4 v[218:219], off
	s_add_i32 m0, s53, 0x2000
	s_nop 0
	global_load_lds_dwordx4 v[170:171], off
	v_lshl_add_u64 v[170:171], v[216:217], 0, s[24:25]
	s_mov_b32 m0, s75
	s_nop 0
	global_load_lds_dwordx4 v[170:171], off
	v_lshl_add_u64 v[170:171], v[216:217], 0, s[26:27]
	s_mov_b32 m0, s76
	s_nop 0
	global_load_lds_dwordx4 v[170:171], off
	s_waitcnt vmcnt(8)
	s_waitcnt lgkmcnt(0)
	s_barrier
	s_setprio 1
	s_waitcnt lgkmcnt(0)
	v_mfma_f32_16x16x32_bf16 v[62:65], v[130:133], v[184:187], v[62:65]
	v_mfma_f32_16x16x32_bf16 v[62:65], v[134:137], v[188:191], v[62:65]
	v_mfma_f32_16x16x32_bf16 v[46:49], v[134:137], v[196:199], v[46:49]
	v_mfma_f32_16x16x32_bf16 v[46:49], v[130:133], v[192:195], v[46:49]
	v_mfma_f32_16x16x32_bf16 v[30:33], v[130:133], v[200:203], v[30:33]
	v_mfma_f32_16x16x32_bf16 v[30:33], v[134:137], v[204:207], v[30:33]
	v_mfma_f32_16x16x32_bf16 v[14:17], v[134:137], v[212:215], v[14:17]
	v_mfma_f32_16x16x32_bf16 v[14:17], v[130:133], v[208:211], v[14:17]
	v_mfma_f32_16x16x32_bf16 v[10:13], v[138:141], v[208:211], v[10:13]
	v_mfma_f32_16x16x32_bf16 v[10:13], v[142:145], v[212:215], v[10:13]
	v_mfma_f32_16x16x32_bf16 v[26:29], v[142:145], v[204:207], v[26:29]
	v_mfma_f32_16x16x32_bf16 v[26:29], v[138:141], v[200:203], v[26:29]
	v_mfma_f32_16x16x32_bf16 v[42:45], v[138:141], v[192:195], v[42:45]
	v_mfma_f32_16x16x32_bf16 v[42:45], v[142:145], v[196:199], v[42:45]
	v_mfma_f32_16x16x32_bf16 v[58:61], v[142:145], v[188:191], v[58:61]
	v_mfma_f32_16x16x32_bf16 v[58:61], v[138:141], v[184:187], v[58:61]
	v_mfma_f32_16x16x32_bf16 v[54:57], v[146:149], v[184:187], v[54:57]
	v_mfma_f32_16x16x32_bf16 v[54:57], v[150:153], v[188:191], v[54:57]
	v_mfma_f32_16x16x32_bf16 v[38:41], v[150:153], v[196:199], v[38:41]
	v_mfma_f32_16x16x32_bf16 v[38:41], v[146:149], v[192:195], v[38:41]
	v_mfma_f32_16x16x32_bf16 v[22:25], v[146:149], v[200:203], v[22:25]
	v_mfma_f32_16x16x32_bf16 v[22:25], v[150:153], v[204:207], v[22:25]
	v_mfma_f32_16x16x32_bf16 v[6:9], v[150:153], v[212:215], v[6:9]
	v_mfma_f32_16x16x32_bf16 v[6:9], v[146:149], v[208:211], v[6:9]
	v_mfma_f32_16x16x32_bf16 v[2:5], v[154:157], v[208:211], v[2:5]
	v_mfma_f32_16x16x32_bf16 v[2:5], v[158:161], v[212:215], v[2:5]
	v_mfma_f32_16x16x32_bf16 v[18:21], v[158:161], v[204:207], v[18:21]
	v_mfma_f32_16x16x32_bf16 v[18:21], v[154:157], v[200:203], v[18:21]
	s_barrier
	s_setprio 2
	v_mfma_f32_16x16x32_bf16 v[34:37], v[154:157], v[192:195], v[34:37]
	v_mfma_f32_16x16x32_bf16 v[34:37], v[158:161], v[196:199], v[34:37]
	v_mfma_f32_16x16x32_bf16 v[50:53], v[158:161], v[188:191], v[50:53]
	v_mfma_f32_16x16x32_bf16 v[50:53], v[154:157], v[184:187], v[50:53]
	s_setprio 3
	s_add_u32 s62, s62, 0x1000
	s_addc_u32 s63, s63, 0
	s_add_u32 s11, s11, 0x1000
	s_addc_u32 s49, s49, 0
	s_cmp_ge_i32 s55, s89
	s_mov_b32 s53, s55
	s_cbranch_scc0 .LBB0_2399
	s_and_b64 vcc, exec, s[34:35]
	s_cbranch_vccnz .LBB0_2404
	s_lshl_b32 s11, s2, 8
	s_cmp_gt_i32 s2, 63
	s_mov_b64 s[62:63], -1
	s_cbranch_scc1 .LBB0_2405
